# gate epilogue specialised for the first branch of a tile (no running-sum tile loaded); duplicate lgkmcnt(0) per MFMA phase removed
# speedup vs baseline: 1.0180x; 1.0100x over previous
; #define G_STAGE(bufoff, gbase, v0, v1) do { \
;     __builtin_amdgcn_global_load_lds((const unsigned*)((const char*)(gbase) + (v0)), (LAS unsigned*)(lds + (bufoff) + ldsw), 16, 0, 0); \
;     __builtin_amdgcn_global_load_lds((const unsigned*)((const char*)(gbase) + (v1)), (LAS unsigned*)(lds + (bufoff) + ldsw + 8192), 16, 0, 0); } while (0)
; #define G_LDA(dst, b, h) do { _Pragma("unroll") for (int m = 0; m < 4; ++m) _Pragma("unroll") for (int k = 0; k < 2; ++k) dst[m][k] = *(const LAS bf16x8*)(lds + G_SA(b, h) + aoff + m * 2048 + k * 1024); } while (0)
; #define G_LDB(dst, b, h) do { _Pragma("unroll") for (int n = 0; n < 2; ++n) _Pragma("unroll") for (int k = 0; k < 2; ++k) dst[n][k] = *(const LAS bf16x8*)(lds + G_SB(b, h) + boff + n * 2048 + k * 1024); } while (0)
; #define G_MMA(ai, bj, At, Bt) do { __builtin_amdgcn_s_setprio(1); _Pragma("unroll") for (int m = 0; m < 4; ++m) _Pragma("unroll") for (int n = 0; n < 2; ++n) _Pragma("unroll") for (int k = 0; k < 2; ++k) \
;     acc[ai][bj][m][n] = __builtin_amdgcn_mfma_f32_16x16x32_bf16(Bt[n][k], At[m][k], acc[ai][bj][m][n], 0, 0, 0); __builtin_amdgcn_s_setprio(0); } while (0)
; #define G_WAIT_L(n) asm volatile("s_waitcnt lgkmcnt(" #n ")" ::: "memory")
; #define G_BAR __builtin_amdgcn_s_barrier()
; #define G_SCHED __builtin_amdgcn_sched_barrier(0)
; __device__ __forceinline__ void gemm_run(const Params& p, int l, int kind, int single) {
;     ...
;       G_LDB(B0, 0, 0); G_SCHED; G_LDA(At, 0, 0); G_STAGE(G_SA(1, 1), a1 + hc, vc0, vc1);
;       G_WAIT_L(8); G_BAR; G_WAIT_L(0); G_MMA(0, 0, At, B0); G_BAR; G_SCHED;
;       G_LDB(B1, 0, 1); G_STAGE(G_SB(0, 0), b2, w0, w1);
;       G_BAR; G_WAIT_L(0); G_MMA(0, 1, At, B1); G_BAR;
;       G_LDA(At, 0, 1); G_STAGE(G_SA(0, 0), a2, w0, w1);
;       G_BAR; G_WAIT_L(0); G_MMA(1, 0, At, B0); G_BAR; G_SCHED;
.LBB0_94:
	s_add_u32 s8, s0, 0xfffc0080
	s_addc_u32 s9, s1, -1
	s_cmp_eq_u32 s24, 12
	s_cselect_b32 s21, s13, s9
	s_cselect_b32 s20, s12, s8
	s_cselect_b32 s9, s15, s11
	s_cselect_b32 s8, s14, s5
	s_add_i32 s25, s89, 0x100
	v_add_u32_e32 v140, s25, v172
	ds_read_b128 v[128:131], v140
	ds_read_b128 v[132:135], v140 offset:1024
	ds_read_b128 v[136:139], v140 offset:2048
	ds_read_b128 v[140:143], v140 offset:3072
	v_lshl_add_u64 v[186:187], s[0:1], 0, v[156:157]
	s_add_i32 m0, s27, 0xc000
	ds_read_b128 v[144:147], v173
	ds_read_b128 v[148:151], v173 offset:1024
	ds_read_b128 v[160:163], v173 offset:2048
	ds_read_b128 v[164:167], v173 offset:3072
	ds_read_b128 v[168:171], v173 offset:4096
	ds_read_b128 v[174:177], v173 offset:5120
	ds_read_b128 v[178:181], v173 offset:6144
	ds_read_b128 v[182:185], v173 offset:7168
	global_load_lds_dwordx4 v[186:187], off
	v_lshl_add_u64 v[186:187], s[0:1], 0, v[158:159]
	s_add_i32 m0, s27, 0xe000
	s_nop 0
	global_load_lds_dwordx4 v[186:187], off
	s_waitcnt lgkmcnt(8)
	s_barrier
	s_waitcnt lgkmcnt(0)
	s_setprio 1
	v_mfma_f32_16x16x32_bf16 v[124:127], v[128:131], v[144:147], v[124:127]
	v_mfma_f32_16x16x32_bf16 v[120:123], v[136:139], v[144:147], v[120:123]
	v_mfma_f32_16x16x32_bf16 v[108:111], v[128:131], v[160:163], v[108:111]
	v_mfma_f32_16x16x32_bf16 v[104:107], v[136:139], v[160:163], v[104:107]
	v_mfma_f32_16x16x32_bf16 v[92:95], v[128:131], v[168:171], v[92:95]
	v_mfma_f32_16x16x32_bf16 v[88:91], v[136:139], v[168:171], v[88:91]
	v_mfma_f32_16x16x32_bf16 v[76:79], v[128:131], v[178:181], v[76:79]
	v_mfma_f32_16x16x32_bf16 v[72:75], v[136:139], v[178:181], v[72:75]
	v_mfma_f32_16x16x32_bf16 v[124:127], v[132:135], v[148:151], v[124:127]
	v_mfma_f32_16x16x32_bf16 v[120:123], v[140:143], v[148:151], v[120:123]
	v_mfma_f32_16x16x32_bf16 v[108:111], v[132:135], v[164:167], v[108:111]
	v_mfma_f32_16x16x32_bf16 v[104:107], v[140:143], v[164:167], v[104:107]
	v_mfma_f32_16x16x32_bf16 v[92:95], v[132:135], v[174:177], v[92:95]
	v_mfma_f32_16x16x32_bf16 v[88:91], v[140:143], v[174:177], v[88:91]
	v_mfma_f32_16x16x32_bf16 v[76:79], v[132:135], v[182:185], v[76:79]
	v_mfma_f32_16x16x32_bf16 v[72:75], v[140:143], v[182:185], v[72:75]
	s_setprio 0
	s_barrier
	s_add_i32 s47, s90, 0x100
	v_add_u32_e32 v186, s47, v172
	s_add_i32 s25, s25, s3
	ds_read_b128 v[200:203], v186
	ds_read_b128 v[204:207], v186 offset:1024
	ds_read_b128 v[218:221], v186 offset:2048
	ds_read_b128 v[222:225], v186 offset:3072
	v_lshl_add_u64 v[186:187], s[8:9], 0, v[152:153]
	s_mov_b32 m0, s25
	v_lshl_add_u64 v[226:227], s[8:9], 0, v[154:155]
	global_load_lds_dwordx4 v[186:187], off
	s_add_i32 m0, s25, 0x2000
	s_nop 0
	global_load_lds_dwordx4 v[226:227], off
	s_barrier
	s_waitcnt lgkmcnt(0)
	s_setprio 1
	v_mfma_f32_16x16x32_bf16 v[116:119], v[200:203], v[144:147], v[116:119]
	v_mfma_f32_16x16x32_bf16 v[112:115], v[218:221], v[144:147], v[112:115]
	v_mfma_f32_16x16x32_bf16 v[100:103], v[200:203], v[160:163], v[100:103]
	v_mfma_f32_16x16x32_bf16 v[96:99], v[218:221], v[160:163], v[96:99]
	v_mfma_f32_16x16x32_bf16 v[84:87], v[200:203], v[168:171], v[84:87]
	v_mfma_f32_16x16x32_bf16 v[80:83], v[218:221], v[168:171], v[80:83]
	v_mfma_f32_16x16x32_bf16 v[68:71], v[200:203], v[178:181], v[68:71]
	v_mfma_f32_16x16x32_bf16 v[64:67], v[218:221], v[178:181], v[64:67]
	v_mfma_f32_16x16x32_bf16 v[116:119], v[204:207], v[148:151], v[116:119]
	v_mfma_f32_16x16x32_bf16 v[112:115], v[222:225], v[148:151], v[112:115]
	v_mfma_f32_16x16x32_bf16 v[100:103], v[204:207], v[164:167], v[100:103]
	v_mfma_f32_16x16x32_bf16 v[96:99], v[222:225], v[164:167], v[96:99]
	v_mfma_f32_16x16x32_bf16 v[84:87], v[204:207], v[174:177], v[84:87]
	v_mfma_f32_16x16x32_bf16 v[80:83], v[222:225], v[174:177], v[80:83]
	v_mfma_f32_16x16x32_bf16 v[68:71], v[204:207], v[182:185], v[68:71]
	v_mfma_f32_16x16x32_bf16 v[64:67], v[222:225], v[182:185], v[64:67]
	s_setprio 0
	s_mov_b32 m0, s27
	v_lshl_add_u64 v[228:229], s[20:21], 0, v[152:153]
	s_barrier
	ds_read_b128 v[144:147], v173 offset:16384
	ds_read_b128 v[148:151], v173 offset:17408
	ds_read_b128 v[160:163], v173 offset:18432
	ds_read_b128 v[164:167], v173 offset:19456
	ds_read_b128 v[168:171], v173 offset:20480
	ds_read_b128 v[174:177], v173 offset:21504
	ds_read_b128 v[178:181], v173 offset:22528
	ds_read_b128 v[182:185], v173 offset:23552
	global_load_lds_dwordx4 v[228:229], off
	v_lshl_add_u64 v[230:231], s[20:21], 0, v[154:155]
	s_mov_b32 m0, s28
	s_nop 0
	global_load_lds_dwordx4 v[230:231], off
	s_barrier
	s_waitcnt lgkmcnt(0)
	s_setprio 1
	v_mfma_f32_16x16x32_bf16 v[60:63], v[128:131], v[144:147], v[60:63]
	v_mfma_f32_16x16x32_bf16 v[56:59], v[136:139], v[144:147], v[56:59]
	v_mfma_f32_16x16x32_bf16 v[44:47], v[128:131], v[160:163], v[44:47]
	v_mfma_f32_16x16x32_bf16 v[40:43], v[136:139], v[160:163], v[40:43]
	v_mfma_f32_16x16x32_bf16 v[28:31], v[128:131], v[168:171], v[28:31]
	v_mfma_f32_16x16x32_bf16 v[24:27], v[136:139], v[168:171], v[24:27]
	v_mfma_f32_16x16x32_bf16 v[12:15], v[128:131], v[178:181], v[12:15]
	v_mfma_f32_16x16x32_bf16 v[8:11], v[136:139], v[178:181], v[8:11]
	v_mfma_f32_16x16x32_bf16 v[60:63], v[132:135], v[148:151], v[60:63]
	v_mfma_f32_16x16x32_bf16 v[56:59], v[140:143], v[148:151], v[56:59]
	v_mfma_f32_16x16x32_bf16 v[44:47], v[132:135], v[164:167], v[44:47]
	v_mfma_f32_16x16x32_bf16 v[40:43], v[140:143], v[164:167], v[40:43]
	v_mfma_f32_16x16x32_bf16 v[28:31], v[132:135], v[174:177], v[28:31]
	v_mfma_f32_16x16x32_bf16 v[24:27], v[140:143], v[174:177], v[24:27]
	v_mfma_f32_16x16x32_bf16 v[12:15], v[132:135], v[182:185], v[12:15]
	v_mfma_f32_16x16x32_bf16 v[8:11], v[140:143], v[182:185], v[8:11]
	s_setprio 0
	s_barrier
; #define G_STAGE(bufoff, gbase, v0, v1) do { \
;     __builtin_amdgcn_global_load_lds((const unsigned*)((const char*)(gbase) + (v0)), (LAS unsigned*)(lds + (bufoff) + ldsw), 16, 0, 0); \
;     __builtin_amdgcn_global_load_lds((const unsigned*)((const char*)(gbase) + (v1)), (LAS unsigned*)(lds + (bufoff) + ldsw + 8192), 16, 0, 0); } while (0)
; #define G_LDA(dst, b, h) do { _Pragma("unroll") for (int m = 0; m < 4; ++m) _Pragma("unroll") for (int k = 0; k < 2; ++k) dst[m][k] = *(const LAS bf16x8*)(lds + G_SA(b, h) + aoff + m * 2048 + k * 1024); } while (0)
; #define G_LDB(dst, b, h) do { _Pragma("unroll") for (int n = 0; n < 2; ++n) _Pragma("unroll") for (int k = 0; k < 2; ++k) dst[n][k] = *(const LAS bf16x8*)(lds + G_SB(b, h) + boff + n * 2048 + k * 1024); } while (0)
; #define G_MMA(ai, bj, At, Bt) do { __builtin_amdgcn_s_setprio(1); _Pragma("unroll") for (int m = 0; m < 4; ++m) _Pragma("unroll") for (int n = 0; n < 2; ++n) _Pragma("unroll") for (int k = 0; k < 2; ++k) \
;     acc[ai][bj][m][n] = __builtin_amdgcn_mfma_f32_16x16x32_bf16(Bt[n][k], At[m][k], acc[ai][bj][m][n], 0, 0, 0); __builtin_amdgcn_s_setprio(0); } while (0)
; #define G_WAIT_V(n) asm volatile("s_waitcnt vmcnt(" #n ")" ::: "memory")
; #define G_WAIT_L(n) asm volatile("s_waitcnt lgkmcnt(" #n ")" ::: "memory")
; #define G_BAR __builtin_amdgcn_s_barrier()
; #define G_SCHED __builtin_amdgcn_sched_barrier(0)
; __device__ __forceinline__ void gemm_run(const Params& p, int l, int kind, int single) {
;     ...
;       G_STAGE(G_SB(0, 1), b2 + h2, w0, w1);
;       G_WAIT_V(6); G_BAR; G_MMA(1, 1, At, B1); G_BAR;
;       G_LDB(B0, 1, 0); G_SCHED; G_LDA(At, 1, 0); G_STAGE(G_SA(0, 1), a2 + h2, w0, w1);
;       G_WAIT_L(8); G_BAR; G_WAIT_L(0); G_MMA(0, 0, At, B0); G_BAR; G_SCHED;
;       G_LDB(B1, 1, 1); G_STAGE(G_SB(1, 0), b3, w0, w1);
;       G_BAR; G_WAIT_L(0); G_MMA(0, 1, At, B1); G_BAR;
;       G_LDA(At, 1, 1); G_STAGE(G_SA(1, 0), a3, w0, w1);
	s_add_u32 s48, s8, 0x40000
	s_addc_u32 s49, s9, 0
	s_add_i32 s25, s47, s3
	v_lshl_add_u64 v[128:129], s[48:49], 0, v[152:153]
	s_mov_b32 m0, s25
	s_nop 0
	global_load_lds_dwordx4 v[128:129], off
	v_lshl_add_u64 v[128:129], s[48:49], 0, v[154:155]
	s_add_i32 m0, s25, 0x2000
	s_nop 0
	global_load_lds_dwordx4 v[128:129], off
	s_waitcnt vmcnt(6)
	s_barrier
	s_setprio 1
	v_mfma_f32_16x16x32_bf16 v[52:55], v[200:203], v[144:147], v[52:55]
	v_mfma_f32_16x16x32_bf16 v[48:51], v[218:221], v[144:147], v[48:51]
	v_mfma_f32_16x16x32_bf16 v[36:39], v[200:203], v[160:163], v[36:39]
	v_mfma_f32_16x16x32_bf16 v[32:35], v[218:221], v[160:163], v[32:35]
	v_mfma_f32_16x16x32_bf16 v[20:23], v[200:203], v[168:171], v[20:23]
	v_mfma_f32_16x16x32_bf16 v[16:19], v[218:221], v[168:171], v[16:19]
	v_mfma_f32_16x16x32_bf16 v[4:7], v[200:203], v[178:181], v[4:7]
	v_mfma_f32_16x16x32_bf16 v[0:3], v[218:221], v[178:181], v[0:3]
	v_mfma_f32_16x16x32_bf16 v[52:55], v[204:207], v[148:151], v[52:55]
	v_mfma_f32_16x16x32_bf16 v[48:51], v[222:225], v[148:151], v[48:51]
	v_mfma_f32_16x16x32_bf16 v[36:39], v[204:207], v[164:167], v[36:39]
	v_mfma_f32_16x16x32_bf16 v[32:35], v[222:225], v[164:167], v[32:35]
	v_mfma_f32_16x16x32_bf16 v[20:23], v[204:207], v[174:177], v[20:23]
	v_mfma_f32_16x16x32_bf16 v[16:19], v[222:225], v[174:177], v[16:19]
	v_mfma_f32_16x16x32_bf16 v[4:7], v[204:207], v[182:185], v[4:7]
	v_mfma_f32_16x16x32_bf16 v[0:3], v[222:225], v[182:185], v[0:3]
	s_setprio 0
	s_add_i32 s25, s91, 0x100
	v_add_u32_e32 v140, s25, v172
	s_barrier
	ds_read_b128 v[128:131], v140
	ds_read_b128 v[132:135], v140 offset:1024
	ds_read_b128 v[136:139], v140 offset:2048
	ds_read_b128 v[140:143], v140 offset:3072
	s_add_u32 s20, s20, 0x40000
	s_addc_u32 s21, s21, 0
	s_mov_b32 m0, s29
	v_lshl_add_u64 v[200:201], s[20:21], 0, v[152:153]
	ds_read_b128 v[144:147], v173 offset:32768
	ds_read_b128 v[148:151], v173 offset:33792
	ds_read_b128 v[160:163], v173 offset:34816
	ds_read_b128 v[164:167], v173 offset:35840
	ds_read_b128 v[168:171], v173 offset:36864
	ds_read_b128 v[174:177], v173 offset:37888
	ds_read_b128 v[178:181], v173 offset:38912
	ds_read_b128 v[182:185], v173 offset:39936
	global_load_lds_dwordx4 v[200:201], off
	v_lshl_add_u64 v[200:201], s[20:21], 0, v[154:155]
	s_mov_b32 m0, s30
	s_nop 0
	global_load_lds_dwordx4 v[200:201], off
	s_waitcnt lgkmcnt(8)
	s_barrier
	s_waitcnt lgkmcnt(0)
	s_setprio 1
	v_mfma_f32_16x16x32_bf16 v[124:127], v[128:131], v[144:147], v[124:127]
	v_mfma_f32_16x16x32_bf16 v[120:123], v[136:139], v[144:147], v[120:123]
	v_mfma_f32_16x16x32_bf16 v[108:111], v[128:131], v[160:163], v[108:111]
	v_mfma_f32_16x16x32_bf16 v[104:107], v[136:139], v[160:163], v[104:107]
	v_mfma_f32_16x16x32_bf16 v[92:95], v[128:131], v[168:171], v[92:95]
	v_mfma_f32_16x16x32_bf16 v[88:91], v[136:139], v[168:171], v[88:91]
	v_mfma_f32_16x16x32_bf16 v[76:79], v[128:131], v[178:181], v[76:79]
	v_mfma_f32_16x16x32_bf16 v[72:75], v[136:139], v[178:181], v[72:75]
	v_mfma_f32_16x16x32_bf16 v[124:127], v[132:135], v[148:151], v[124:127]
	v_mfma_f32_16x16x32_bf16 v[120:123], v[140:143], v[148:151], v[120:123]
	v_mfma_f32_16x16x32_bf16 v[108:111], v[132:135], v[164:167], v[108:111]
	v_mfma_f32_16x16x32_bf16 v[104:107], v[140:143], v[164:167], v[104:107]
	v_mfma_f32_16x16x32_bf16 v[92:95], v[132:135], v[174:177], v[92:95]
	v_mfma_f32_16x16x32_bf16 v[88:91], v[140:143], v[174:177], v[88:91]
	v_mfma_f32_16x16x32_bf16 v[76:79], v[132:135], v[182:185], v[76:79]
	v_mfma_f32_16x16x32_bf16 v[72:75], v[140:143], v[182:185], v[72:75]
	s_setprio 0
	s_barrier
	s_add_i32 s20, s94, 0x100
	s_add_i32 s21, s25, s3
	v_add_u32_e32 v190, s20, v172
	v_lshl_add_u64 v[186:187], v[186:187], 0, s[96:97]
	s_mov_b32 m0, s21
	ds_read_b128 v[200:203], v190
	ds_read_b128 v[204:207], v190 offset:1024
	ds_read_b128 v[218:221], v190 offset:2048
	ds_read_b128 v[222:225], v190 offset:3072
	global_load_lds_dwordx4 v[186:187], off
	v_lshl_add_u64 v[186:187], v[226:227], 0, s[96:97]
	s_add_i32 m0, s21, 0x2000
	s_nop 0
	global_load_lds_dwordx4 v[186:187], off
	s_barrier
; #define G_STAGE(bufoff, gbase, v0, v1) do { \
;     __builtin_amdgcn_global_load_lds((const unsigned*)((const char*)(gbase) + (v0)), (LAS unsigned*)(lds + (bufoff) + ldsw), 16, 0, 0); \
;     __builtin_amdgcn_global_load_lds((const unsigned*)((const char*)(gbase) + (v1)), (LAS unsigned*)(lds + (bufoff) + ldsw + 8192), 16, 0, 0); } while (0)
; #define G_LDA(dst, b, h) do { _Pragma("unroll") for (int m = 0; m < 4; ++m) _Pragma("unroll") for (int k = 0; k < 2; ++k) dst[m][k] = *(const LAS bf16x8*)(lds + G_SA(b, h) + aoff + m * 2048 + k * 1024); } while (0)
; #define G_MMA(ai, bj, At, Bt) do { __builtin_amdgcn_s_setprio(1); _Pragma("unroll") for (int m = 0; m < 4; ++m) _Pragma("unroll") for (int n = 0; n < 2; ++n) _Pragma("unroll") for (int k = 0; k < 2; ++k) \
;     acc[ai][bj][m][n] = __builtin_amdgcn_mfma_f32_16x16x32_bf16(Bt[n][k], At[m][k], acc[ai][bj][m][n], 0, 0, 0); __builtin_amdgcn_s_setprio(0); } while (0)
; #define G_WAIT_V(n) asm volatile("s_waitcnt vmcnt(" #n ")" ::: "memory")
; #define G_WAIT_L(n) asm volatile("s_waitcnt lgkmcnt(" #n ")" ::: "memory")
; #define G_BAR __builtin_amdgcn_s_barrier()
; #define G_SCHED __builtin_amdgcn_sched_barrier(0)
; __device__ __forceinline__ void gemm_run(const Params& p, int l, int kind, int single) {
;     ...
;       G_LDA(At, 1, 1); G_STAGE(G_SA(1, 0), a3, w0, w1);
;       G_BAR; G_WAIT_L(0); G_MMA(1, 0, At, B0); G_BAR; G_SCHED;
;       G_STAGE(G_SB(1, 1), b3 + h2, w0, w1);
;       G_WAIT_V(6); G_BAR; G_MMA(1, 1, At, B1); G_BAR;
;     }
;     ...
;   G_WAIT_V(0);
;   if (wr == 0) G_BAR;
	s_waitcnt lgkmcnt(0)
	s_setprio 1
	v_mfma_f32_16x16x32_bf16 v[116:119], v[200:203], v[144:147], v[116:119]
	v_mfma_f32_16x16x32_bf16 v[112:115], v[218:221], v[144:147], v[112:115]
	v_mfma_f32_16x16x32_bf16 v[100:103], v[200:203], v[160:163], v[100:103]
	v_mfma_f32_16x16x32_bf16 v[96:99], v[218:221], v[160:163], v[96:99]
	v_mfma_f32_16x16x32_bf16 v[84:87], v[200:203], v[168:171], v[84:87]
	v_mfma_f32_16x16x32_bf16 v[80:83], v[218:221], v[168:171], v[80:83]
	v_mfma_f32_16x16x32_bf16 v[68:71], v[200:203], v[178:181], v[68:71]
	v_mfma_f32_16x16x32_bf16 v[64:67], v[218:221], v[178:181], v[64:67]
	v_mfma_f32_16x16x32_bf16 v[116:119], v[204:207], v[148:151], v[116:119]
	v_mfma_f32_16x16x32_bf16 v[112:115], v[222:225], v[148:151], v[112:115]
	v_mfma_f32_16x16x32_bf16 v[100:103], v[204:207], v[164:167], v[100:103]
	v_mfma_f32_16x16x32_bf16 v[96:99], v[222:225], v[164:167], v[96:99]
	v_mfma_f32_16x16x32_bf16 v[84:87], v[204:207], v[174:177], v[84:87]
	v_mfma_f32_16x16x32_bf16 v[80:83], v[222:225], v[174:177], v[80:83]
	v_mfma_f32_16x16x32_bf16 v[68:71], v[204:207], v[182:185], v[68:71]
	v_mfma_f32_16x16x32_bf16 v[64:67], v[222:225], v[182:185], v[64:67]
	s_setprio 0
	s_mov_b32 m0, s31
	v_lshl_add_u64 v[186:187], v[228:229], 0, s[96:97]
	s_barrier
	ds_read_b128 v[144:147], v173 offset:49152
	ds_read_b128 v[148:151], v173 offset:50176
	ds_read_b128 v[160:163], v173 offset:51200
	ds_read_b128 v[164:167], v173 offset:52224
	ds_read_b128 v[168:171], v173 offset:53248
	ds_read_b128 v[174:177], v173 offset:54272
	ds_read_b128 v[178:181], v173 offset:55296
	ds_read_b128 v[182:185], v173 offset:56320
	global_load_lds_dwordx4 v[186:187], off
	v_lshl_add_u64 v[186:187], v[230:231], 0, s[96:97]
	s_mov_b32 m0, s34
	s_nop 0
	global_load_lds_dwordx4 v[186:187], off
	s_barrier
	s_waitcnt lgkmcnt(0)
	s_setprio 1
	v_mfma_f32_16x16x32_bf16 v[60:63], v[128:131], v[144:147], v[60:63]
	v_mfma_f32_16x16x32_bf16 v[56:59], v[136:139], v[144:147], v[56:59]
	v_mfma_f32_16x16x32_bf16 v[44:47], v[128:131], v[160:163], v[44:47]
	v_mfma_f32_16x16x32_bf16 v[40:43], v[136:139], v[160:163], v[40:43]
	v_mfma_f32_16x16x32_bf16 v[28:31], v[128:131], v[168:171], v[28:31]
	v_mfma_f32_16x16x32_bf16 v[24:27], v[136:139], v[168:171], v[24:27]
	v_mfma_f32_16x16x32_bf16 v[12:15], v[128:131], v[178:181], v[12:15]
	v_mfma_f32_16x16x32_bf16 v[8:11], v[136:139], v[178:181], v[8:11]
	v_mfma_f32_16x16x32_bf16 v[60:63], v[132:135], v[148:151], v[60:63]
	v_mfma_f32_16x16x32_bf16 v[56:59], v[140:143], v[148:151], v[56:59]
	v_mfma_f32_16x16x32_bf16 v[44:47], v[132:135], v[164:167], v[44:47]
	v_mfma_f32_16x16x32_bf16 v[40:43], v[140:143], v[164:167], v[40:43]
	v_mfma_f32_16x16x32_bf16 v[28:31], v[132:135], v[174:177], v[28:31]
	v_mfma_f32_16x16x32_bf16 v[24:27], v[140:143], v[174:177], v[24:27]
	v_mfma_f32_16x16x32_bf16 v[12:15], v[132:135], v[182:185], v[12:15]
	v_mfma_f32_16x16x32_bf16 v[8:11], v[140:143], v[182:185], v[8:11]
	s_setprio 0
	s_barrier
	s_add_u32 s8, s8, 0x40080
	s_addc_u32 s9, s9, 0
	s_add_i32 s20, s20, s3
	v_lshl_add_u64 v[128:129], s[8:9], 0, v[152:153]
	s_mov_b32 m0, s20
	s_nop 0
	global_load_lds_dwordx4 v[128:129], off
	v_lshl_add_u64 v[128:129], s[8:9], 0, v[154:155]
	s_add_i32 m0, s20, 0x2000
	s_nop 0
	global_load_lds_dwordx4 v[128:129], off
	s_waitcnt vmcnt(6)
	s_barrier
	s_setprio 1
	v_mfma_f32_16x16x32_bf16 v[52:55], v[200:203], v[144:147], v[52:55]
	v_mfma_f32_16x16x32_bf16 v[48:51], v[218:221], v[144:147], v[48:51]
	v_mfma_f32_16x16x32_bf16 v[36:39], v[200:203], v[160:163], v[36:39]
	v_mfma_f32_16x16x32_bf16 v[32:35], v[218:221], v[160:163], v[32:35]
	v_mfma_f32_16x16x32_bf16 v[20:23], v[200:203], v[168:171], v[20:23]
	v_mfma_f32_16x16x32_bf16 v[16:19], v[218:221], v[168:171], v[16:19]
	v_mfma_f32_16x16x32_bf16 v[4:7], v[200:203], v[178:181], v[4:7]
	v_mfma_f32_16x16x32_bf16 v[0:3], v[218:221], v[178:181], v[0:3]
	v_mfma_f32_16x16x32_bf16 v[52:55], v[204:207], v[148:151], v[52:55]
	v_mfma_f32_16x16x32_bf16 v[48:51], v[222:225], v[148:151], v[48:51]
	v_mfma_f32_16x16x32_bf16 v[36:39], v[204:207], v[164:167], v[36:39]
	v_mfma_f32_16x16x32_bf16 v[32:35], v[222:225], v[164:167], v[32:35]
	v_mfma_f32_16x16x32_bf16 v[20:23], v[204:207], v[174:177], v[20:23]
	v_mfma_f32_16x16x32_bf16 v[16:19], v[222:225], v[174:177], v[16:19]
	v_mfma_f32_16x16x32_bf16 v[4:7], v[204:207], v[182:185], v[4:7]
	v_mfma_f32_16x16x32_bf16 v[0:3], v[222:225], v[182:185], v[0:3]
	s_setprio 0
	s_add_i32 s24, s24, 2
	s_add_u32 s0, s0, 0x100
	s_addc_u32 s1, s1, 0
	s_add_u32 s5, s5, 0x100
	s_addc_u32 s11, s11, 0
	s_cmp_gt_u32 s24, 13
	s_barrier
	s_cbranch_scc0 .LBB0_94
	s_cmpk_gt_u32 s2, 0xff
	s_cbranch_scc1 .Lal1_a
	s_barrier

; #define G_STAGE(bufoff, gbase, v0, v1) do { \
;     __builtin_amdgcn_global_load_lds((const unsigned*)((const char*)(gbase) + (v0)), (LAS unsigned*)(lds + (bufoff) + ldsw), 16, 0, 0); \
;     __builtin_amdgcn_global_load_lds((const unsigned*)((const char*)(gbase) + (v1)), (LAS unsigned*)(lds + (bufoff) + ldsw + 8192), 16, 0, 0); } while (0)
; #define G_LDA(dst, b, h) do { _Pragma("unroll") for (int m = 0; m < 4; ++m) _Pragma("unroll") for (int k = 0; k < 2; ++k) dst[m][k] = *(const LAS bf16x8*)(lds + G_SA(b, h) + aoff + m * 2048 + k * 1024); } while (0)
; #define G_LDB(dst, b, h) do { _Pragma("unroll") for (int n = 0; n < 2; ++n) _Pragma("unroll") for (int k = 0; k < 2; ++k) dst[n][k] = *(const LAS bf16x8*)(lds + G_SB(b, h) + boff + n * 2048 + k * 1024); } while (0)
; #define G_MMA(ai, bj, At, Bt) do { __builtin_amdgcn_s_setprio(1); _Pragma("unroll") for (int m = 0; m < 4; ++m) _Pragma("unroll") for (int n = 0; n < 2; ++n) _Pragma("unroll") for (int k = 0; k < 2; ++k) \
;     acc[ai][bj][m][n] = __builtin_amdgcn_mfma_f32_16x16x32_bf16(Bt[n][k], At[m][k], acc[ai][bj][m][n], 0, 0, 0); __builtin_amdgcn_s_setprio(0); } while (0)
; #define G_WAIT_L(n) asm volatile("s_waitcnt lgkmcnt(" #n ")" ::: "memory")
; #define G_BAR __builtin_amdgcn_s_barrier()
; #define G_SCHED __builtin_amdgcn_sched_barrier(0)
; __device__ __forceinline__ void gemm_run(const Params& p, int l, int kind, int single) {
;     ...
;       G_LDB(B0, 0, 0); G_SCHED; G_LDA(At, 0, 0); G_STAGE(G_SA(1, 1), a1 + hc, vc0, vc1);
;       G_WAIT_L(8); G_BAR; G_WAIT_L(0); G_MMA(0, 0, At, B0); G_BAR; G_SCHED;
;       G_LDB(B1, 0, 1); G_STAGE(G_SB(0, 0), b2, w0, w1);
;       G_BAR; G_WAIT_L(0); G_MMA(0, 1, At, B1); G_BAR;
;       G_LDA(At, 0, 1); G_STAGE(G_SA(0, 0), a2, w0, w1);
;       G_BAR; G_WAIT_L(0); G_MMA(1, 0, At, B0); G_BAR; G_SCHED;
.LBB0_406:
	s_add_u32 s22, s20, 0xfffc0080
	s_addc_u32 s23, s21, -1
	s_cmp_eq_u32 s35, 12
	s_cselect_b32 s25, s13, s23
	s_cselect_b32 s24, s12, s22
	s_cselect_b32 s23, s15, s11
	s_cselect_b32 s22, s14, s9
	s_add_i32 s36, s39, 0x100
	v_add_u32_e32 v138, s36, v140
	ds_read_b128 v[134:137], v138
	ds_read_b128 v[142:145], v138 offset:1024
	ds_read_b128 v[146:149], v138 offset:2048
	ds_read_b128 v[150:153], v138 offset:3072
	v_lshl_add_u64 v[138:139], s[20:21], 0, v[130:131]
	s_add_i32 m0, s17, 0xc000
	ds_read_b128 v[154:157], v141
	ds_read_b128 v[158:161], v141 offset:1024
	ds_read_b128 v[162:165], v141 offset:2048
	ds_read_b128 v[166:169], v141 offset:3072
	ds_read_b128 v[170:173], v141 offset:4096
	ds_read_b128 v[174:177], v141 offset:5120
	ds_read_b128 v[178:181], v141 offset:6144
	ds_read_b128 v[182:185], v141 offset:7168
	global_load_lds_dwordx4 v[138:139], off
	v_lshl_add_u64 v[138:139], s[20:21], 0, v[132:133]
	s_add_i32 m0, s17, 0xe000
	s_nop 0
	global_load_lds_dwordx4 v[138:139], off
	s_waitcnt lgkmcnt(8)
	s_barrier
	s_waitcnt lgkmcnt(0)
	s_setprio 1
	v_mfma_f32_16x16x32_bf16 v[124:127], v[134:137], v[154:157], v[124:127]
	v_mfma_f32_16x16x32_bf16 v[120:123], v[146:149], v[154:157], v[120:123]
	v_mfma_f32_16x16x32_bf16 v[116:119], v[134:137], v[162:165], v[116:119]
	v_mfma_f32_16x16x32_bf16 v[112:115], v[146:149], v[162:165], v[112:115]
	v_mfma_f32_16x16x32_bf16 v[108:111], v[134:137], v[170:173], v[108:111]
	v_mfma_f32_16x16x32_bf16 v[100:103], v[146:149], v[170:173], v[100:103]
	v_mfma_f32_16x16x32_bf16 v[84:87], v[134:137], v[178:181], v[84:87]
	v_mfma_f32_16x16x32_bf16 v[72:75], v[146:149], v[178:181], v[72:75]
	v_mfma_f32_16x16x32_bf16 v[124:127], v[142:145], v[158:161], v[124:127]
	v_mfma_f32_16x16x32_bf16 v[120:123], v[150:153], v[158:161], v[120:123]
	v_mfma_f32_16x16x32_bf16 v[116:119], v[142:145], v[166:169], v[116:119]
	v_mfma_f32_16x16x32_bf16 v[112:115], v[150:153], v[166:169], v[112:115]
	v_mfma_f32_16x16x32_bf16 v[108:111], v[142:145], v[174:177], v[108:111]
	v_mfma_f32_16x16x32_bf16 v[100:103], v[150:153], v[174:177], v[100:103]
	v_mfma_f32_16x16x32_bf16 v[84:87], v[142:145], v[182:185], v[84:87]
	v_mfma_f32_16x16x32_bf16 v[72:75], v[150:153], v[182:185], v[72:75]
	s_setprio 0
	s_barrier
	s_add_i32 s38, s40, 0x100
	v_add_u32_e32 v138, s38, v140
	s_add_i32 s36, s36, s3
	ds_read_b128 v[200:203], v138
	ds_read_b128 v[204:207], v138 offset:1024
	ds_read_b128 v[218:221], v138 offset:2048
	ds_read_b128 v[222:225], v138 offset:3072
	v_lshl_add_u64 v[138:139], s[22:23], 0, v[190:191]
	s_mov_b32 m0, s36
	v_lshl_add_u64 v[186:187], s[22:23], 0, v[128:129]
	global_load_lds_dwordx4 v[138:139], off
	s_add_i32 m0, s36, 0x2000
	s_nop 0
	global_load_lds_dwordx4 v[186:187], off
	s_barrier
	s_waitcnt lgkmcnt(0)
	s_setprio 1
	v_mfma_f32_16x16x32_bf16 v[104:107], v[200:203], v[154:157], v[104:107]
	v_mfma_f32_16x16x32_bf16 v[96:99], v[218:221], v[154:157], v[96:99]
	v_mfma_f32_16x16x32_bf16 v[92:95], v[200:203], v[162:165], v[92:95]
	v_mfma_f32_16x16x32_bf16 v[88:91], v[218:221], v[162:165], v[88:91]
	v_mfma_f32_16x16x32_bf16 v[80:83], v[200:203], v[170:173], v[80:83]
	v_mfma_f32_16x16x32_bf16 v[76:79], v[218:221], v[170:173], v[76:79]
	v_mfma_f32_16x16x32_bf16 v[68:71], v[200:203], v[178:181], v[68:71]
	v_mfma_f32_16x16x32_bf16 v[64:67], v[218:221], v[178:181], v[64:67]
	v_mfma_f32_16x16x32_bf16 v[104:107], v[204:207], v[158:161], v[104:107]
	v_mfma_f32_16x16x32_bf16 v[96:99], v[222:225], v[158:161], v[96:99]
	v_mfma_f32_16x16x32_bf16 v[92:95], v[204:207], v[166:169], v[92:95]
	v_mfma_f32_16x16x32_bf16 v[88:91], v[222:225], v[166:169], v[88:91]
	v_mfma_f32_16x16x32_bf16 v[80:83], v[204:207], v[174:177], v[80:83]
	v_mfma_f32_16x16x32_bf16 v[76:79], v[222:225], v[174:177], v[76:79]
	v_mfma_f32_16x16x32_bf16 v[68:71], v[204:207], v[182:185], v[68:71]
	v_mfma_f32_16x16x32_bf16 v[64:67], v[222:225], v[182:185], v[64:67]
	s_setprio 0
	s_mov_b32 m0, s17
	v_lshl_add_u64 v[226:227], s[24:25], 0, v[190:191]
	s_barrier
	ds_read_b128 v[154:157], v141 offset:16384
	ds_read_b128 v[158:161], v141 offset:17408
	ds_read_b128 v[162:165], v141 offset:18432
	ds_read_b128 v[166:169], v141 offset:19456
	ds_read_b128 v[170:173], v141 offset:20480
	ds_read_b128 v[174:177], v141 offset:21504
	ds_read_b128 v[178:181], v141 offset:22528
	ds_read_b128 v[182:185], v141 offset:23552
	global_load_lds_dwordx4 v[226:227], off
	v_lshl_add_u64 v[228:229], s[24:25], 0, v[128:129]
	s_mov_b32 m0, s19
	s_nop 0
	global_load_lds_dwordx4 v[228:229], off
	s_barrier
	s_waitcnt lgkmcnt(0)
	s_setprio 1
	v_mfma_f32_16x16x32_bf16 v[60:63], v[134:137], v[154:157], v[60:63]
	v_mfma_f32_16x16x32_bf16 v[56:59], v[146:149], v[154:157], v[56:59]
	v_mfma_f32_16x16x32_bf16 v[52:55], v[134:137], v[162:165], v[52:55]
	v_mfma_f32_16x16x32_bf16 v[48:51], v[146:149], v[162:165], v[48:51]
	v_mfma_f32_16x16x32_bf16 v[44:47], v[134:137], v[170:173], v[44:47]
	v_mfma_f32_16x16x32_bf16 v[36:39], v[146:149], v[170:173], v[36:39]
	v_mfma_f32_16x16x32_bf16 v[28:31], v[134:137], v[178:181], v[28:31]
	v_mfma_f32_16x16x32_bf16 v[16:19], v[146:149], v[178:181], v[16:19]
	v_mfma_f32_16x16x32_bf16 v[60:63], v[142:145], v[158:161], v[60:63]
	v_mfma_f32_16x16x32_bf16 v[56:59], v[150:153], v[158:161], v[56:59]
	v_mfma_f32_16x16x32_bf16 v[52:55], v[142:145], v[166:169], v[52:55]
	v_mfma_f32_16x16x32_bf16 v[48:51], v[150:153], v[166:169], v[48:51]
	v_mfma_f32_16x16x32_bf16 v[44:47], v[142:145], v[174:177], v[44:47]
	v_mfma_f32_16x16x32_bf16 v[36:39], v[150:153], v[174:177], v[36:39]
	v_mfma_f32_16x16x32_bf16 v[28:31], v[142:145], v[182:185], v[28:31]
	v_mfma_f32_16x16x32_bf16 v[16:19], v[150:153], v[182:185], v[16:19]
	s_setprio 0
	s_barrier
; #define G_STAGE(bufoff, gbase, v0, v1) do { \
;     __builtin_amdgcn_global_load_lds((const unsigned*)((const char*)(gbase) + (v0)), (LAS unsigned*)(lds + (bufoff) + ldsw), 16, 0, 0); \
;     __builtin_amdgcn_global_load_lds((const unsigned*)((const char*)(gbase) + (v1)), (LAS unsigned*)(lds + (bufoff) + ldsw + 8192), 16, 0, 0); } while (0)
; #define G_LDA(dst, b, h) do { _Pragma("unroll") for (int m = 0; m < 4; ++m) _Pragma("unroll") for (int k = 0; k < 2; ++k) dst[m][k] = *(const LAS bf16x8*)(lds + G_SA(b, h) + aoff + m * 2048 + k * 1024); } while (0)
; #define G_LDB(dst, b, h) do { _Pragma("unroll") for (int n = 0; n < 2; ++n) _Pragma("unroll") for (int k = 0; k < 2; ++k) dst[n][k] = *(const LAS bf16x8*)(lds + G_SB(b, h) + boff + n * 2048 + k * 1024); } while (0)
; #define G_MMA(ai, bj, At, Bt) do { __builtin_amdgcn_s_setprio(1); _Pragma("unroll") for (int m = 0; m < 4; ++m) _Pragma("unroll") for (int n = 0; n < 2; ++n) _Pragma("unroll") for (int k = 0; k < 2; ++k) \
;     acc[ai][bj][m][n] = __builtin_amdgcn_mfma_f32_16x16x32_bf16(Bt[n][k], At[m][k], acc[ai][bj][m][n], 0, 0, 0); __builtin_amdgcn_s_setprio(0); } while (0)
; #define G_WAIT_V(n) asm volatile("s_waitcnt vmcnt(" #n ")" ::: "memory")
; #define G_WAIT_L(n) asm volatile("s_waitcnt lgkmcnt(" #n ")" ::: "memory")
; #define G_BAR __builtin_amdgcn_s_barrier()
; #define G_SCHED __builtin_amdgcn_sched_barrier(0)
; __device__ __forceinline__ void gemm_run(const Params& p, int l, int kind, int single) {
;     ...
;       G_STAGE(G_SB(0, 1), b2 + h2, w0, w1);
;       G_WAIT_V(6); G_BAR; G_MMA(1, 1, At, B1); G_BAR;
;       G_LDB(B0, 1, 0); G_SCHED; G_LDA(At, 1, 0); G_STAGE(G_SA(0, 1), a2 + h2, w0, w1);
;       G_WAIT_L(8); G_BAR; G_WAIT_L(0); G_MMA(0, 0, At, B0); G_BAR; G_SCHED;
;       G_LDB(B1, 1, 1); G_STAGE(G_SB(1, 0), b3, w0, w1);
;       G_BAR; G_WAIT_L(0); G_MMA(0, 1, At, B1); G_BAR;
;       G_LDA(At, 1, 1); G_STAGE(G_SA(1, 0), a3, w0, w1);
	s_add_u32 s36, s22, 0x40000
	s_addc_u32 s37, s23, 0
	s_add_i32 s38, s38, s3
	v_lshl_add_u64 v[134:135], s[36:37], 0, v[190:191]
	s_mov_b32 m0, s38
	s_nop 0
	global_load_lds_dwordx4 v[134:135], off
	v_lshl_add_u64 v[134:135], s[36:37], 0, v[128:129]
	s_add_i32 m0, s38, 0x2000
	s_nop 0
	global_load_lds_dwordx4 v[134:135], off
	s_waitcnt vmcnt(6)
	s_barrier
	s_setprio 1
	v_mfma_f32_16x16x32_bf16 v[40:43], v[200:203], v[154:157], v[40:43]
	v_mfma_f32_16x16x32_bf16 v[32:35], v[218:221], v[154:157], v[32:35]
	v_mfma_f32_16x16x32_bf16 v[24:27], v[200:203], v[162:165], v[24:27]
	v_mfma_f32_16x16x32_bf16 v[20:23], v[218:221], v[162:165], v[20:23]
	v_mfma_f32_16x16x32_bf16 v[12:15], v[200:203], v[170:173], v[12:15]
	v_mfma_f32_16x16x32_bf16 v[8:11], v[218:221], v[170:173], v[8:11]
	v_mfma_f32_16x16x32_bf16 v[4:7], v[200:203], v[178:181], v[4:7]
	v_mfma_f32_16x16x32_bf16 v[0:3], v[218:221], v[178:181], v[0:3]
	v_mfma_f32_16x16x32_bf16 v[40:43], v[204:207], v[158:161], v[40:43]
	v_mfma_f32_16x16x32_bf16 v[32:35], v[222:225], v[158:161], v[32:35]
	v_mfma_f32_16x16x32_bf16 v[24:27], v[204:207], v[166:169], v[24:27]
	v_mfma_f32_16x16x32_bf16 v[20:23], v[222:225], v[166:169], v[20:23]
	v_mfma_f32_16x16x32_bf16 v[12:15], v[204:207], v[174:177], v[12:15]
	v_mfma_f32_16x16x32_bf16 v[8:11], v[222:225], v[174:177], v[8:11]
	v_mfma_f32_16x16x32_bf16 v[4:7], v[204:207], v[182:185], v[4:7]
	v_mfma_f32_16x16x32_bf16 v[0:3], v[222:225], v[182:185], v[0:3]
	s_setprio 0
	s_add_i32 s36, s41, 0x100
	v_add_u32_e32 v150, s36, v140
	s_barrier
	ds_read_b128 v[134:137], v150
	ds_read_b128 v[142:145], v150 offset:1024
	ds_read_b128 v[146:149], v150 offset:2048
	ds_read_b128 v[150:153], v150 offset:3072
	s_add_u32 s24, s24, 0x40000
	s_addc_u32 s25, s25, 0
	s_mov_b32 m0, s26
	v_lshl_add_u64 v[200:201], s[24:25], 0, v[190:191]
	ds_read_b128 v[154:157], v141 offset:32768
	ds_read_b128 v[158:161], v141 offset:33792
	ds_read_b128 v[162:165], v141 offset:34816
	ds_read_b128 v[166:169], v141 offset:35840
	ds_read_b128 v[170:173], v141 offset:36864
	ds_read_b128 v[174:177], v141 offset:37888
	ds_read_b128 v[178:181], v141 offset:38912
	ds_read_b128 v[182:185], v141 offset:39936
	global_load_lds_dwordx4 v[200:201], off
	v_lshl_add_u64 v[200:201], s[24:25], 0, v[128:129]
	s_mov_b32 m0, s27
	s_nop 0
	global_load_lds_dwordx4 v[200:201], off
	s_waitcnt lgkmcnt(8)
	s_barrier
	s_waitcnt lgkmcnt(0)
	s_setprio 1
	v_mfma_f32_16x16x32_bf16 v[124:127], v[134:137], v[154:157], v[124:127]
	v_mfma_f32_16x16x32_bf16 v[120:123], v[146:149], v[154:157], v[120:123]
	v_mfma_f32_16x16x32_bf16 v[116:119], v[134:137], v[162:165], v[116:119]
	v_mfma_f32_16x16x32_bf16 v[112:115], v[146:149], v[162:165], v[112:115]
	v_mfma_f32_16x16x32_bf16 v[108:111], v[134:137], v[170:173], v[108:111]
	v_mfma_f32_16x16x32_bf16 v[100:103], v[146:149], v[170:173], v[100:103]
	v_mfma_f32_16x16x32_bf16 v[84:87], v[134:137], v[178:181], v[84:87]
	v_mfma_f32_16x16x32_bf16 v[72:75], v[146:149], v[178:181], v[72:75]
	v_mfma_f32_16x16x32_bf16 v[124:127], v[142:145], v[158:161], v[124:127]
	v_mfma_f32_16x16x32_bf16 v[120:123], v[150:153], v[158:161], v[120:123]
	v_mfma_f32_16x16x32_bf16 v[116:119], v[142:145], v[166:169], v[116:119]
	v_mfma_f32_16x16x32_bf16 v[112:115], v[150:153], v[166:169], v[112:115]
	v_mfma_f32_16x16x32_bf16 v[108:111], v[142:145], v[174:177], v[108:111]
	v_mfma_f32_16x16x32_bf16 v[100:103], v[150:153], v[174:177], v[100:103]
	v_mfma_f32_16x16x32_bf16 v[84:87], v[142:145], v[182:185], v[84:87]
	v_mfma_f32_16x16x32_bf16 v[72:75], v[150:153], v[182:185], v[72:75]
	s_setprio 0
	s_barrier
	s_add_i32 s24, s42, 0x100
	s_add_i32 s25, s36, s3
	v_add_u32_e32 v199, s24, v140
	v_lshl_add_u64 v[138:139], v[138:139], 0, s[96:97]
	s_mov_b32 m0, s25
	ds_read_b128 v[200:203], v199
	ds_read_b128 v[204:207], v199 offset:1024
	ds_read_b128 v[218:221], v199 offset:2048
	ds_read_b128 v[222:225], v199 offset:3072
	global_load_lds_dwordx4 v[138:139], off
	v_lshl_add_u64 v[138:139], v[186:187], 0, s[96:97]
	s_add_i32 m0, s25, 0x2000
	s_nop 0
	global_load_lds_dwordx4 v[138:139], off
	s_barrier
	s_waitcnt lgkmcnt(0)
	s_setprio 1
	v_mfma_f32_16x16x32_bf16 v[104:107], v[200:203], v[154:157], v[104:107]
	v_mfma_f32_16x16x32_bf16 v[96:99], v[218:221], v[154:157], v[96:99]
	v_mfma_f32_16x16x32_bf16 v[92:95], v[200:203], v[162:165], v[92:95]
	v_mfma_f32_16x16x32_bf16 v[88:91], v[218:221], v[162:165], v[88:91]
	v_mfma_f32_16x16x32_bf16 v[80:83], v[200:203], v[170:173], v[80:83]
	v_mfma_f32_16x16x32_bf16 v[76:79], v[218:221], v[170:173], v[76:79]
	v_mfma_f32_16x16x32_bf16 v[68:71], v[200:203], v[178:181], v[68:71]
	v_mfma_f32_16x16x32_bf16 v[64:67], v[218:221], v[178:181], v[64:67]
	v_mfma_f32_16x16x32_bf16 v[104:107], v[204:207], v[158:161], v[104:107]
	v_mfma_f32_16x16x32_bf16 v[96:99], v[222:225], v[158:161], v[96:99]
	v_mfma_f32_16x16x32_bf16 v[92:95], v[204:207], v[166:169], v[92:95]
	v_mfma_f32_16x16x32_bf16 v[88:91], v[222:225], v[166:169], v[88:91]
	v_mfma_f32_16x16x32_bf16 v[80:83], v[204:207], v[174:177], v[80:83]
	v_mfma_f32_16x16x32_bf16 v[76:79], v[222:225], v[174:177], v[76:79]
	v_mfma_f32_16x16x32_bf16 v[68:71], v[204:207], v[182:185], v[68:71]
	v_mfma_f32_16x16x32_bf16 v[64:67], v[222:225], v[182:185], v[64:67]
	s_setprio 0
	s_mov_b32 m0, s28
	v_lshl_add_u64 v[138:139], v[226:227], 0, s[96:97]
	s_barrier
	ds_read_b128 v[154:157], v141 offset:49152
	ds_read_b128 v[158:161], v141 offset:50176
	ds_read_b128 v[162:165], v141 offset:51200
	ds_read_b128 v[166:169], v141 offset:52224
	ds_read_b128 v[170:173], v141 offset:53248
	ds_read_b128 v[174:177], v141 offset:54272
	ds_read_b128 v[178:181], v141 offset:55296
	ds_read_b128 v[182:185], v141 offset:56320
	global_load_lds_dwordx4 v[138:139], off
	v_lshl_add_u64 v[138:139], v[228:229], 0, s[96:97]
	s_mov_b32 m0, s29
	s_nop 0
	global_load_lds_dwordx4 v[138:139], off
	s_barrier
; __device__ __forceinline__ int otid() { int t = threadIdx.x; asm volatile("" : "+v"(t)); return t; }
; #define G_STAGE(bufoff, gbase, v0, v1) do { \
;     __builtin_amdgcn_global_load_lds((const unsigned*)((const char*)(gbase) + (v0)), (LAS unsigned*)(lds + (bufoff) + ldsw), 16, 0, 0); \
;     __builtin_amdgcn_global_load_lds((const unsigned*)((const char*)(gbase) + (v1)), (LAS unsigned*)(lds + (bufoff) + ldsw + 8192), 16, 0, 0); } while (0)
; #define G_LDA(dst, b, h) do { _Pragma("unroll") for (int m = 0; m < 4; ++m) _Pragma("unroll") for (int k = 0; k < 2; ++k) dst[m][k] = *(const LAS bf16x8*)(lds + G_SA(b, h) + aoff + m * 2048 + k * 1024); } while (0)
; #define G_MMA(ai, bj, At, Bt) do { __builtin_amdgcn_s_setprio(1); _Pragma("unroll") for (int m = 0; m < 4; ++m) _Pragma("unroll") for (int n = 0; n < 2; ++n) _Pragma("unroll") for (int k = 0; k < 2; ++k) \
;     acc[ai][bj][m][n] = __builtin_amdgcn_mfma_f32_16x16x32_bf16(Bt[n][k], At[m][k], acc[ai][bj][m][n], 0, 0, 0); __builtin_amdgcn_s_setprio(0); } while (0)
; #define G_WAIT_V(n) asm volatile("s_waitcnt vmcnt(" #n ")" ::: "memory")
; __device__ __forceinline__ void gemm_epi(const Params& p, int l, int kind, const GUnit& u, f32x4 (&acc)[2][2][4][2]) {
;   const int tid = otid(), wid = __builtin_amdgcn_readfirstlane(tid >> 6), lane = tid & 63, wr = wid >> 2, wc = wid & 3, fr = lane & 15, fq = lane >> 4;
;   int row0 = u.pm * 256 + wr * 64 + fr;
;   asm volatile("" : "+v"(row0));
;   if (kind == 4) {
;     const int col0 = u.pn * 256 + wc * 32 + 4 * fq;
;     const float* xbase = (l == 0) ? (u.pm < 256 ? p.xp : p.xs - (long)NP * 1024) : p.out;
; #pragma unroll
;     for (int ai = 0; ai < 2; ++ai) {
;       f32x4 xv[4][2][2];
; #pragma unroll
;       for (int m = 0; m < 4; ++m) {
;         const float* xr = xbase + (long)(row0 + ai * 128 + m * 16) * 1024 + col0;
; #pragma unroll
;         for (int bj = 0; bj < 2; ++bj)
; #pragma unroll
;           for (int n = 0; n < 2; ++n) xv[m][bj][n] = *reinterpret_cast<const f32x4*>(xr + bj * 128 + n * 16);
;       }
; __device__ __forceinline__ void gemm_run(const Params& p, int l, int kind, int single) {
;     ...
;       G_LDA(At, 1, 1); G_STAGE(G_SA(1, 0), a3, w0, w1);
;       G_BAR; G_WAIT_L(0); G_MMA(1, 0, At, B0); G_BAR; G_SCHED;
;       G_STAGE(G_SB(1, 1), b3 + h2, w0, w1);
;       G_WAIT_V(6); G_BAR; G_MMA(1, 1, At, B1); G_BAR;
;     }
	s_waitcnt lgkmcnt(0)
	s_setprio 1
	v_mfma_f32_16x16x32_bf16 v[60:63], v[134:137], v[154:157], v[60:63]
	v_mfma_f32_16x16x32_bf16 v[56:59], v[146:149], v[154:157], v[56:59]
	v_mfma_f32_16x16x32_bf16 v[52:55], v[134:137], v[162:165], v[52:55]
	v_mfma_f32_16x16x32_bf16 v[48:51], v[146:149], v[162:165], v[48:51]
	v_mfma_f32_16x16x32_bf16 v[44:47], v[134:137], v[170:173], v[44:47]
	v_mfma_f32_16x16x32_bf16 v[36:39], v[146:149], v[170:173], v[36:39]
	v_mfma_f32_16x16x32_bf16 v[28:31], v[134:137], v[178:181], v[28:31]
	v_mfma_f32_16x16x32_bf16 v[16:19], v[146:149], v[178:181], v[16:19]
	v_mfma_f32_16x16x32_bf16 v[60:63], v[142:145], v[158:161], v[60:63]
	v_mfma_f32_16x16x32_bf16 v[56:59], v[150:153], v[158:161], v[56:59]
	v_mfma_f32_16x16x32_bf16 v[52:55], v[142:145], v[166:169], v[52:55]
	v_mfma_f32_16x16x32_bf16 v[48:51], v[150:153], v[166:169], v[48:51]
	v_mfma_f32_16x16x32_bf16 v[44:47], v[142:145], v[174:177], v[44:47]
	v_mfma_f32_16x16x32_bf16 v[36:39], v[150:153], v[174:177], v[36:39]
	v_mfma_f32_16x16x32_bf16 v[28:31], v[142:145], v[182:185], v[28:31]
	v_mfma_f32_16x16x32_bf16 v[16:19], v[150:153], v[182:185], v[16:19]
	s_setprio 0
	s_barrier
	s_add_u32 s22, s22, 0x40080
	s_addc_u32 s23, s23, 0
	s_add_i32 s24, s24, s3
	v_lshl_add_u64 v[134:135], s[22:23], 0, v[190:191]
	s_mov_b32 m0, s24
	s_nop 0
	global_load_lds_dwordx4 v[134:135], off
	v_lshl_add_u64 v[134:135], s[22:23], 0, v[128:129]
	s_add_i32 m0, s24, 0x2000
	s_nop 0
	global_load_lds_dwordx4 v[134:135], off
	s_waitcnt vmcnt(6)
	s_barrier
	s_setprio 1
	v_mfma_f32_16x16x32_bf16 v[40:43], v[200:203], v[154:157], v[40:43]
	v_mfma_f32_16x16x32_bf16 v[32:35], v[218:221], v[154:157], v[32:35]
	v_mfma_f32_16x16x32_bf16 v[24:27], v[200:203], v[162:165], v[24:27]
	v_mfma_f32_16x16x32_bf16 v[20:23], v[218:221], v[162:165], v[20:23]
	v_mfma_f32_16x16x32_bf16 v[12:15], v[200:203], v[170:173], v[12:15]
	v_mfma_f32_16x16x32_bf16 v[8:11], v[218:221], v[170:173], v[8:11]
	v_mfma_f32_16x16x32_bf16 v[4:7], v[200:203], v[178:181], v[4:7]
	v_mfma_f32_16x16x32_bf16 v[0:3], v[218:221], v[178:181], v[0:3]
	v_mfma_f32_16x16x32_bf16 v[40:43], v[204:207], v[158:161], v[40:43]
	v_mfma_f32_16x16x32_bf16 v[32:35], v[222:225], v[158:161], v[32:35]
	v_mfma_f32_16x16x32_bf16 v[24:27], v[204:207], v[166:169], v[24:27]
	v_mfma_f32_16x16x32_bf16 v[20:23], v[222:225], v[166:169], v[20:23]
	v_mfma_f32_16x16x32_bf16 v[12:15], v[204:207], v[174:177], v[12:15]
	v_mfma_f32_16x16x32_bf16 v[8:11], v[222:225], v[174:177], v[8:11]
	v_mfma_f32_16x16x32_bf16 v[4:7], v[204:207], v[182:185], v[4:7]
	v_mfma_f32_16x16x32_bf16 v[0:3], v[222:225], v[182:185], v[0:3]
	s_setprio 0
	s_add_i32 s35, s35, 2
	s_add_u32 s20, s20, 0x100
	s_addc_u32 s21, s21, 0
	s_add_u32 s9, s9, 0x100
	s_addc_u32 s11, s11, 0
	s_cmp_gt_u32 s35, 13
	s_barrier
	s_cbranch_scc0 .LBB0_406
	v_mov_b32_e32 v134, v188
	s_lshl_b32 s11, s16, 8
	v_readfirstlane_b32 s9, v134
	s_ashr_i32 s20, s9, 2
	s_andn2_b32 s20, s20, 63
	s_lshr_b32 s9, s9, 1
	s_add_i32 s20, s20, s11
	s_lshl_b32 s11, s18, 8
	s_and_b32 s9, s9, 0x60
	v_and_or_b32 v138, v134, 15, s20
	s_or_b32 s9, s9, s11
	v_lshrrev_b32_e32 v134, 2, v134
	v_readlane_b32 s36, v248, 20
	v_readlane_b32 s20, v247, 48
	v_and_or_b32 v134, v134, 12, s9
	s_cmpk_lt_i32 s16, 0x100
	v_readlane_b32 s37, v248, 21
	v_readlane_b32 s21, v247, 49
	v_readlane_b32 s48, v248, 49
	s_cselect_b32 s9, s36, s81
	s_cselect_b32 s11, s37, s88
	s_and_b64 s[20:21], s[20:21], exec
	v_readlane_b32 s49, v248, 50
	v_ashrrev_i32_e32 v135, 31, v134
	s_cselect_b32 s21, s11, s49
	s_cselect_b32 s20, s9, s48
	v_lshlrev_b64 v[134:135], 2, v[134:135]
	v_ashrrev_i32_e32 v139, 31, v138
	v_lshl_add_u64 v[136:137], s[20:21], 0, v[134:135]
	v_lshlrev_b64 v[138:139], 12, v[138:139]
	s_mov_b64 s[20:21], 0x10000
	v_lshl_add_u64 v[186:187], v[138:139], 0, s[20:21]
	s_mov_b64 s[20:21], 0x20000
	v_lshl_add_u64 v[230:231], v[138:139], 0, s[20:21]
	s_mov_b64 s[20:21], 0x30000
	v_lshl_add_u64 v[154:155], v[136:137], 0, v[138:139]
	v_lshl_add_u64 v[232:233], v[138:139], 0, s[20:21]
	global_load_dwordx4 v[142:145], v[154:155], off
	global_load_dwordx4 v[146:149], v[154:155], off offset:64
	global_load_dwordx4 v[150:153], v[154:155], off offset:512
	s_nop 0
	global_load_dwordx4 v[154:157], v[154:155], off offset:576
	v_lshl_add_u64 v[170:171], v[136:137], 0, v[186:187]
	v_lshl_add_u64 v[200:201], v[136:137], 0, v[230:231]
	v_lshl_add_u64 v[226:227], v[136:137], 0, v[232:233]
	global_load_dwordx4 v[158:161], v[170:171], off
	global_load_dwordx4 v[162:165], v[170:171], off offset:64
	global_load_dwordx4 v[166:169], v[170:171], off offset:512
	s_nop 0
	global_load_dwordx4 v[170:173], v[170:171], off offset:576
	s_nop 0
	global_load_dwordx4 v[174:177], v[200:201], off
	global_load_dwordx4 v[178:181], v[200:201], off offset:64
	global_load_dwordx4 v[182:185], v[200:201], off offset:512
	s_nop 0
	global_load_dwordx4 v[200:203], v[200:201], off offset:576
	s_nop 0
	global_load_dwordx4 v[204:207], v[226:227], off
	global_load_dwordx4 v[218:221], v[226:227], off offset:64
	global_load_dwordx4 v[222:225], v[226:227], off offset:512
	s_nop 0
	global_load_dwordx4 v[226:229], v[226:227], off offset:576
	v_lshl_add_u64 v[234:235], s[48:49], 0, v[138:139]
	v_lshl_add_u64 v[234:235], v[234:235], 0, v[134:135]
	v_lshl_add_u64 v[186:187], s[48:49], 0, v[186:187]
	v_lshl_add_u64 v[232:233], s[48:49], 0, v[232:233]
	s_mov_b32 s95, 0x1c000
	s_mov_b32 s94, 0x18000
	s_mov_b32 s91, 0x14000
	s_mov_b32 s90, 0x10000
	v_lshl_add_u64 v[230:231], s[48:49], 0, v[230:231]
	v_lshl_add_u64 v[186:187], v[186:187], 0, v[134:135]
	v_lshl_add_u64 v[232:233], v[232:233], 0, v[134:135]
	v_readlane_b32 s38, v248, 22
	v_readlane_b32 s39, v248, 23
	v_readlane_b32 s40, v248, 24
	v_readlane_b32 s41, v248, 25
	v_readlane_b32 s42, v248, 26
	v_readlane_b32 s43, v248, 27
	v_readlane_b32 s50, v248, 51
	v_readlane_b32 s51, v248, 52
	v_readlane_b32 s52, v248, 53
	v_readlane_b32 s53, v248, 54
	v_readlane_b32 s54, v248, 55
	v_readlane_b32 s55, v248, 56
	v_readlane_b32 s56, v248, 57
	v_readlane_b32 s57, v248, 58
	v_readlane_b32 s58, v248, 59
	v_readlane_b32 s59, v248, 60
	v_readlane_b32 s60, v248, 61
	v_readlane_b32 s61, v248, 62
	v_readlane_b32 s62, v248, 63
	v_readlane_b32 s63, v247, 0
	v_lshl_add_u64 v[230:231], v[230:231], 0, v[134:135]
	s_waitcnt vmcnt(0)
; #define G_WAIT_V(n) asm volatile("s_waitcnt vmcnt(" #n ")" ::: "memory")
; #define G_BAR __builtin_amdgcn_s_barrier()
; __device__ __forceinline__ void gemm_epi(const Params& p, int l, int kind, const GUnit& u, f32x4 (&acc)[2][2][4][2]) {
;     ...
;     for (int ai = 0; ai < 2; ++ai) {
;       f32x4 xv[4][2][2];
; #pragma unroll
;       for (int m = 0; m < 4; ++m) {
;         const float* xr = xbase + (long)(row0 + ai * 128 + m * 16) * 1024 + col0;
; #pragma unroll
;         for (int bj = 0; bj < 2; ++bj)
; #pragma unroll
;           for (int n = 0; n < 2; ++n) xv[m][bj][n] = *reinterpret_cast<const f32x4*>(xr + bj * 128 + n * 16);
;       }
; #pragma unroll
;       for (int m = 0; m < 4; ++m) {
;         float* yr = p.out + (long)(row0 + ai * 128 + m * 16) * 1024 + col0;
; #pragma unroll
;         for (int bj = 0; bj < 2; ++bj)
; #pragma unroll
;           for (int n = 0; n < 2; ++n) *reinterpret_cast<f32x4*>(yr + bj * 128 + n * 16) = xv[m][bj][n] + acc[ai][bj][m][n];
;       }
;       __builtin_amdgcn_sched_barrier(0);
;     }
; __device__ __forceinline__ void gemm_run(const Params& p, int l, int kind, int single) {
;     ...
;   G_WAIT_V(0);
;   if (wr == 0) G_BAR;
	v_pk_add_f32 v[126:127], v[126:127], v[144:145]
	v_pk_add_f32 v[124:125], v[124:125], v[142:143]
	v_pk_add_f32 v[122:123], v[122:123], v[148:149]
	v_pk_add_f32 v[98:99], v[98:99], v[156:157]
	v_pk_add_f32 v[96:97], v[96:97], v[154:155]
	v_pk_add_f32 v[120:121], v[120:121], v[146:147]
	v_pk_add_f32 v[106:107], v[106:107], v[152:153]
	v_pk_add_f32 v[104:105], v[104:105], v[150:151]
	global_store_dwordx4 v[234:235], v[124:127], off
	global_store_dwordx4 v[234:235], v[120:123], off offset:64
	global_store_dwordx4 v[234:235], v[104:107], off offset:512
	global_store_dwordx4 v[234:235], v[96:99], off offset:576
	v_pk_add_f32 v[86:87], v[86:87], v[206:207]
	v_pk_add_f32 v[84:85], v[84:85], v[204:205]
	v_pk_add_f32 v[98:99], v[118:119], v[160:161]
	v_pk_add_f32 v[96:97], v[116:117], v[158:159]
	v_pk_add_f32 v[74:75], v[74:75], v[220:221]
	v_pk_add_f32 v[72:73], v[72:73], v[218:219]
	v_pk_add_f32 v[70:71], v[70:71], v[224:225]
	v_pk_add_f32 v[68:69], v[68:69], v[222:223]
	v_pk_add_f32 v[66:67], v[66:67], v[228:229]
	v_pk_add_f32 v[64:65], v[64:65], v[226:227]
	v_pk_add_f32 v[106:107], v[114:115], v[164:165]
	v_pk_add_f32 v[104:105], v[112:113], v[162:163]
	v_pk_add_f32 v[94:95], v[94:95], v[168:169]
	v_pk_add_f32 v[92:93], v[92:93], v[166:167]
	v_pk_add_f32 v[90:91], v[90:91], v[172:173]
	v_pk_add_f32 v[88:89], v[88:89], v[170:171]
	v_pk_add_f32 v[110:111], v[110:111], v[176:177]
	v_pk_add_f32 v[108:109], v[108:109], v[174:175]
	v_pk_add_f32 v[102:103], v[102:103], v[180:181]
	v_pk_add_f32 v[100:101], v[100:101], v[178:179]
	v_pk_add_f32 v[82:83], v[82:83], v[184:185]
	v_pk_add_f32 v[80:81], v[80:81], v[182:183]
	v_pk_add_f32 v[78:79], v[78:79], v[202:203]
	v_pk_add_f32 v[76:77], v[76:77], v[200:201]
	global_store_dwordx4 v[186:187], v[96:99], off
	global_store_dwordx4 v[186:187], v[104:107], off offset:64
	global_store_dwordx4 v[186:187], v[92:95], off offset:512
	global_store_dwordx4 v[186:187], v[88:91], off offset:576
	global_store_dwordx4 v[230:231], v[108:111], off
	global_store_dwordx4 v[230:231], v[100:103], off offset:64
	global_store_dwordx4 v[230:231], v[80:83], off offset:512
	global_store_dwordx4 v[230:231], v[76:79], off offset:576
	global_store_dwordx4 v[232:233], v[84:87], off
	global_store_dwordx4 v[232:233], v[72:75], off offset:64
	global_store_dwordx4 v[232:233], v[68:71], off offset:512
	global_store_dwordx4 v[232:233], v[64:67], off offset:576
	s_mov_b64 s[20:21], 0x80000
	v_lshl_add_u64 v[142:143], v[138:139], 0, s[20:21]
	s_mov_b64 s[20:21], 0x90000
	v_lshl_add_u64 v[144:145], v[138:139], 0, s[20:21]
	s_mov_b64 s[20:21], 0xa0000
	v_lshl_add_u64 v[146:147], v[138:139], 0, s[20:21]
	s_mov_b64 s[20:21], 0xb0000
	v_lshl_add_u64 v[138:139], v[138:139], 0, s[20:21]
	v_lshl_add_u64 v[76:77], v[136:137], 0, v[142:143]
	v_lshl_add_u64 v[92:93], v[136:137], 0, v[144:145]
	v_lshl_add_u64 v[108:109], v[136:137], 0, v[146:147]
	v_lshl_add_u64 v[124:125], v[136:137], 0, v[138:139]
	global_load_dwordx4 v[64:67], v[76:77], off
	global_load_dwordx4 v[68:71], v[76:77], off offset:64
	global_load_dwordx4 v[72:75], v[76:77], off offset:512
	v_lshl_add_u64 v[136:137], s[48:49], 0, v[142:143]
	global_load_dwordx4 v[76:79], v[76:77], off offset:576
	s_nop 0
	global_load_dwordx4 v[80:83], v[92:93], off
	global_load_dwordx4 v[84:87], v[92:93], off offset:64
	global_load_dwordx4 v[88:91], v[92:93], off offset:512
	v_lshl_add_u64 v[142:143], s[48:49], 0, v[144:145]
	global_load_dwordx4 v[92:95], v[92:93], off offset:576
	s_nop 0
	global_load_dwordx4 v[96:99], v[108:109], off
	global_load_dwordx4 v[100:103], v[108:109], off offset:64
	global_load_dwordx4 v[104:107], v[108:109], off offset:512
	v_lshl_add_u64 v[144:145], s[48:49], 0, v[146:147]
	global_load_dwordx4 v[108:111], v[108:109], off offset:576
	s_nop 0
	global_load_dwordx4 v[112:115], v[124:125], off
	global_load_dwordx4 v[116:119], v[124:125], off offset:64
	global_load_dwordx4 v[120:123], v[124:125], off offset:512
	s_nop 0
	global_load_dwordx4 v[124:127], v[124:125], off offset:576
	v_lshl_add_u64 v[138:139], s[48:49], 0, v[138:139]
	v_lshl_add_u64 v[136:137], v[136:137], 0, v[134:135]
	v_lshl_add_u64 v[142:143], v[142:143], 0, v[134:135]
	v_lshl_add_u64 v[144:145], v[144:145], 0, v[134:135]
	v_lshl_add_u64 v[134:135], v[138:139], 0, v[134:135]
	s_waitcnt vmcnt(0)
	v_pk_add_f32 v[62:63], v[62:63], v[66:67]
	v_pk_add_f32 v[60:61], v[60:61], v[64:65]
	v_pk_add_f32 v[58:59], v[58:59], v[70:71]
	v_pk_add_f32 v[56:57], v[56:57], v[68:69]
	v_pk_add_f32 v[42:43], v[42:43], v[74:75]
	v_pk_add_f32 v[40:41], v[40:41], v[72:73]
	v_pk_add_f32 v[34:35], v[34:35], v[78:79]
	v_pk_add_f32 v[32:33], v[32:33], v[76:77]
	v_pk_add_f32 v[54:55], v[54:55], v[82:83]
	v_pk_add_f32 v[52:53], v[52:53], v[80:81]
	v_pk_add_f32 v[50:51], v[50:51], v[86:87]
	v_pk_add_f32 v[48:49], v[48:49], v[84:85]
	v_pk_add_f32 v[26:27], v[26:27], v[90:91]
	v_pk_add_f32 v[24:25], v[24:25], v[88:89]
	v_pk_add_f32 v[22:23], v[22:23], v[94:95]
	v_pk_add_f32 v[20:21], v[20:21], v[92:93]
	v_pk_add_f32 v[46:47], v[46:47], v[98:99]
	v_pk_add_f32 v[44:45], v[44:45], v[96:97]
	v_pk_add_f32 v[38:39], v[38:39], v[102:103]
	v_pk_add_f32 v[36:37], v[36:37], v[100:101]
	v_pk_add_f32 v[14:15], v[14:15], v[106:107]
	v_pk_add_f32 v[12:13], v[12:13], v[104:105]
	v_pk_add_f32 v[10:11], v[10:11], v[110:111]
	v_pk_add_f32 v[8:9], v[8:9], v[108:109]
	v_pk_add_f32 v[30:31], v[30:31], v[114:115]
	v_pk_add_f32 v[28:29], v[28:29], v[112:113]
	v_pk_add_f32 v[18:19], v[18:19], v[118:119]
	v_pk_add_f32 v[16:17], v[16:17], v[116:117]
	v_pk_add_f32 v[6:7], v[6:7], v[122:123]
	v_pk_add_f32 v[4:5], v[4:5], v[120:121]
	v_pk_add_f32 v[2:3], v[2:3], v[126:127]
	v_pk_add_f32 v[0:1], v[0:1], v[124:125]
	global_store_dwordx4 v[136:137], v[60:63], off
	global_store_dwordx4 v[136:137], v[56:59], off offset:64
	global_store_dwordx4 v[136:137], v[40:43], off offset:512
	global_store_dwordx4 v[136:137], v[32:35], off offset:576
	global_store_dwordx4 v[142:143], v[52:55], off
	global_store_dwordx4 v[142:143], v[48:51], off offset:64
	global_store_dwordx4 v[142:143], v[24:27], off offset:512
	global_store_dwordx4 v[142:143], v[20:23], off offset:576
	global_store_dwordx4 v[144:145], v[44:47], off
	global_store_dwordx4 v[144:145], v[36:39], off offset:64
	global_store_dwordx4 v[144:145], v[12:15], off offset:512
	global_store_dwordx4 v[144:145], v[8:11], off offset:576
	global_store_dwordx4 v[134:135], v[28:31], off
	global_store_dwordx4 v[134:135], v[16:19], off offset:64
	global_store_dwordx4 v[134:135], v[4:7], off offset:512
	global_store_dwordx4 v[134:135], v[0:3], off offset:576
	s_and_b64 vcc, exec, s[6:7]
	s_mov_b32 s16, s10
	s_mov_b32 s18, s8
	s_mov_b64 s[22:23], s[14:15]
	s_mov_b64 s[20:21], s[12:13]
	s_cbranch_vccz .LBB0_401
	s_waitcnt vmcnt(0)
	s_cmpk_gt_u32 s2, 0xff
	s_mov_b32 s55, s93
	s_cbranch_scc1 .LBB0_410
	s_barrier

; #define G_STAGE(bufoff, gbase, v0, v1) do { \
;     __builtin_amdgcn_global_load_lds((const unsigned*)((const char*)(gbase) + (v0)), (LAS unsigned*)(lds + (bufoff) + ldsw), 16, 0, 0); \
;     __builtin_amdgcn_global_load_lds((const unsigned*)((const char*)(gbase) + (v1)), (LAS unsigned*)(lds + (bufoff) + ldsw + 8192), 16, 0, 0); } while (0)
; #define G_LDA(dst, b, h) do { _Pragma("unroll") for (int m = 0; m < 4; ++m) _Pragma("unroll") for (int k = 0; k < 2; ++k) dst[m][k] = *(const LAS bf16x8*)(lds + G_SA(b, h) + aoff + m * 2048 + k * 1024); } while (0)
; #define G_LDB(dst, b, h) do { _Pragma("unroll") for (int n = 0; n < 2; ++n) _Pragma("unroll") for (int k = 0; k < 2; ++k) dst[n][k] = *(const LAS bf16x8*)(lds + G_SB(b, h) + boff + n * 2048 + k * 1024); } while (0)
; #define G_MMA(ai, bj, At, Bt) do { __builtin_amdgcn_s_setprio(1); _Pragma("unroll") for (int m = 0; m < 4; ++m) _Pragma("unroll") for (int n = 0; n < 2; ++n) _Pragma("unroll") for (int k = 0; k < 2; ++k) \
;     acc[ai][bj][m][n] = __builtin_amdgcn_mfma_f32_16x16x32_bf16(Bt[n][k], At[m][k], acc[ai][bj][m][n], 0, 0, 0); __builtin_amdgcn_s_setprio(0); } while (0)
; #define G_WAIT_L(n) asm volatile("s_waitcnt lgkmcnt(" #n ")" ::: "memory")
; #define G_BAR __builtin_amdgcn_s_barrier()
; #define G_SCHED __builtin_amdgcn_sched_barrier(0)
; __device__ __forceinline__ void gemm_run(const Params& p, int l, int kind, int single) {
;     ...
;       G_LDB(B0, 0, 0); G_SCHED; G_LDA(At, 0, 0); G_STAGE(G_SA(1, 1), a1 + hc, vc0, vc1);
;       G_WAIT_L(8); G_BAR; G_WAIT_L(0); G_MMA(0, 0, At, B0); G_BAR; G_SCHED;
;       G_LDB(B1, 0, 1); G_STAGE(G_SB(0, 0), b2, w0, w1);
;       G_BAR; G_WAIT_L(0); G_MMA(0, 1, At, B1); G_BAR;
;       G_LDA(At, 0, 1); G_STAGE(G_SA(0, 0), a2, w0, w1);
;       G_BAR; G_WAIT_L(0); G_MMA(1, 0, At, B0); G_BAR; G_SCHED;
.LBB0_442:
	s_add_i32 s21, s21, 2
	s_add_u32 s48, s10, 0x80
	s_addc_u32 s49, s11, 0
	s_and_b64 s[34:35], exec, s[34:35]
	s_cselect_b32 s35, s5, s49
	s_cselect_b32 s34, s4, s48
	s_add_i32 s48, s90, 0x100
	v_add_u32_e32 v150, s48, v221
	ds_read_b128 v[138:141], v150
	ds_read_b128 v[142:145], v150 offset:1024
	ds_read_b128 v[146:149], v150 offset:2048
	ds_read_b128 v[150:153], v150 offset:3072
	v_lshl_add_u64 v[186:187], s[10:11], 0, v[130:131]
	s_add_i32 m0, s37, 0xc000
	ds_read_b128 v[154:157], v222
	ds_read_b128 v[158:161], v222 offset:1024
	ds_read_b128 v[162:165], v222 offset:2048
	ds_read_b128 v[166:169], v222 offset:3072
	ds_read_b128 v[170:173], v222 offset:4096
	ds_read_b128 v[174:177], v222 offset:5120
	ds_read_b128 v[178:181], v222 offset:6144
	ds_read_b128 v[182:185], v222 offset:7168
	global_load_lds_dwordx4 v[186:187], off
	v_lshl_add_u64 v[186:187], s[10:11], 0, v[132:133]
	s_add_i32 m0, s37, 0xe000
	s_nop 0
	global_load_lds_dwordx4 v[186:187], off
	s_waitcnt lgkmcnt(8)
	s_barrier
	s_waitcnt lgkmcnt(0)
	s_setprio 1
	v_mfma_f32_16x16x32_bf16 v[124:127], v[138:141], v[154:157], v[124:127]
	v_mfma_f32_16x16x32_bf16 v[120:123], v[146:149], v[154:157], v[120:123]
	v_mfma_f32_16x16x32_bf16 v[116:119], v[138:141], v[162:165], v[116:119]
	v_mfma_f32_16x16x32_bf16 v[112:115], v[146:149], v[162:165], v[112:115]
	v_mfma_f32_16x16x32_bf16 v[108:111], v[138:141], v[170:173], v[108:111]
	v_mfma_f32_16x16x32_bf16 v[104:107], v[146:149], v[170:173], v[104:107]
	v_mfma_f32_16x16x32_bf16 v[100:103], v[138:141], v[178:181], v[100:103]
	v_mfma_f32_16x16x32_bf16 v[96:99], v[146:149], v[178:181], v[96:99]
	v_mfma_f32_16x16x32_bf16 v[124:127], v[142:145], v[158:161], v[124:127]
	v_mfma_f32_16x16x32_bf16 v[120:123], v[150:153], v[158:161], v[120:123]
	v_mfma_f32_16x16x32_bf16 v[116:119], v[142:145], v[166:169], v[116:119]
	v_mfma_f32_16x16x32_bf16 v[112:115], v[150:153], v[166:169], v[112:115]
	v_mfma_f32_16x16x32_bf16 v[108:111], v[142:145], v[174:177], v[108:111]
	v_mfma_f32_16x16x32_bf16 v[104:107], v[150:153], v[174:177], v[104:107]
	v_mfma_f32_16x16x32_bf16 v[100:103], v[142:145], v[182:185], v[100:103]
	v_mfma_f32_16x16x32_bf16 v[96:99], v[150:153], v[182:185], v[96:99]
	s_setprio 0
	s_barrier
	s_add_i32 s49, s91, 0x100
	v_add_u32_e32 v186, s49, v221
	s_add_i32 s48, s48, s19
	ds_read_b128 v[204:207], v186
	ds_read_b128 v[224:227], v186 offset:1024
	ds_read_b128 v[228:231], v186 offset:2048
	ds_read_b128 v[232:235], v186 offset:3072
	v_lshl_add_u64 v[186:187], s[30:31], 0, v[136:137]
	s_mov_b32 m0, s48
	v_lshl_add_u64 v[236:237], s[30:31], 0, v[134:135]
	global_load_lds_dwordx4 v[186:187], off
	s_add_i32 m0, s48, 0x2000
	s_nop 0
	global_load_lds_dwordx4 v[236:237], off
	s_barrier
	s_waitcnt lgkmcnt(0)
	s_setprio 1
	v_mfma_f32_16x16x32_bf16 v[92:95], v[204:207], v[154:157], v[92:95]
	v_mfma_f32_16x16x32_bf16 v[88:91], v[228:231], v[154:157], v[88:91]
	v_mfma_f32_16x16x32_bf16 v[84:87], v[204:207], v[162:165], v[84:87]
	v_mfma_f32_16x16x32_bf16 v[80:83], v[228:231], v[162:165], v[80:83]
	v_mfma_f32_16x16x32_bf16 v[76:79], v[204:207], v[170:173], v[76:79]
	v_mfma_f32_16x16x32_bf16 v[72:75], v[228:231], v[170:173], v[72:75]
	v_mfma_f32_16x16x32_bf16 v[68:71], v[204:207], v[178:181], v[68:71]
	v_mfma_f32_16x16x32_bf16 v[64:67], v[228:231], v[178:181], v[64:67]
	v_mfma_f32_16x16x32_bf16 v[92:95], v[224:227], v[158:161], v[92:95]
	v_mfma_f32_16x16x32_bf16 v[88:91], v[232:235], v[158:161], v[88:91]
	v_mfma_f32_16x16x32_bf16 v[84:87], v[224:227], v[166:169], v[84:87]
	v_mfma_f32_16x16x32_bf16 v[80:83], v[232:235], v[166:169], v[80:83]
	v_mfma_f32_16x16x32_bf16 v[76:79], v[224:227], v[174:177], v[76:79]
	v_mfma_f32_16x16x32_bf16 v[72:75], v[232:235], v[174:177], v[72:75]
	v_mfma_f32_16x16x32_bf16 v[68:71], v[224:227], v[182:185], v[68:71]
	v_mfma_f32_16x16x32_bf16 v[64:67], v[232:235], v[182:185], v[64:67]
	s_setprio 0
	s_mov_b32 m0, s37
	v_lshl_add_u64 v[238:239], s[34:35], 0, v[136:137]
	s_barrier
	ds_read_b128 v[154:157], v222 offset:16384
	ds_read_b128 v[158:161], v222 offset:17408
	ds_read_b128 v[162:165], v222 offset:18432
	ds_read_b128 v[166:169], v222 offset:19456
	ds_read_b128 v[170:173], v222 offset:20480
	ds_read_b128 v[174:177], v222 offset:21504
	ds_read_b128 v[178:181], v222 offset:22528
	ds_read_b128 v[182:185], v222 offset:23552
	global_load_lds_dwordx4 v[238:239], off
	v_lshl_add_u64 v[240:241], s[34:35], 0, v[134:135]
	s_mov_b32 m0, s38
	s_nop 0
	global_load_lds_dwordx4 v[240:241], off
	s_barrier
	s_waitcnt lgkmcnt(0)
	s_setprio 1
	v_mfma_f32_16x16x32_bf16 v[60:63], v[138:141], v[154:157], v[60:63]
	v_mfma_f32_16x16x32_bf16 v[56:59], v[146:149], v[154:157], v[56:59]
	v_mfma_f32_16x16x32_bf16 v[52:55], v[138:141], v[162:165], v[52:55]
	v_mfma_f32_16x16x32_bf16 v[48:51], v[146:149], v[162:165], v[48:51]
	v_mfma_f32_16x16x32_bf16 v[44:47], v[138:141], v[170:173], v[44:47]
	v_mfma_f32_16x16x32_bf16 v[40:43], v[146:149], v[170:173], v[40:43]
	v_mfma_f32_16x16x32_bf16 v[36:39], v[138:141], v[178:181], v[36:39]
	v_mfma_f32_16x16x32_bf16 v[32:35], v[146:149], v[178:181], v[32:35]
	v_mfma_f32_16x16x32_bf16 v[60:63], v[142:145], v[158:161], v[60:63]
	v_mfma_f32_16x16x32_bf16 v[56:59], v[150:153], v[158:161], v[56:59]
	v_mfma_f32_16x16x32_bf16 v[52:55], v[142:145], v[166:169], v[52:55]
	v_mfma_f32_16x16x32_bf16 v[48:51], v[150:153], v[166:169], v[48:51]
	v_mfma_f32_16x16x32_bf16 v[44:47], v[142:145], v[174:177], v[44:47]
	v_mfma_f32_16x16x32_bf16 v[40:43], v[150:153], v[174:177], v[40:43]
	v_mfma_f32_16x16x32_bf16 v[36:39], v[142:145], v[182:185], v[36:39]
	v_mfma_f32_16x16x32_bf16 v[32:35], v[150:153], v[182:185], v[32:35]
	s_setprio 0
	s_barrier
; #define G_STAGE(bufoff, gbase, v0, v1) do { \
;     __builtin_amdgcn_global_load_lds((const unsigned*)((const char*)(gbase) + (v0)), (LAS unsigned*)(lds + (bufoff) + ldsw), 16, 0, 0); \
;     __builtin_amdgcn_global_load_lds((const unsigned*)((const char*)(gbase) + (v1)), (LAS unsigned*)(lds + (bufoff) + ldsw + 8192), 16, 0, 0); } while (0)
; #define G_LDA(dst, b, h) do { _Pragma("unroll") for (int m = 0; m < 4; ++m) _Pragma("unroll") for (int k = 0; k < 2; ++k) dst[m][k] = *(const LAS bf16x8*)(lds + G_SA(b, h) + aoff + m * 2048 + k * 1024); } while (0)
; #define G_LDB(dst, b, h) do { _Pragma("unroll") for (int n = 0; n < 2; ++n) _Pragma("unroll") for (int k = 0; k < 2; ++k) dst[n][k] = *(const LAS bf16x8*)(lds + G_SB(b, h) + boff + n * 2048 + k * 1024); } while (0)
; #define G_MMA(ai, bj, At, Bt) do { __builtin_amdgcn_s_setprio(1); _Pragma("unroll") for (int m = 0; m < 4; ++m) _Pragma("unroll") for (int n = 0; n < 2; ++n) _Pragma("unroll") for (int k = 0; k < 2; ++k) \
;     acc[ai][bj][m][n] = __builtin_amdgcn_mfma_f32_16x16x32_bf16(Bt[n][k], At[m][k], acc[ai][bj][m][n], 0, 0, 0); __builtin_amdgcn_s_setprio(0); } while (0)
; #define G_WAIT_V(n) asm volatile("s_waitcnt vmcnt(" #n ")" ::: "memory")
; #define G_WAIT_L(n) asm volatile("s_waitcnt lgkmcnt(" #n ")" ::: "memory")
; #define G_BAR __builtin_amdgcn_s_barrier()
; #define G_SCHED __builtin_amdgcn_sched_barrier(0)
; __device__ __forceinline__ void gemm_run(const Params& p, int l, int kind, int single) {
;     ...
;       G_STAGE(G_SB(0, 1), b2 + h2, w0, w1);
;       G_WAIT_V(6); G_BAR; G_MMA(1, 1, At, B1); G_BAR;
;       G_LDB(B0, 1, 0); G_SCHED; G_LDA(At, 1, 0); G_STAGE(G_SA(0, 1), a2 + h2, w0, w1);
;       G_WAIT_L(8); G_BAR; G_WAIT_L(0); G_MMA(0, 0, At, B0); G_BAR; G_SCHED;
;       G_LDB(B1, 1, 1); G_STAGE(G_SB(1, 0), b3, w0, w1);
;       G_BAR; G_WAIT_L(0); G_MMA(0, 1, At, B1); G_BAR;
;       G_LDA(At, 1, 1); G_STAGE(G_SA(1, 0), a3, w0, w1);
	s_add_u32 s30, s30, s28
	s_addc_u32 s31, s31, s29
	s_add_i32 s48, s49, s19
	v_lshl_add_u64 v[242:243], s[30:31], 0, v[136:137]
	s_mov_b32 m0, s48
	v_lshl_add_u64 v[244:245], s[30:31], 0, v[134:135]
	global_load_lds_dwordx4 v[242:243], off
	s_add_i32 m0, s48, 0x2000
	s_nop 0
	global_load_lds_dwordx4 v[244:245], off
	s_waitcnt vmcnt(6)
	s_barrier
	s_setprio 1
	v_mfma_f32_16x16x32_bf16 v[28:31], v[204:207], v[154:157], v[28:31]
	v_mfma_f32_16x16x32_bf16 v[24:27], v[228:231], v[154:157], v[24:27]
	v_mfma_f32_16x16x32_bf16 v[20:23], v[204:207], v[162:165], v[20:23]
	v_mfma_f32_16x16x32_bf16 v[16:19], v[228:231], v[162:165], v[16:19]
	v_mfma_f32_16x16x32_bf16 v[12:15], v[204:207], v[170:173], v[12:15]
	v_mfma_f32_16x16x32_bf16 v[8:11], v[228:231], v[170:173], v[8:11]
	v_mfma_f32_16x16x32_bf16 v[4:7], v[204:207], v[178:181], v[4:7]
	v_mfma_f32_16x16x32_bf16 v[0:3], v[228:231], v[178:181], v[0:3]
	v_mfma_f32_16x16x32_bf16 v[28:31], v[224:227], v[158:161], v[28:31]
	v_mfma_f32_16x16x32_bf16 v[24:27], v[232:235], v[158:161], v[24:27]
	v_mfma_f32_16x16x32_bf16 v[20:23], v[224:227], v[166:169], v[20:23]
	v_mfma_f32_16x16x32_bf16 v[16:19], v[232:235], v[166:169], v[16:19]
	v_mfma_f32_16x16x32_bf16 v[12:15], v[224:227], v[174:177], v[12:15]
	v_mfma_f32_16x16x32_bf16 v[8:11], v[232:235], v[174:177], v[8:11]
	v_mfma_f32_16x16x32_bf16 v[4:7], v[224:227], v[182:185], v[4:7]
	v_mfma_f32_16x16x32_bf16 v[0:3], v[232:235], v[182:185], v[0:3]
	s_setprio 0
	s_add_i32 s30, s94, 0x100
	v_add_u32_e32 v150, s30, v221
	s_barrier
	ds_read_b128 v[138:141], v150
	ds_read_b128 v[142:145], v150 offset:1024
	ds_read_b128 v[146:149], v150 offset:2048
	ds_read_b128 v[150:153], v150 offset:3072
	s_add_u32 s28, s34, s28
	s_addc_u32 s29, s35, s29
	s_mov_b32 m0, s39
	v_lshl_add_u64 v[136:137], s[28:29], 0, v[136:137]
	ds_read_b128 v[154:157], v222 offset:32768
	ds_read_b128 v[158:161], v222 offset:33792
	ds_read_b128 v[162:165], v222 offset:34816
	ds_read_b128 v[166:169], v222 offset:35840
	ds_read_b128 v[170:173], v222 offset:36864
	ds_read_b128 v[174:177], v222 offset:37888
	ds_read_b128 v[178:181], v222 offset:38912
	ds_read_b128 v[182:185], v222 offset:39936
	global_load_lds_dwordx4 v[136:137], off
	v_lshl_add_u64 v[134:135], s[28:29], 0, v[134:135]
	s_mov_b32 m0, s40
	s_nop 0
	global_load_lds_dwordx4 v[134:135], off
	s_waitcnt lgkmcnt(8)
	s_barrier
	s_waitcnt lgkmcnt(0)
	s_setprio 1
	v_mfma_f32_16x16x32_bf16 v[124:127], v[138:141], v[154:157], v[124:127]
	v_mfma_f32_16x16x32_bf16 v[120:123], v[146:149], v[154:157], v[120:123]
	v_mfma_f32_16x16x32_bf16 v[116:119], v[138:141], v[162:165], v[116:119]
	v_mfma_f32_16x16x32_bf16 v[112:115], v[146:149], v[162:165], v[112:115]
	v_mfma_f32_16x16x32_bf16 v[108:111], v[138:141], v[170:173], v[108:111]
	v_mfma_f32_16x16x32_bf16 v[104:107], v[146:149], v[170:173], v[104:107]
	v_mfma_f32_16x16x32_bf16 v[100:103], v[138:141], v[178:181], v[100:103]
	v_mfma_f32_16x16x32_bf16 v[96:99], v[146:149], v[178:181], v[96:99]
	v_mfma_f32_16x16x32_bf16 v[124:127], v[142:145], v[158:161], v[124:127]
	v_mfma_f32_16x16x32_bf16 v[120:123], v[150:153], v[158:161], v[120:123]
	v_mfma_f32_16x16x32_bf16 v[116:119], v[142:145], v[166:169], v[116:119]
	v_mfma_f32_16x16x32_bf16 v[112:115], v[150:153], v[166:169], v[112:115]
	v_mfma_f32_16x16x32_bf16 v[108:111], v[142:145], v[174:177], v[108:111]
	v_mfma_f32_16x16x32_bf16 v[104:107], v[150:153], v[174:177], v[104:107]
	v_mfma_f32_16x16x32_bf16 v[100:103], v[142:145], v[182:185], v[100:103]
	v_mfma_f32_16x16x32_bf16 v[96:99], v[150:153], v[182:185], v[96:99]
	s_setprio 0
	s_barrier
	s_add_i32 s28, s95, 0x100
	s_add_i32 s29, s30, s19
	v_add_u32_e32 v223, s28, v221
	v_lshl_add_u64 v[186:187], v[186:187], 0, s[96:97]
	s_mov_b32 m0, s29
	ds_read_b128 v[134:137], v223
	ds_read_b128 v[204:207], v223 offset:1024
	ds_read_b128 v[224:227], v223 offset:2048
	ds_read_b128 v[228:231], v223 offset:3072
	global_load_lds_dwordx4 v[186:187], off
	v_lshl_add_u64 v[186:187], v[236:237], 0, s[96:97]
	s_add_i32 m0, s29, 0x2000
	s_nop 0
	global_load_lds_dwordx4 v[186:187], off
	s_barrier
; #define G_STAGE(bufoff, gbase, v0, v1) do { \
;     __builtin_amdgcn_global_load_lds((const unsigned*)((const char*)(gbase) + (v0)), (LAS unsigned*)(lds + (bufoff) + ldsw), 16, 0, 0); \
;     __builtin_amdgcn_global_load_lds((const unsigned*)((const char*)(gbase) + (v1)), (LAS unsigned*)(lds + (bufoff) + ldsw + 8192), 16, 0, 0); } while (0)
; #define G_LDA(dst, b, h) do { _Pragma("unroll") for (int m = 0; m < 4; ++m) _Pragma("unroll") for (int k = 0; k < 2; ++k) dst[m][k] = *(const LAS bf16x8*)(lds + G_SA(b, h) + aoff + m * 2048 + k * 1024); } while (0)
; #define G_LDB(dst, b, h) do { _Pragma("unroll") for (int n = 0; n < 2; ++n) _Pragma("unroll") for (int k = 0; k < 2; ++k) dst[n][k] = *(const LAS bf16x8*)(lds + G_SB(b, h) + boff + n * 2048 + k * 1024); } while (0)
; #define G_MMA(ai, bj, At, Bt) do { __builtin_amdgcn_s_setprio(1); _Pragma("unroll") for (int m = 0; m < 4; ++m) _Pragma("unroll") for (int n = 0; n < 2; ++n) _Pragma("unroll") for (int k = 0; k < 2; ++k) \
;     acc[ai][bj][m][n] = __builtin_amdgcn_mfma_f32_16x16x32_bf16(Bt[n][k], At[m][k], acc[ai][bj][m][n], 0, 0, 0); __builtin_amdgcn_s_setprio(0); } while (0)
; #define G_WAIT_V(n) asm volatile("s_waitcnt vmcnt(" #n ")" ::: "memory")
; #define G_WAIT_L(n) asm volatile("s_waitcnt lgkmcnt(" #n ")" ::: "memory")
; #define G_BAR __builtin_amdgcn_s_barrier()
; #define G_SCHED __builtin_amdgcn_sched_barrier(0)
; __device__ __forceinline__ void gemm_run(const Params& p, int l, int kind, int single) {
;     ...
;       G_LDB(B0, 1, 0); G_SCHED; G_LDA(At, 1, 0); G_STAGE(G_SA(0, 1), a2 + h2, w0, w1);
;       G_WAIT_L(8); G_BAR; G_WAIT_L(0); G_MMA(0, 0, At, B0); G_BAR; G_SCHED;
;       G_LDB(B1, 1, 1); G_STAGE(G_SB(1, 0), b3, w0, w1);
;       G_BAR; G_WAIT_L(0); G_MMA(0, 1, At, B1); G_BAR;
;       G_LDA(At, 1, 1); G_STAGE(G_SA(1, 0), a3, w0, w1);
;       G_BAR; G_WAIT_L(0); G_MMA(1, 0, At, B0); G_BAR; G_SCHED;
;       G_STAGE(G_SB(1, 1), b3 + h2, w0, w1);
;       G_WAIT_V(6); G_BAR; G_MMA(1, 1, At, B1); G_BAR;
	s_waitcnt lgkmcnt(0)
	s_setprio 1
	v_mfma_f32_16x16x32_bf16 v[92:95], v[134:137], v[154:157], v[92:95]
	v_mfma_f32_16x16x32_bf16 v[88:91], v[224:227], v[154:157], v[88:91]
	v_mfma_f32_16x16x32_bf16 v[84:87], v[134:137], v[162:165], v[84:87]
	v_mfma_f32_16x16x32_bf16 v[80:83], v[224:227], v[162:165], v[80:83]
	v_mfma_f32_16x16x32_bf16 v[76:79], v[134:137], v[170:173], v[76:79]
	v_mfma_f32_16x16x32_bf16 v[72:75], v[224:227], v[170:173], v[72:75]
	v_mfma_f32_16x16x32_bf16 v[68:71], v[134:137], v[178:181], v[68:71]
	v_mfma_f32_16x16x32_bf16 v[64:67], v[224:227], v[178:181], v[64:67]
	v_mfma_f32_16x16x32_bf16 v[92:95], v[204:207], v[158:161], v[92:95]
	v_mfma_f32_16x16x32_bf16 v[88:91], v[228:231], v[158:161], v[88:91]
	v_mfma_f32_16x16x32_bf16 v[84:87], v[204:207], v[166:169], v[84:87]
	v_mfma_f32_16x16x32_bf16 v[80:83], v[228:231], v[166:169], v[80:83]
	v_mfma_f32_16x16x32_bf16 v[76:79], v[204:207], v[174:177], v[76:79]
	v_mfma_f32_16x16x32_bf16 v[72:75], v[228:231], v[174:177], v[72:75]
	v_mfma_f32_16x16x32_bf16 v[68:71], v[204:207], v[182:185], v[68:71]
	v_mfma_f32_16x16x32_bf16 v[64:67], v[228:231], v[182:185], v[64:67]
	s_setprio 0
	s_mov_b32 m0, s41
	v_lshl_add_u64 v[186:187], v[238:239], 0, s[96:97]
	s_barrier
	ds_read_b128 v[154:157], v222 offset:49152
	ds_read_b128 v[158:161], v222 offset:50176
	ds_read_b128 v[162:165], v222 offset:51200
	ds_read_b128 v[166:169], v222 offset:52224
	ds_read_b128 v[170:173], v222 offset:53248
	ds_read_b128 v[174:177], v222 offset:54272
	ds_read_b128 v[178:181], v222 offset:55296
	ds_read_b128 v[182:185], v222 offset:56320
	global_load_lds_dwordx4 v[186:187], off
	v_lshl_add_u64 v[186:187], v[240:241], 0, s[96:97]
	s_mov_b32 m0, s42
	s_nop 0
	global_load_lds_dwordx4 v[186:187], off
	s_barrier
	s_waitcnt lgkmcnt(0)
	s_setprio 1
	v_mfma_f32_16x16x32_bf16 v[60:63], v[138:141], v[154:157], v[60:63]
	v_mfma_f32_16x16x32_bf16 v[56:59], v[146:149], v[154:157], v[56:59]
	v_mfma_f32_16x16x32_bf16 v[52:55], v[138:141], v[162:165], v[52:55]
	v_mfma_f32_16x16x32_bf16 v[48:51], v[146:149], v[162:165], v[48:51]
	v_mfma_f32_16x16x32_bf16 v[44:47], v[138:141], v[170:173], v[44:47]
	v_mfma_f32_16x16x32_bf16 v[40:43], v[146:149], v[170:173], v[40:43]
	v_mfma_f32_16x16x32_bf16 v[36:39], v[138:141], v[178:181], v[36:39]
	v_mfma_f32_16x16x32_bf16 v[32:35], v[146:149], v[178:181], v[32:35]
	v_mfma_f32_16x16x32_bf16 v[60:63], v[142:145], v[158:161], v[60:63]
	v_mfma_f32_16x16x32_bf16 v[56:59], v[150:153], v[158:161], v[56:59]
	v_mfma_f32_16x16x32_bf16 v[52:55], v[142:145], v[166:169], v[52:55]
	v_mfma_f32_16x16x32_bf16 v[48:51], v[150:153], v[166:169], v[48:51]
	v_mfma_f32_16x16x32_bf16 v[44:47], v[142:145], v[174:177], v[44:47]
	v_mfma_f32_16x16x32_bf16 v[40:43], v[150:153], v[174:177], v[40:43]
	v_mfma_f32_16x16x32_bf16 v[36:39], v[142:145], v[182:185], v[36:39]
	v_mfma_f32_16x16x32_bf16 v[32:35], v[150:153], v[182:185], v[32:35]
	s_setprio 0
	s_barrier
	s_add_i32 s28, s28, s19
	v_lshl_add_u64 v[138:139], v[242:243], 0, s[96:97]
	s_mov_b32 m0, s28
	s_nop 0
	global_load_lds_dwordx4 v[138:139], off
	v_lshl_add_u64 v[138:139], v[244:245], 0, s[96:97]
	s_add_i32 m0, s28, 0x2000
	s_nop 0
	global_load_lds_dwordx4 v[138:139], off
	s_waitcnt vmcnt(6)
	s_barrier
	s_setprio 1
	v_mfma_f32_16x16x32_bf16 v[28:31], v[134:137], v[154:157], v[28:31]
	v_mfma_f32_16x16x32_bf16 v[24:27], v[224:227], v[154:157], v[24:27]
	v_mfma_f32_16x16x32_bf16 v[20:23], v[134:137], v[162:165], v[20:23]
	v_mfma_f32_16x16x32_bf16 v[16:19], v[224:227], v[162:165], v[16:19]
	v_mfma_f32_16x16x32_bf16 v[12:15], v[134:137], v[170:173], v[12:15]
	v_mfma_f32_16x16x32_bf16 v[8:11], v[224:227], v[170:173], v[8:11]
	v_mfma_f32_16x16x32_bf16 v[4:7], v[134:137], v[178:181], v[4:7]
	v_mfma_f32_16x16x32_bf16 v[0:3], v[224:227], v[178:181], v[0:3]
	v_mfma_f32_16x16x32_bf16 v[28:31], v[204:207], v[158:161], v[28:31]
	v_mfma_f32_16x16x32_bf16 v[24:27], v[228:231], v[158:161], v[24:27]
	v_mfma_f32_16x16x32_bf16 v[20:23], v[204:207], v[166:169], v[20:23]
	v_mfma_f32_16x16x32_bf16 v[16:19], v[228:231], v[166:169], v[16:19]
	v_mfma_f32_16x16x32_bf16 v[12:15], v[204:207], v[174:177], v[12:15]
	v_mfma_f32_16x16x32_bf16 v[8:11], v[228:231], v[174:177], v[8:11]
	v_mfma_f32_16x16x32_bf16 v[4:7], v[204:207], v[182:185], v[4:7]
	v_mfma_f32_16x16x32_bf16 v[0:3], v[228:231], v[182:185], v[0:3]
	s_setprio 0
	s_add_u32 s10, s10, 0x100
	s_addc_u32 s11, s11, 0
	s_add_u32 s26, s26, 0x100
	s_addc_u32 s27, s27, 0
	s_cmp_ge_i32 s21, s2
	s_barrier
	s_cbranch_scc1 .LBB0_445

; #define G_STAGE(bufoff, gbase, v0, v1) do { \
;     __builtin_amdgcn_global_load_lds((const unsigned*)((const char*)(gbase) + (v0)), (LAS unsigned*)(lds + (bufoff) + ldsw), 16, 0, 0); \
;     __builtin_amdgcn_global_load_lds((const unsigned*)((const char*)(gbase) + (v1)), (LAS unsigned*)(lds + (bufoff) + ldsw + 8192), 16, 0, 0); } while (0)
; #define G_LDA(dst, b, h) do { _Pragma("unroll") for (int m = 0; m < 4; ++m) _Pragma("unroll") for (int k = 0; k < 2; ++k) dst[m][k] = *(const LAS bf16x8*)(lds + G_SA(b, h) + aoff + m * 2048 + k * 1024); } while (0)
; #define G_LDB(dst, b, h) do { _Pragma("unroll") for (int n = 0; n < 2; ++n) _Pragma("unroll") for (int k = 0; k < 2; ++k) dst[n][k] = *(const LAS bf16x8*)(lds + G_SB(b, h) + boff + n * 2048 + k * 1024); } while (0)
; #define G_MMA(ai, bj, At, Bt) do { __builtin_amdgcn_s_setprio(1); _Pragma("unroll") for (int m = 0; m < 4; ++m) _Pragma("unroll") for (int n = 0; n < 2; ++n) _Pragma("unroll") for (int k = 0; k < 2; ++k) \
;     acc[ai][bj][m][n] = __builtin_amdgcn_mfma_f32_16x16x32_bf16(Bt[n][k], At[m][k], acc[ai][bj][m][n], 0, 0, 0); __builtin_amdgcn_s_setprio(0); } while (0)
; #define G_WAIT_L(n) asm volatile("s_waitcnt lgkmcnt(" #n ")" ::: "memory")
; #define G_BAR __builtin_amdgcn_s_barrier()
; #define G_SCHED __builtin_amdgcn_sched_barrier(0)
; __device__ __forceinline__ void gemm_run(const Params& p, int l, int kind, int single) {
;     ...
;     for (int t = 0; t < nt; t += 2) {
;       const bool last = (t == nt - 2);
;       const char* a1 = cA + (size_t)(t + 1) * kstep;
;       const char* a2 = last ? nA : cA + (size_t)(t + 2) * kstep; const char* b2 = last ? nB : cB + (size_t)(t + 2) * kstep;
;       const char* a3 = a2 + kstep; const char* b3 = b2 + kstep;
;       const unsigned w0 = last ? vn0 : vc0, w1 = last ? vn1 : vc1; const size_t h2 = last ? hn : hc;
;       G_LDB(B0, 0, 0); G_SCHED; G_LDA(At, 0, 0); G_STAGE(G_SA(1, 1), a1 + hc, vc0, vc1);
;       G_WAIT_L(8); G_BAR; G_WAIT_L(0); G_MMA(0, 0, At, B0); G_BAR; G_SCHED;
;       G_LDB(B1, 0, 1); G_STAGE(G_SB(0, 0), b2, w0, w1);
;       G_BAR; G_WAIT_L(0); G_MMA(0, 1, At, B1); G_BAR;
;       G_LDA(At, 0, 1); G_STAGE(G_SA(0, 0), a2, w0, w1);
;       G_BAR; G_WAIT_L(0); G_MMA(1, 0, At, B0); G_BAR; G_SCHED;
.LBB0_907:
	s_add_i32 s15, s15, 2
	s_add_u32 s44, s12, 0x80
	s_addc_u32 s45, s13, 0
	s_and_b64 s[28:29], exec, s[28:29]
	s_cselect_b32 s29, s5, s45
	s_cselect_b32 s28, s4, s44
	s_add_i32 s44, s89, 0x100
	v_add_u32_e32 v150, s44, v221
	ds_read_b128 v[138:141], v150
	ds_read_b128 v[142:145], v150 offset:1024
	ds_read_b128 v[146:149], v150 offset:2048
	ds_read_b128 v[150:153], v150 offset:3072
	v_lshl_add_u64 v[186:187], s[12:13], 0, v[130:131]
	s_add_i32 m0, s34, 0xc000
	ds_read_b128 v[154:157], v222
	ds_read_b128 v[158:161], v222 offset:1024
	ds_read_b128 v[162:165], v222 offset:2048
	ds_read_b128 v[166:169], v222 offset:3072
	ds_read_b128 v[170:173], v222 offset:4096
	ds_read_b128 v[174:177], v222 offset:5120
	ds_read_b128 v[178:181], v222 offset:6144
	ds_read_b128 v[182:185], v222 offset:7168
	global_load_lds_dwordx4 v[186:187], off
	v_lshl_add_u64 v[186:187], s[12:13], 0, v[132:133]
	s_add_i32 m0, s34, 0xe000
	s_nop 0
	global_load_lds_dwordx4 v[186:187], off
	s_waitcnt lgkmcnt(8)
	s_barrier
	s_waitcnt lgkmcnt(0)
	s_setprio 1
	v_mfma_f32_16x16x32_bf16 v[124:127], v[138:141], v[154:157], v[124:127]
	v_mfma_f32_16x16x32_bf16 v[120:123], v[146:149], v[154:157], v[120:123]
	v_mfma_f32_16x16x32_bf16 v[116:119], v[138:141], v[162:165], v[116:119]
	v_mfma_f32_16x16x32_bf16 v[112:115], v[146:149], v[162:165], v[112:115]
	v_mfma_f32_16x16x32_bf16 v[108:111], v[138:141], v[170:173], v[108:111]
	v_mfma_f32_16x16x32_bf16 v[104:107], v[146:149], v[170:173], v[104:107]
	v_mfma_f32_16x16x32_bf16 v[100:103], v[138:141], v[178:181], v[100:103]
	v_mfma_f32_16x16x32_bf16 v[96:99], v[146:149], v[178:181], v[96:99]
	v_mfma_f32_16x16x32_bf16 v[124:127], v[142:145], v[158:161], v[124:127]
	v_mfma_f32_16x16x32_bf16 v[120:123], v[150:153], v[158:161], v[120:123]
	v_mfma_f32_16x16x32_bf16 v[116:119], v[142:145], v[166:169], v[116:119]
	v_mfma_f32_16x16x32_bf16 v[112:115], v[150:153], v[166:169], v[112:115]
	v_mfma_f32_16x16x32_bf16 v[108:111], v[142:145], v[174:177], v[108:111]
	v_mfma_f32_16x16x32_bf16 v[104:107], v[150:153], v[174:177], v[104:107]
	v_mfma_f32_16x16x32_bf16 v[100:103], v[142:145], v[182:185], v[100:103]
	v_mfma_f32_16x16x32_bf16 v[96:99], v[150:153], v[182:185], v[96:99]
	s_setprio 0
	s_barrier
	s_add_i32 s45, s90, 0x100
	v_add_u32_e32 v186, s45, v221
	s_add_i32 s44, s44, s31
	ds_read_b128 v[204:207], v186
	ds_read_b128 v[224:227], v186 offset:1024
	ds_read_b128 v[228:231], v186 offset:2048
	ds_read_b128 v[232:235], v186 offset:3072
	v_lshl_add_u64 v[186:187], s[26:27], 0, v[136:137]
	s_mov_b32 m0, s44
	v_lshl_add_u64 v[236:237], s[26:27], 0, v[134:135]
	global_load_lds_dwordx4 v[186:187], off
	s_add_i32 m0, s44, 0x2000
	s_nop 0
	global_load_lds_dwordx4 v[236:237], off
	s_barrier
	s_waitcnt lgkmcnt(0)
	s_setprio 1
	v_mfma_f32_16x16x32_bf16 v[92:95], v[204:207], v[154:157], v[92:95]
	v_mfma_f32_16x16x32_bf16 v[88:91], v[228:231], v[154:157], v[88:91]
	v_mfma_f32_16x16x32_bf16 v[84:87], v[204:207], v[162:165], v[84:87]
	v_mfma_f32_16x16x32_bf16 v[80:83], v[228:231], v[162:165], v[80:83]
	v_mfma_f32_16x16x32_bf16 v[76:79], v[204:207], v[170:173], v[76:79]
	v_mfma_f32_16x16x32_bf16 v[72:75], v[228:231], v[170:173], v[72:75]
	v_mfma_f32_16x16x32_bf16 v[68:71], v[204:207], v[178:181], v[68:71]
	v_mfma_f32_16x16x32_bf16 v[64:67], v[228:231], v[178:181], v[64:67]
	v_mfma_f32_16x16x32_bf16 v[92:95], v[224:227], v[158:161], v[92:95]
	v_mfma_f32_16x16x32_bf16 v[88:91], v[232:235], v[158:161], v[88:91]
	v_mfma_f32_16x16x32_bf16 v[84:87], v[224:227], v[166:169], v[84:87]
	v_mfma_f32_16x16x32_bf16 v[80:83], v[232:235], v[166:169], v[80:83]
	v_mfma_f32_16x16x32_bf16 v[76:79], v[224:227], v[174:177], v[76:79]
	v_mfma_f32_16x16x32_bf16 v[72:75], v[232:235], v[174:177], v[72:75]
	v_mfma_f32_16x16x32_bf16 v[68:71], v[224:227], v[182:185], v[68:71]
	v_mfma_f32_16x16x32_bf16 v[64:67], v[232:235], v[182:185], v[64:67]
	s_setprio 0
	s_mov_b32 m0, s34
	v_lshl_add_u64 v[238:239], s[28:29], 0, v[136:137]
	s_barrier
	ds_read_b128 v[154:157], v222 offset:16384
	ds_read_b128 v[158:161], v222 offset:17408
	ds_read_b128 v[162:165], v222 offset:18432
	ds_read_b128 v[166:169], v222 offset:19456
	ds_read_b128 v[170:173], v222 offset:20480
	ds_read_b128 v[174:177], v222 offset:21504
	ds_read_b128 v[178:181], v222 offset:22528
	ds_read_b128 v[182:185], v222 offset:23552
	global_load_lds_dwordx4 v[238:239], off
	v_lshl_add_u64 v[240:241], s[28:29], 0, v[134:135]
	s_mov_b32 m0, s35
	s_nop 0
	global_load_lds_dwordx4 v[240:241], off
	s_barrier
	s_waitcnt lgkmcnt(0)
	s_setprio 1
	v_mfma_f32_16x16x32_bf16 v[60:63], v[138:141], v[154:157], v[60:63]
	v_mfma_f32_16x16x32_bf16 v[56:59], v[146:149], v[154:157], v[56:59]
	v_mfma_f32_16x16x32_bf16 v[52:55], v[138:141], v[162:165], v[52:55]
	v_mfma_f32_16x16x32_bf16 v[48:51], v[146:149], v[162:165], v[48:51]
	v_mfma_f32_16x16x32_bf16 v[44:47], v[138:141], v[170:173], v[44:47]
	v_mfma_f32_16x16x32_bf16 v[40:43], v[146:149], v[170:173], v[40:43]
	v_mfma_f32_16x16x32_bf16 v[36:39], v[138:141], v[178:181], v[36:39]
	v_mfma_f32_16x16x32_bf16 v[32:35], v[146:149], v[178:181], v[32:35]
	v_mfma_f32_16x16x32_bf16 v[60:63], v[142:145], v[158:161], v[60:63]
	v_mfma_f32_16x16x32_bf16 v[56:59], v[150:153], v[158:161], v[56:59]
	v_mfma_f32_16x16x32_bf16 v[52:55], v[142:145], v[166:169], v[52:55]
	v_mfma_f32_16x16x32_bf16 v[48:51], v[150:153], v[166:169], v[48:51]
	v_mfma_f32_16x16x32_bf16 v[44:47], v[142:145], v[174:177], v[44:47]
	v_mfma_f32_16x16x32_bf16 v[40:43], v[150:153], v[174:177], v[40:43]
	v_mfma_f32_16x16x32_bf16 v[36:39], v[142:145], v[182:185], v[36:39]
	v_mfma_f32_16x16x32_bf16 v[32:35], v[150:153], v[182:185], v[32:35]
	s_setprio 0
	s_barrier
; #define G_STAGE(bufoff, gbase, v0, v1) do { \
;     __builtin_amdgcn_global_load_lds((const unsigned*)((const char*)(gbase) + (v0)), (LAS unsigned*)(lds + (bufoff) + ldsw), 16, 0, 0); \
;     __builtin_amdgcn_global_load_lds((const unsigned*)((const char*)(gbase) + (v1)), (LAS unsigned*)(lds + (bufoff) + ldsw + 8192), 16, 0, 0); } while (0)
; #define G_LDA(dst, b, h) do { _Pragma("unroll") for (int m = 0; m < 4; ++m) _Pragma("unroll") for (int k = 0; k < 2; ++k) dst[m][k] = *(const LAS bf16x8*)(lds + G_SA(b, h) + aoff + m * 2048 + k * 1024); } while (0)
; #define G_LDB(dst, b, h) do { _Pragma("unroll") for (int n = 0; n < 2; ++n) _Pragma("unroll") for (int k = 0; k < 2; ++k) dst[n][k] = *(const LAS bf16x8*)(lds + G_SB(b, h) + boff + n * 2048 + k * 1024); } while (0)
; #define G_MMA(ai, bj, At, Bt) do { __builtin_amdgcn_s_setprio(1); _Pragma("unroll") for (int m = 0; m < 4; ++m) _Pragma("unroll") for (int n = 0; n < 2; ++n) _Pragma("unroll") for (int k = 0; k < 2; ++k) \
;     acc[ai][bj][m][n] = __builtin_amdgcn_mfma_f32_16x16x32_bf16(Bt[n][k], At[m][k], acc[ai][bj][m][n], 0, 0, 0); __builtin_amdgcn_s_setprio(0); } while (0)
; #define G_WAIT_V(n) asm volatile("s_waitcnt vmcnt(" #n ")" ::: "memory")
; #define G_WAIT_L(n) asm volatile("s_waitcnt lgkmcnt(" #n ")" ::: "memory")
; #define G_BAR __builtin_amdgcn_s_barrier()
; #define G_SCHED __builtin_amdgcn_sched_barrier(0)
; __device__ __forceinline__ void gemm_run(const Params& p, int l, int kind, int single) {
;     ...
;       G_STAGE(G_SB(0, 1), b2 + h2, w0, w1);
;       G_WAIT_V(6); G_BAR; G_MMA(1, 1, At, B1); G_BAR;
;       G_LDB(B0, 1, 0); G_SCHED; G_LDA(At, 1, 0); G_STAGE(G_SA(0, 1), a2 + h2, w0, w1);
;       G_WAIT_L(8); G_BAR; G_WAIT_L(0); G_MMA(0, 0, At, B0); G_BAR; G_SCHED;
;       G_LDB(B1, 1, 1); G_STAGE(G_SB(1, 0), b3, w0, w1);
	s_add_u32 s26, s26, s24
	s_addc_u32 s27, s27, s25
	s_add_i32 s44, s45, s31
	v_lshl_add_u64 v[242:243], s[26:27], 0, v[136:137]
	s_mov_b32 m0, s44
	v_lshl_add_u64 v[244:245], s[26:27], 0, v[134:135]
	global_load_lds_dwordx4 v[242:243], off
	s_add_i32 m0, s44, 0x2000
	s_nop 0
	global_load_lds_dwordx4 v[244:245], off
	s_waitcnt vmcnt(6)
	s_barrier
	s_setprio 1
	v_mfma_f32_16x16x32_bf16 v[28:31], v[204:207], v[154:157], v[28:31]
	v_mfma_f32_16x16x32_bf16 v[24:27], v[228:231], v[154:157], v[24:27]
	v_mfma_f32_16x16x32_bf16 v[20:23], v[204:207], v[162:165], v[20:23]
	v_mfma_f32_16x16x32_bf16 v[16:19], v[228:231], v[162:165], v[16:19]
	v_mfma_f32_16x16x32_bf16 v[12:15], v[204:207], v[170:173], v[12:15]
	v_mfma_f32_16x16x32_bf16 v[8:11], v[228:231], v[170:173], v[8:11]
	v_mfma_f32_16x16x32_bf16 v[4:7], v[204:207], v[178:181], v[4:7]
	v_mfma_f32_16x16x32_bf16 v[0:3], v[228:231], v[178:181], v[0:3]
	v_mfma_f32_16x16x32_bf16 v[28:31], v[224:227], v[158:161], v[28:31]
	v_mfma_f32_16x16x32_bf16 v[24:27], v[232:235], v[158:161], v[24:27]
	v_mfma_f32_16x16x32_bf16 v[20:23], v[224:227], v[166:169], v[20:23]
	v_mfma_f32_16x16x32_bf16 v[16:19], v[232:235], v[166:169], v[16:19]
	v_mfma_f32_16x16x32_bf16 v[12:15], v[224:227], v[174:177], v[12:15]
	v_mfma_f32_16x16x32_bf16 v[8:11], v[232:235], v[174:177], v[8:11]
	v_mfma_f32_16x16x32_bf16 v[4:7], v[224:227], v[182:185], v[4:7]
	v_mfma_f32_16x16x32_bf16 v[0:3], v[232:235], v[182:185], v[0:3]
	s_setprio 0
	s_add_i32 s26, s91, 0x100
	v_add_u32_e32 v150, s26, v221
	s_barrier
	ds_read_b128 v[138:141], v150
	ds_read_b128 v[142:145], v150 offset:1024
	ds_read_b128 v[146:149], v150 offset:2048
	ds_read_b128 v[150:153], v150 offset:3072
	s_add_u32 s24, s28, s24
	s_addc_u32 s25, s29, s25
	s_mov_b32 m0, s36
	v_lshl_add_u64 v[136:137], s[24:25], 0, v[136:137]
	ds_read_b128 v[154:157], v222 offset:32768
	ds_read_b128 v[158:161], v222 offset:33792
	ds_read_b128 v[162:165], v222 offset:34816
	ds_read_b128 v[166:169], v222 offset:35840
	ds_read_b128 v[170:173], v222 offset:36864
	ds_read_b128 v[174:177], v222 offset:37888
	ds_read_b128 v[178:181], v222 offset:38912
	ds_read_b128 v[182:185], v222 offset:39936
	global_load_lds_dwordx4 v[136:137], off
	v_lshl_add_u64 v[134:135], s[24:25], 0, v[134:135]
	s_mov_b32 m0, s37
	s_nop 0
	global_load_lds_dwordx4 v[134:135], off
	s_waitcnt lgkmcnt(8)
	s_barrier
	s_waitcnt lgkmcnt(0)
	s_setprio 1
	v_mfma_f32_16x16x32_bf16 v[124:127], v[138:141], v[154:157], v[124:127]
	v_mfma_f32_16x16x32_bf16 v[120:123], v[146:149], v[154:157], v[120:123]
	v_mfma_f32_16x16x32_bf16 v[116:119], v[138:141], v[162:165], v[116:119]
	v_mfma_f32_16x16x32_bf16 v[112:115], v[146:149], v[162:165], v[112:115]
	v_mfma_f32_16x16x32_bf16 v[108:111], v[138:141], v[170:173], v[108:111]
	v_mfma_f32_16x16x32_bf16 v[104:107], v[146:149], v[170:173], v[104:107]
	v_mfma_f32_16x16x32_bf16 v[100:103], v[138:141], v[178:181], v[100:103]
	v_mfma_f32_16x16x32_bf16 v[96:99], v[146:149], v[178:181], v[96:99]
	v_mfma_f32_16x16x32_bf16 v[124:127], v[142:145], v[158:161], v[124:127]
	v_mfma_f32_16x16x32_bf16 v[120:123], v[150:153], v[158:161], v[120:123]
	v_mfma_f32_16x16x32_bf16 v[116:119], v[142:145], v[166:169], v[116:119]
	v_mfma_f32_16x16x32_bf16 v[112:115], v[150:153], v[166:169], v[112:115]
	v_mfma_f32_16x16x32_bf16 v[108:111], v[142:145], v[174:177], v[108:111]
	v_mfma_f32_16x16x32_bf16 v[104:107], v[150:153], v[174:177], v[104:107]
	v_mfma_f32_16x16x32_bf16 v[100:103], v[142:145], v[182:185], v[100:103]
	v_mfma_f32_16x16x32_bf16 v[96:99], v[150:153], v[182:185], v[96:99]
	s_setprio 0
	s_barrier
	s_add_i32 s24, s94, 0x100
	s_add_i32 s25, s26, s31
	v_add_u32_e32 v223, s24, v221
	v_lshl_add_u64 v[186:187], v[186:187], 0, s[96:97]
	s_mov_b32 m0, s25
	ds_read_b128 v[134:137], v223
	ds_read_b128 v[204:207], v223 offset:1024
	ds_read_b128 v[224:227], v223 offset:2048
	ds_read_b128 v[228:231], v223 offset:3072
	global_load_lds_dwordx4 v[186:187], off
	v_lshl_add_u64 v[186:187], v[236:237], 0, s[96:97]
	s_add_i32 m0, s25, 0x2000
	s_nop 0
	global_load_lds_dwordx4 v[186:187], off
	s_barrier
; #define G_STAGE(bufoff, gbase, v0, v1) do { \
;     __builtin_amdgcn_global_load_lds((const unsigned*)((const char*)(gbase) + (v0)), (LAS unsigned*)(lds + (bufoff) + ldsw), 16, 0, 0); \
;     __builtin_amdgcn_global_load_lds((const unsigned*)((const char*)(gbase) + (v1)), (LAS unsigned*)(lds + (bufoff) + ldsw + 8192), 16, 0, 0); } while (0)
; #define G_LDA(dst, b, h) do { _Pragma("unroll") for (int m = 0; m < 4; ++m) _Pragma("unroll") for (int k = 0; k < 2; ++k) dst[m][k] = *(const LAS bf16x8*)(lds + G_SA(b, h) + aoff + m * 2048 + k * 1024); } while (0)
; #define G_LDB(dst, b, h) do { _Pragma("unroll") for (int n = 0; n < 2; ++n) _Pragma("unroll") for (int k = 0; k < 2; ++k) dst[n][k] = *(const LAS bf16x8*)(lds + G_SB(b, h) + boff + n * 2048 + k * 1024); } while (0)
; #define G_MMA(ai, bj, At, Bt) do { __builtin_amdgcn_s_setprio(1); _Pragma("unroll") for (int m = 0; m < 4; ++m) _Pragma("unroll") for (int n = 0; n < 2; ++n) _Pragma("unroll") for (int k = 0; k < 2; ++k) \
;     acc[ai][bj][m][n] = __builtin_amdgcn_mfma_f32_16x16x32_bf16(Bt[n][k], At[m][k], acc[ai][bj][m][n], 0, 0, 0); __builtin_amdgcn_s_setprio(0); } while (0)
; #define G_WAIT_V(n) asm volatile("s_waitcnt vmcnt(" #n ")" ::: "memory")
; #define G_WAIT_L(n) asm volatile("s_waitcnt lgkmcnt(" #n ")" ::: "memory")
; #define G_BAR __builtin_amdgcn_s_barrier()
; #define G_SCHED __builtin_amdgcn_sched_barrier(0)
; __device__ __forceinline__ void gemm_run(const Params& p, int l, int kind, int single) {
;     ...
;       G_LDB(B1, 1, 1); G_STAGE(G_SB(1, 0), b3, w0, w1);
;       G_BAR; G_WAIT_L(0); G_MMA(0, 1, At, B1); G_BAR;
;       G_LDA(At, 1, 1); G_STAGE(G_SA(1, 0), a3, w0, w1);
;       G_BAR; G_WAIT_L(0); G_MMA(1, 0, At, B0); G_BAR; G_SCHED;
;       G_STAGE(G_SB(1, 1), b3 + h2, w0, w1);
;       G_WAIT_V(6); G_BAR; G_MMA(1, 1, At, B1); G_BAR;
	s_waitcnt lgkmcnt(0)
	s_setprio 1
	v_mfma_f32_16x16x32_bf16 v[92:95], v[134:137], v[154:157], v[92:95]
	v_mfma_f32_16x16x32_bf16 v[88:91], v[224:227], v[154:157], v[88:91]
	v_mfma_f32_16x16x32_bf16 v[84:87], v[134:137], v[162:165], v[84:87]
	v_mfma_f32_16x16x32_bf16 v[80:83], v[224:227], v[162:165], v[80:83]
	v_mfma_f32_16x16x32_bf16 v[76:79], v[134:137], v[170:173], v[76:79]
	v_mfma_f32_16x16x32_bf16 v[72:75], v[224:227], v[170:173], v[72:75]
	v_mfma_f32_16x16x32_bf16 v[68:71], v[134:137], v[178:181], v[68:71]
	v_mfma_f32_16x16x32_bf16 v[64:67], v[224:227], v[178:181], v[64:67]
	v_mfma_f32_16x16x32_bf16 v[92:95], v[204:207], v[158:161], v[92:95]
	v_mfma_f32_16x16x32_bf16 v[88:91], v[228:231], v[158:161], v[88:91]
	v_mfma_f32_16x16x32_bf16 v[84:87], v[204:207], v[166:169], v[84:87]
	v_mfma_f32_16x16x32_bf16 v[80:83], v[228:231], v[166:169], v[80:83]
	v_mfma_f32_16x16x32_bf16 v[76:79], v[204:207], v[174:177], v[76:79]
	v_mfma_f32_16x16x32_bf16 v[72:75], v[228:231], v[174:177], v[72:75]
	v_mfma_f32_16x16x32_bf16 v[68:71], v[204:207], v[182:185], v[68:71]
	v_mfma_f32_16x16x32_bf16 v[64:67], v[228:231], v[182:185], v[64:67]
	s_setprio 0
	s_mov_b32 m0, s38
	v_lshl_add_u64 v[186:187], v[238:239], 0, s[96:97]
	s_barrier
	ds_read_b128 v[154:157], v222 offset:49152
	ds_read_b128 v[158:161], v222 offset:50176
	ds_read_b128 v[162:165], v222 offset:51200
	ds_read_b128 v[166:169], v222 offset:52224
	ds_read_b128 v[170:173], v222 offset:53248
	ds_read_b128 v[174:177], v222 offset:54272
	ds_read_b128 v[178:181], v222 offset:55296
	ds_read_b128 v[182:185], v222 offset:56320
	global_load_lds_dwordx4 v[186:187], off
	v_lshl_add_u64 v[186:187], v[240:241], 0, s[96:97]
	s_mov_b32 m0, s39
	s_nop 0
	global_load_lds_dwordx4 v[186:187], off
	s_barrier
	s_waitcnt lgkmcnt(0)
	s_setprio 1
	v_mfma_f32_16x16x32_bf16 v[60:63], v[138:141], v[154:157], v[60:63]
	v_mfma_f32_16x16x32_bf16 v[56:59], v[146:149], v[154:157], v[56:59]
	v_mfma_f32_16x16x32_bf16 v[52:55], v[138:141], v[162:165], v[52:55]
	v_mfma_f32_16x16x32_bf16 v[48:51], v[146:149], v[162:165], v[48:51]
	v_mfma_f32_16x16x32_bf16 v[44:47], v[138:141], v[170:173], v[44:47]
	v_mfma_f32_16x16x32_bf16 v[40:43], v[146:149], v[170:173], v[40:43]
	v_mfma_f32_16x16x32_bf16 v[36:39], v[138:141], v[178:181], v[36:39]
	v_mfma_f32_16x16x32_bf16 v[32:35], v[146:149], v[178:181], v[32:35]
	v_mfma_f32_16x16x32_bf16 v[60:63], v[142:145], v[158:161], v[60:63]
	v_mfma_f32_16x16x32_bf16 v[56:59], v[150:153], v[158:161], v[56:59]
	v_mfma_f32_16x16x32_bf16 v[52:55], v[142:145], v[166:169], v[52:55]
	v_mfma_f32_16x16x32_bf16 v[48:51], v[150:153], v[166:169], v[48:51]
	v_mfma_f32_16x16x32_bf16 v[44:47], v[142:145], v[174:177], v[44:47]
	v_mfma_f32_16x16x32_bf16 v[40:43], v[150:153], v[174:177], v[40:43]
	v_mfma_f32_16x16x32_bf16 v[36:39], v[142:145], v[182:185], v[36:39]
	v_mfma_f32_16x16x32_bf16 v[32:35], v[150:153], v[182:185], v[32:35]
	s_setprio 0
	s_barrier
	s_add_i32 s24, s24, s31
	v_lshl_add_u64 v[138:139], v[242:243], 0, s[96:97]
	s_mov_b32 m0, s24
	s_nop 0
	global_load_lds_dwordx4 v[138:139], off
	v_lshl_add_u64 v[138:139], v[244:245], 0, s[96:97]
	s_add_i32 m0, s24, 0x2000
	s_nop 0
	global_load_lds_dwordx4 v[138:139], off
	s_waitcnt vmcnt(6)
	s_barrier
	s_setprio 1
	v_mfma_f32_16x16x32_bf16 v[28:31], v[134:137], v[154:157], v[28:31]
	v_mfma_f32_16x16x32_bf16 v[24:27], v[224:227], v[154:157], v[24:27]
	v_mfma_f32_16x16x32_bf16 v[20:23], v[134:137], v[162:165], v[20:23]
	v_mfma_f32_16x16x32_bf16 v[16:19], v[224:227], v[162:165], v[16:19]
	v_mfma_f32_16x16x32_bf16 v[12:15], v[134:137], v[170:173], v[12:15]
	v_mfma_f32_16x16x32_bf16 v[8:11], v[224:227], v[170:173], v[8:11]
	v_mfma_f32_16x16x32_bf16 v[4:7], v[134:137], v[178:181], v[4:7]
	v_mfma_f32_16x16x32_bf16 v[0:3], v[224:227], v[178:181], v[0:3]
	v_mfma_f32_16x16x32_bf16 v[28:31], v[204:207], v[158:161], v[28:31]
	v_mfma_f32_16x16x32_bf16 v[24:27], v[228:231], v[158:161], v[24:27]
	v_mfma_f32_16x16x32_bf16 v[20:23], v[204:207], v[166:169], v[20:23]
	v_mfma_f32_16x16x32_bf16 v[16:19], v[228:231], v[166:169], v[16:19]
	v_mfma_f32_16x16x32_bf16 v[12:15], v[204:207], v[174:177], v[12:15]
	v_mfma_f32_16x16x32_bf16 v[8:11], v[228:231], v[174:177], v[8:11]
	v_mfma_f32_16x16x32_bf16 v[4:7], v[204:207], v[182:185], v[4:7]
	v_mfma_f32_16x16x32_bf16 v[0:3], v[228:231], v[182:185], v[0:3]
	s_setprio 0
	s_add_u32 s12, s12, 0x100
	s_addc_u32 s13, s13, 0
	s_add_u32 s22, s22, 0x100
	s_addc_u32 s23, s23, 0
	s_cmp_ge_i32 s15, s2
	s_barrier
	s_cbranch_scc1 .LBB0_910

; __device__ __forceinline__ float sigmoidf_(float x) { return __builtin_amdgcn_rcpf(1.f + fexp(-x)); }
; __device__ __forceinline__ unsigned pack2(float a, float b) { unsigned r; asm volatile("v_cvt_pk_bf16_f32 %0, %1, %2" : "=v"(r) : "v"(a), "v"(b)); return r; }
; __device__ __forceinline__ void gemm_epi(const Params& p, int l, int kind, const GUnit& u, f32x4 (&acc)[2][2][4][2]) {
;     ...
;     unsigned lo16 = (unsigned)tid * 16u;
;     asm volatile("" : "+v"(lo16));
;     const int br = u.sub >> 1;
;     if (!(u.sub & 1)) {
; #pragma unroll
;       for (int ai = 0; ai < 2; ++ai)
; #pragma unroll
;         for (int bj = 0; bj < 2; ++bj)
; #pragma unroll
;           for (int m = 0; m < 4; ++m) {
;             const int q = (ai * 2 + bj) * 4 + m;
;             const f32x4 a0 = acc[ai][bj][m][0], a1 = acc[ai][bj][m][1];
;             uint4 o;
;             o.x = pack2(a0[0], a0[1]); o.y = pack2(a0[2], a0[3]); o.z = pack2(a1[0], a1[1]); o.w = pack2(a1[2], a1[3]);
;             *reinterpret_cast<uint4*>((gbu + q * 8192) + lo16) = o;
;           }
;     } else {
; #pragma unroll
;       for (int ai = 0; ai < 2; ++ai) {
;         uint4 g[2][4], mm[2][4];
; #pragma unroll
;         for (int bj = 0; bj < 2; ++bj)
; #pragma unroll
;           for (int m = 0; m < 4; ++m) {
;             const int q = (ai * 2 + bj) * 4 + m;
;             g[bj][m] = *reinterpret_cast<const uint4*>((gbu + q * 8192) + lo16);
;             mm[bj][m] = *reinterpret_cast<const uint4*>((mbu + q * 8192) + lo16);
;           }
; #pragma unroll
;         for (int bj = 0; bj < 2; ++bj)
; #pragma unroll
;           for (int m = 0; m < 4; ++m) {
;             const int q = (ai * 2 + bj) * 4 + m;
;             const uint4 yy = g[bj][m]; uint4 mo = mm[bj][m];
;             mo.x = (br > 0) ? mo.x : 0u; mo.y = (br > 0) ? mo.y : 0u; mo.z = (br > 0) ? mo.z : 0u; mo.w = (br > 0) ? mo.w : 0u;
;             f32x4 s0 = acc[ai][bj][m][0], s1 = acc[ai][bj][m][1];
; #pragma unroll
;             for (int j = 0; j < 4; ++j) { s0[j] = sigmoidf_(s0[j]); s1[j] = sigmoidf_(s1[j]); }
.Lal3_a:
	v_mov_b32_e32 v203, v188
	s_lshl_b32 s2, s16, 8
	v_readfirstlane_b32 s15, v203
	s_ashr_i32 s3, s15, 2
	s_andn2_b32 s3, s3, 63
	s_add_i32 s3, s3, s2
	v_and_or_b32 v201, v203, 15, s3
	v_lshlrev_b32_e32 v190, 4, v203
	s_bitcmp0_b32 s17, 0
	s_mov_b64 s[2:3], -1
	s_cbranch_scc1 .LBB0_948
	s_ashr_i32 s2, s17, 1
	s_cmp_gt_i32 s2, 0
	s_cselect_b64 s[10:11], -1, 0
	s_cmp_lg_u32 s2, 0
	s_cbranch_scc1 .Lg3_general
	global_load_dwordx4 v[128:131], v190, s[74:75]
	v_add_u32_e32 v223, 0x2000, v190
	global_load_dwordx4 v[140:143], v223, s[74:75]
	v_add_u32_e32 v236, 0x4000, v190
	global_load_dwordx4 v[156:159], v236, s[74:75]
	v_add_u32_e32 v223, 0x6000, v190
	global_load_dwordx4 v[168:171], v223, s[74:75]
	v_add_u32_e32 v236, 0x8000, v190
	global_load_dwordx4 v[164:167], v236, s[74:75]
	v_add_u32_e32 v223, 0xa000, v190
	global_load_dwordx4 v[152:155], v223, s[74:75]
	v_add_u32_e32 v236, 0xc000, v190
	global_load_dwordx4 v[144:147], v236, s[74:75]
	v_add_u32_e32 v223, 0xe000, v190
	global_load_dwordx4 v[132:135], v223, s[74:75]
	v_mul_f32_e32 v124, 0xbfb8aa3b, v124
	v_mul_f32_e32 v125, 0xbfb8aa3b, v125
	v_mul_f32_e32 v126, 0xbfb8aa3b, v126
	v_mul_f32_e32 v127, 0xbfb8aa3b, v127
	v_mul_f32_e32 v120, 0xbfb8aa3b, v120
	v_mul_f32_e32 v121, 0xbfb8aa3b, v121
	v_mul_f32_e32 v122, 0xbfb8aa3b, v122
	v_mul_f32_e32 v123, 0xbfb8aa3b, v123
	v_exp_f32_e32 v124, v124
	v_exp_f32_e32 v125, v125
	v_exp_f32_e32 v126, v126
	v_exp_f32_e32 v127, v127
	v_exp_f32_e32 v120, v120
	v_exp_f32_e32 v121, v121
	v_exp_f32_e32 v122, v122
	v_exp_f32_e32 v123, v123
	v_add_f32_e32 v124, 1.0, v124
	v_add_f32_e32 v125, 1.0, v125
	v_add_f32_e32 v126, 1.0, v126
	v_add_f32_e32 v127, 1.0, v127
	v_add_f32_e32 v120, 1.0, v120
	v_add_f32_e32 v121, 1.0, v121
	v_add_f32_e32 v122, 1.0, v122
	v_add_f32_e32 v123, 1.0, v123
	v_rcp_f32_e32 v124, v124
	v_rcp_f32_e32 v125, v125
	v_rcp_f32_e32 v126, v126
	v_rcp_f32_e32 v127, v127
	v_rcp_f32_e32 v120, v120
	v_rcp_f32_e32 v121, v121
	v_rcp_f32_e32 v122, v122
	v_rcp_f32_e32 v123, v123
	v_mul_f32_e32 v116, 0xbfb8aa3b, v116
	v_mul_f32_e32 v117, 0xbfb8aa3b, v117
	v_mul_f32_e32 v118, 0xbfb8aa3b, v118
	v_mul_f32_e32 v119, 0xbfb8aa3b, v119
	v_mul_f32_e32 v112, 0xbfb8aa3b, v112
	v_mul_f32_e32 v113, 0xbfb8aa3b, v113
	v_mul_f32_e32 v114, 0xbfb8aa3b, v114
	v_mul_f32_e32 v115, 0xbfb8aa3b, v115
	v_exp_f32_e32 v116, v116
	v_exp_f32_e32 v117, v117
	v_exp_f32_e32 v118, v118
	v_exp_f32_e32 v119, v119
	v_exp_f32_e32 v112, v112
	v_exp_f32_e32 v113, v113
	v_exp_f32_e32 v114, v114
	v_exp_f32_e32 v115, v115
	v_add_f32_e32 v116, 1.0, v116
	v_add_f32_e32 v117, 1.0, v117
	v_add_f32_e32 v118, 1.0, v118
	v_add_f32_e32 v119, 1.0, v119
	v_add_f32_e32 v112, 1.0, v112
	v_add_f32_e32 v113, 1.0, v113
	v_add_f32_e32 v114, 1.0, v114
	v_add_f32_e32 v115, 1.0, v115
	v_rcp_f32_e32 v116, v116
	v_rcp_f32_e32 v117, v117
	v_rcp_f32_e32 v118, v118
	v_rcp_f32_e32 v119, v119
	v_rcp_f32_e32 v112, v112
	v_rcp_f32_e32 v113, v113
	v_rcp_f32_e32 v114, v114
	v_rcp_f32_e32 v115, v115
	v_mul_f32_e32 v108, 0xbfb8aa3b, v108
	v_mul_f32_e32 v109, 0xbfb8aa3b, v109
	v_mul_f32_e32 v110, 0xbfb8aa3b, v110
	v_mul_f32_e32 v111, 0xbfb8aa3b, v111
	v_mul_f32_e32 v104, 0xbfb8aa3b, v104
	v_mul_f32_e32 v105, 0xbfb8aa3b, v105
	v_mul_f32_e32 v106, 0xbfb8aa3b, v106
	v_mul_f32_e32 v107, 0xbfb8aa3b, v107
	v_exp_f32_e32 v108, v108
	v_exp_f32_e32 v109, v109
	v_exp_f32_e32 v110, v110
	v_exp_f32_e32 v111, v111
	v_exp_f32_e32 v104, v104
	v_exp_f32_e32 v105, v105
	v_exp_f32_e32 v106, v106
	v_exp_f32_e32 v107, v107
	v_add_f32_e32 v108, 1.0, v108
	v_add_f32_e32 v109, 1.0, v109
	v_add_f32_e32 v110, 1.0, v110
	v_add_f32_e32 v111, 1.0, v111
	v_add_f32_e32 v104, 1.0, v104
	v_add_f32_e32 v105, 1.0, v105
	v_add_f32_e32 v106, 1.0, v106
	v_add_f32_e32 v107, 1.0, v107
	v_rcp_f32_e32 v108, v108
	v_rcp_f32_e32 v109, v109
	v_rcp_f32_e32 v110, v110
	v_rcp_f32_e32 v111, v111
	v_rcp_f32_e32 v104, v104
	v_rcp_f32_e32 v105, v105
	v_rcp_f32_e32 v106, v106
	v_rcp_f32_e32 v107, v107
	v_mul_f32_e32 v100, 0xbfb8aa3b, v100
	v_mul_f32_e32 v101, 0xbfb8aa3b, v101
	v_mul_f32_e32 v102, 0xbfb8aa3b, v102
	v_mul_f32_e32 v103, 0xbfb8aa3b, v103
	v_mul_f32_e32 v96, 0xbfb8aa3b, v96
	v_mul_f32_e32 v97, 0xbfb8aa3b, v97
	v_mul_f32_e32 v98, 0xbfb8aa3b, v98
	v_mul_f32_e32 v99, 0xbfb8aa3b, v99
	v_exp_f32_e32 v100, v100
	v_exp_f32_e32 v101, v101
	v_exp_f32_e32 v102, v102
	v_exp_f32_e32 v103, v103
	v_exp_f32_e32 v96, v96
	v_exp_f32_e32 v97, v97
	v_exp_f32_e32 v98, v98
	v_exp_f32_e32 v99, v99
	v_add_f32_e32 v100, 1.0, v100
	v_add_f32_e32 v101, 1.0, v101
	v_add_f32_e32 v102, 1.0, v102
	v_add_f32_e32 v103, 1.0, v103
	v_add_f32_e32 v96, 1.0, v96
	v_add_f32_e32 v97, 1.0, v97
	v_add_f32_e32 v98, 1.0, v98
	v_add_f32_e32 v99, 1.0, v99
	v_rcp_f32_e32 v100, v100
	v_rcp_f32_e32 v101, v101
	v_rcp_f32_e32 v102, v102
	v_rcp_f32_e32 v103, v103
	v_rcp_f32_e32 v96, v96
	v_rcp_f32_e32 v97, v97
	v_rcp_f32_e32 v98, v98
	v_rcp_f32_e32 v99, v99
	v_mul_f32_e32 v92, 0xbfb8aa3b, v92
	v_mul_f32_e32 v93, 0xbfb8aa3b, v93
	v_mul_f32_e32 v94, 0xbfb8aa3b, v94
	v_mul_f32_e32 v95, 0xbfb8aa3b, v95
	v_mul_f32_e32 v88, 0xbfb8aa3b, v88
	v_mul_f32_e32 v89, 0xbfb8aa3b, v89
	v_mul_f32_e32 v90, 0xbfb8aa3b, v90
	v_mul_f32_e32 v91, 0xbfb8aa3b, v91
	v_exp_f32_e32 v92, v92
	v_exp_f32_e32 v93, v93
	v_exp_f32_e32 v94, v94
	v_exp_f32_e32 v95, v95
	v_exp_f32_e32 v88, v88
	v_exp_f32_e32 v89, v89
	v_exp_f32_e32 v90, v90
	v_exp_f32_e32 v91, v91
	v_add_f32_e32 v92, 1.0, v92
	v_add_f32_e32 v93, 1.0, v93
	v_add_f32_e32 v94, 1.0, v94
	v_add_f32_e32 v95, 1.0, v95
	v_add_f32_e32 v88, 1.0, v88
	v_add_f32_e32 v89, 1.0, v89
	v_add_f32_e32 v90, 1.0, v90
	v_add_f32_e32 v91, 1.0, v91
	v_rcp_f32_e32 v92, v92
	v_rcp_f32_e32 v93, v93
; __device__ __forceinline__ float sigmoidf_(float x) { return __builtin_amdgcn_rcpf(1.f + fexp(-x)); }
; __device__ __forceinline__ unsigned pack2(float a, float b) { unsigned r; asm volatile("v_cvt_pk_bf16_f32 %0, %1, %2" : "=v"(r) : "v"(a), "v"(b)); return r; }
; __device__ __forceinline__ void gemm_epi(const Params& p, int l, int kind, const GUnit& u, f32x4 (&acc)[2][2][4][2]) {
;     ...
; #pragma unroll
;         for (int bj = 0; bj < 2; ++bj)
; #pragma unroll
;           for (int m = 0; m < 4; ++m) {
;             const int q = (ai * 2 + bj) * 4 + m;
;             const uint4 yy = g[bj][m]; uint4 mo = mm[bj][m];
;             mo.x = (br > 0) ? mo.x : 0u; mo.y = (br > 0) ? mo.y : 0u; mo.z = (br > 0) ? mo.z : 0u; mo.w = (br > 0) ? mo.w : 0u;
;             f32x4 s0 = acc[ai][bj][m][0], s1 = acc[ai][bj][m][1];
; #pragma unroll
;             for (int j = 0; j < 4; ++j) { s0[j] = sigmoidf_(s0[j]); s1[j] = sigmoidf_(s1[j]); }
;             uint4 o;
;             o.x = pack2(__uint_as_float(yy.x << 16) * s0[0] + __uint_as_float(mo.x << 16), __uint_as_float(yy.x & 0xffff0000u) * s0[1] + __uint_as_float(mo.x & 0xffff0000u));
;             o.y = pack2(__uint_as_float(yy.y << 16) * s0[2] + __uint_as_float(mo.y << 16), __uint_as_float(yy.y & 0xffff0000u) * s0[3] + __uint_as_float(mo.y & 0xffff0000u));
;             o.z = pack2(__uint_as_float(yy.z << 16) * s1[0] + __uint_as_float(mo.z << 16), __uint_as_float(yy.z & 0xffff0000u) * s1[1] + __uint_as_float(mo.z & 0xffff0000u));
;             o.w = pack2(__uint_as_float(yy.w << 16) * s1[2] + __uint_as_float(mo.w << 16), __uint_as_float(yy.w & 0xffff0000u) * s1[3] + __uint_as_float(mo.w & 0xffff0000u));
;             if (br < 2) *reinterpret_cast<uint4*>((mbu + q * 8192) + lo16) = o;
;             mm[bj][m] = o;
;           }
	v_rcp_f32_e32 v94, v94
	v_rcp_f32_e32 v95, v95
	v_rcp_f32_e32 v88, v88
	v_rcp_f32_e32 v89, v89
	v_rcp_f32_e32 v90, v90
	v_rcp_f32_e32 v91, v91
	v_mul_f32_e32 v84, 0xbfb8aa3b, v84
	v_mul_f32_e32 v85, 0xbfb8aa3b, v85
	v_mul_f32_e32 v86, 0xbfb8aa3b, v86
	v_mul_f32_e32 v87, 0xbfb8aa3b, v87
	v_mul_f32_e32 v80, 0xbfb8aa3b, v80
	v_mul_f32_e32 v81, 0xbfb8aa3b, v81
	v_mul_f32_e32 v82, 0xbfb8aa3b, v82
	v_mul_f32_e32 v83, 0xbfb8aa3b, v83
	v_exp_f32_e32 v84, v84
	v_exp_f32_e32 v85, v85
	v_exp_f32_e32 v86, v86
	v_exp_f32_e32 v87, v87
	v_exp_f32_e32 v80, v80
	v_exp_f32_e32 v81, v81
	v_exp_f32_e32 v82, v82
	v_exp_f32_e32 v83, v83
	v_add_f32_e32 v84, 1.0, v84
	v_add_f32_e32 v85, 1.0, v85
	v_add_f32_e32 v86, 1.0, v86
	v_add_f32_e32 v87, 1.0, v87
	v_add_f32_e32 v80, 1.0, v80
	v_add_f32_e32 v81, 1.0, v81
	v_add_f32_e32 v82, 1.0, v82
	v_add_f32_e32 v83, 1.0, v83
	v_rcp_f32_e32 v84, v84
	v_rcp_f32_e32 v85, v85
	v_rcp_f32_e32 v86, v86
	v_rcp_f32_e32 v87, v87
	v_rcp_f32_e32 v80, v80
	v_rcp_f32_e32 v81, v81
	v_rcp_f32_e32 v82, v82
	v_rcp_f32_e32 v83, v83
	v_mul_f32_e32 v76, 0xbfb8aa3b, v76
	v_mul_f32_e32 v77, 0xbfb8aa3b, v77
	v_mul_f32_e32 v78, 0xbfb8aa3b, v78
	v_mul_f32_e32 v79, 0xbfb8aa3b, v79
	v_mul_f32_e32 v72, 0xbfb8aa3b, v72
	v_mul_f32_e32 v73, 0xbfb8aa3b, v73
	v_mul_f32_e32 v74, 0xbfb8aa3b, v74
	v_mul_f32_e32 v75, 0xbfb8aa3b, v75
	v_exp_f32_e32 v76, v76
	v_exp_f32_e32 v77, v77
	v_exp_f32_e32 v78, v78
	v_exp_f32_e32 v79, v79
	v_exp_f32_e32 v72, v72
	v_exp_f32_e32 v73, v73
	v_exp_f32_e32 v74, v74
	v_exp_f32_e32 v75, v75
	v_add_f32_e32 v76, 1.0, v76
	v_add_f32_e32 v77, 1.0, v77
	v_add_f32_e32 v78, 1.0, v78
	v_add_f32_e32 v79, 1.0, v79
	v_add_f32_e32 v72, 1.0, v72
	v_add_f32_e32 v73, 1.0, v73
	v_add_f32_e32 v74, 1.0, v74
	v_add_f32_e32 v75, 1.0, v75
	v_rcp_f32_e32 v76, v76
	v_rcp_f32_e32 v77, v77
	v_rcp_f32_e32 v78, v78
	v_rcp_f32_e32 v79, v79
	v_rcp_f32_e32 v72, v72
	v_rcp_f32_e32 v73, v73
	v_rcp_f32_e32 v74, v74
	v_rcp_f32_e32 v75, v75
	v_mul_f32_e32 v68, 0xbfb8aa3b, v68
	v_mul_f32_e32 v69, 0xbfb8aa3b, v69
	v_mul_f32_e32 v70, 0xbfb8aa3b, v70
	v_mul_f32_e32 v71, 0xbfb8aa3b, v71
	v_mul_f32_e32 v64, 0xbfb8aa3b, v64
	v_mul_f32_e32 v65, 0xbfb8aa3b, v65
	v_mul_f32_e32 v66, 0xbfb8aa3b, v66
	v_mul_f32_e32 v67, 0xbfb8aa3b, v67
	v_exp_f32_e32 v68, v68
	v_exp_f32_e32 v69, v69
	v_exp_f32_e32 v70, v70
	v_exp_f32_e32 v71, v71
	v_exp_f32_e32 v64, v64
	v_exp_f32_e32 v65, v65
	v_exp_f32_e32 v66, v66
	v_exp_f32_e32 v67, v67
	v_add_f32_e32 v68, 1.0, v68
	v_add_f32_e32 v69, 1.0, v69
	v_add_f32_e32 v70, 1.0, v70
	v_add_f32_e32 v71, 1.0, v71
	v_add_f32_e32 v64, 1.0, v64
	v_add_f32_e32 v65, 1.0, v65
	v_add_f32_e32 v66, 1.0, v66
	v_add_f32_e32 v67, 1.0, v67
	v_rcp_f32_e32 v68, v68
	v_rcp_f32_e32 v69, v69
	v_rcp_f32_e32 v70, v70
	v_rcp_f32_e32 v71, v71
	v_rcp_f32_e32 v64, v64
	v_rcp_f32_e32 v65, v65
	v_rcp_f32_e32 v66, v66
	v_rcp_f32_e32 v67, v67
	s_waitcnt vmcnt(7)
	v_lshlrev_b32_e32 v228, 16, v128
	v_lshlrev_b32_e32 v229, 16, v129
	v_lshlrev_b32_e32 v230, 16, v130
	v_lshlrev_b32_e32 v231, 16, v131
	v_and_b32_e32 v128, 0xffff0000, v128
	v_and_b32_e32 v129, 0xffff0000, v129
	v_and_b32_e32 v130, 0xffff0000, v130
	v_and_b32_e32 v131, 0xffff0000, v131
	v_fma_f32 v232, v124, v228, 0
	v_fma_f32 v233, v126, v229, 0
	v_fma_f32 v234, v120, v230, 0
	v_fma_f32 v235, v122, v231, 0
	v_fma_f32 v228, v125, v128, 0
	v_fma_f32 v229, v127, v129, 0
	v_fma_f32 v230, v121, v130, 0
	v_fma_f32 v231, v123, v131, 0
	v_cvt_pk_bf16_f32 v128, v232, v228
	v_cvt_pk_bf16_f32 v129, v233, v229
	v_cvt_pk_bf16_f32 v130, v234, v230
	v_cvt_pk_bf16_f32 v131, v235, v231
	v_add_u32_e32 v236, 0x10000, v190
	global_load_dwordx4 v[124:127], v236, s[74:75]
	s_waitcnt vmcnt(7)
	v_lshlrev_b32_e32 v228, 16, v140
	v_lshlrev_b32_e32 v229, 16, v141
	v_lshlrev_b32_e32 v230, 16, v142
	v_lshlrev_b32_e32 v231, 16, v143
	v_and_b32_e32 v140, 0xffff0000, v140
	v_and_b32_e32 v141, 0xffff0000, v141
	v_and_b32_e32 v142, 0xffff0000, v142
	v_and_b32_e32 v143, 0xffff0000, v143
	v_fma_f32 v232, v116, v228, 0
	v_fma_f32 v233, v118, v229, 0
	v_fma_f32 v234, v112, v230, 0
	v_fma_f32 v235, v114, v231, 0
	v_fma_f32 v228, v117, v140, 0
	v_fma_f32 v229, v119, v141, 0
	v_fma_f32 v230, v113, v142, 0
	v_fma_f32 v231, v115, v143, 0
	v_cvt_pk_bf16_f32 v140, v232, v228
	v_cvt_pk_bf16_f32 v141, v233, v229
	v_cvt_pk_bf16_f32 v142, v234, v230
	v_cvt_pk_bf16_f32 v143, v235, v231
	v_add_u32_e32 v223, 0x12000, v190
	global_load_dwordx4 v[116:119], v223, s[74:75]
	s_waitcnt vmcnt(7)
	v_lshlrev_b32_e32 v228, 16, v156
	v_lshlrev_b32_e32 v229, 16, v157
	v_lshlrev_b32_e32 v230, 16, v158
	v_lshlrev_b32_e32 v231, 16, v159
	v_and_b32_e32 v156, 0xffff0000, v156
	v_and_b32_e32 v157, 0xffff0000, v157
	v_and_b32_e32 v158, 0xffff0000, v158
	v_and_b32_e32 v159, 0xffff0000, v159
	v_fma_f32 v232, v108, v228, 0
	v_fma_f32 v233, v110, v229, 0
	v_fma_f32 v234, v104, v230, 0
	v_fma_f32 v235, v106, v231, 0
	v_fma_f32 v228, v109, v156, 0
	v_fma_f32 v229, v111, v157, 0
	v_fma_f32 v230, v105, v158, 0
	v_fma_f32 v231, v107, v159, 0
	v_cvt_pk_bf16_f32 v156, v232, v228
	v_cvt_pk_bf16_f32 v157, v233, v229
	v_cvt_pk_bf16_f32 v158, v234, v230
	v_cvt_pk_bf16_f32 v159, v235, v231
	v_add_u32_e32 v236, 0x14000, v190
	global_load_dwordx4 v[108:111], v236, s[74:75]
	s_waitcnt vmcnt(7)
	v_lshlrev_b32_e32 v228, 16, v168
	v_lshlrev_b32_e32 v229, 16, v169
	v_lshlrev_b32_e32 v230, 16, v170
	v_lshlrev_b32_e32 v231, 16, v171
	v_and_b32_e32 v168, 0xffff0000, v168
	v_and_b32_e32 v169, 0xffff0000, v169
	v_and_b32_e32 v170, 0xffff0000, v170
	v_and_b32_e32 v171, 0xffff0000, v171
	v_fma_f32 v232, v100, v228, 0
	v_fma_f32 v233, v102, v229, 0
	v_fma_f32 v234, v96, v230, 0
	v_fma_f32 v235, v98, v231, 0
	v_fma_f32 v228, v101, v168, 0
	v_fma_f32 v229, v103, v169, 0
	v_fma_f32 v230, v97, v170, 0
	v_fma_f32 v231, v99, v171, 0
	v_cvt_pk_bf16_f32 v168, v232, v228
	v_cvt_pk_bf16_f32 v169, v233, v229
	v_cvt_pk_bf16_f32 v170, v234, v230
	v_cvt_pk_bf16_f32 v171, v235, v231
	v_add_u32_e32 v223, 0x16000, v190
	global_load_dwordx4 v[100:103], v223, s[74:75]
	s_waitcnt vmcnt(7)
; __device__ __forceinline__ float sigmoidf_(float x) { return __builtin_amdgcn_rcpf(1.f + fexp(-x)); }
; __device__ __forceinline__ unsigned pack2(float a, float b) { unsigned r; asm volatile("v_cvt_pk_bf16_f32 %0, %1, %2" : "=v"(r) : "v"(a), "v"(b)); return r; }
; __device__ __forceinline__ void gemm_epi(const Params& p, int l, int kind, const GUnit& u, f32x4 (&acc)[2][2][4][2]) {
;     ...
; #pragma unroll
;         for (int bj = 0; bj < 2; ++bj)
; #pragma unroll
;           for (int m = 0; m < 4; ++m) {
;             const int q = (ai * 2 + bj) * 4 + m;
;             const uint4 yy = g[bj][m]; uint4 mo = mm[bj][m];
;             mo.x = (br > 0) ? mo.x : 0u; mo.y = (br > 0) ? mo.y : 0u; mo.z = (br > 0) ? mo.z : 0u; mo.w = (br > 0) ? mo.w : 0u;
;             f32x4 s0 = acc[ai][bj][m][0], s1 = acc[ai][bj][m][1];
; #pragma unroll
;             for (int j = 0; j < 4; ++j) { s0[j] = sigmoidf_(s0[j]); s1[j] = sigmoidf_(s1[j]); }
;             uint4 o;
;             o.x = pack2(__uint_as_float(yy.x << 16) * s0[0] + __uint_as_float(mo.x << 16), __uint_as_float(yy.x & 0xffff0000u) * s0[1] + __uint_as_float(mo.x & 0xffff0000u));
;             o.y = pack2(__uint_as_float(yy.y << 16) * s0[2] + __uint_as_float(mo.y << 16), __uint_as_float(yy.y & 0xffff0000u) * s0[3] + __uint_as_float(mo.y & 0xffff0000u));
;             o.z = pack2(__uint_as_float(yy.z << 16) * s1[0] + __uint_as_float(mo.z << 16), __uint_as_float(yy.z & 0xffff0000u) * s1[1] + __uint_as_float(mo.z & 0xffff0000u));
;             o.w = pack2(__uint_as_float(yy.w << 16) * s1[2] + __uint_as_float(mo.w << 16), __uint_as_float(yy.w & 0xffff0000u) * s1[3] + __uint_as_float(mo.w & 0xffff0000u));
;             if (br < 2) *reinterpret_cast<uint4*>((mbu + q * 8192) + lo16) = o;
;             mm[bj][m] = o;
;           }
	v_lshlrev_b32_e32 v228, 16, v164
	v_lshlrev_b32_e32 v229, 16, v165
	v_lshlrev_b32_e32 v230, 16, v166
	v_lshlrev_b32_e32 v231, 16, v167
	v_and_b32_e32 v164, 0xffff0000, v164
	v_and_b32_e32 v165, 0xffff0000, v165
	v_and_b32_e32 v166, 0xffff0000, v166
	v_and_b32_e32 v167, 0xffff0000, v167
	v_fma_f32 v232, v92, v228, 0
	v_fma_f32 v233, v94, v229, 0
	v_fma_f32 v234, v88, v230, 0
	v_fma_f32 v235, v90, v231, 0
	v_fma_f32 v228, v93, v164, 0
	v_fma_f32 v229, v95, v165, 0
	v_fma_f32 v230, v89, v166, 0
	v_fma_f32 v231, v91, v167, 0
	v_cvt_pk_bf16_f32 v164, v232, v228
	v_cvt_pk_bf16_f32 v165, v233, v229
	v_cvt_pk_bf16_f32 v166, v234, v230
	v_cvt_pk_bf16_f32 v167, v235, v231
	v_add_u32_e32 v236, 0x18000, v190
	global_load_dwordx4 v[92:95], v236, s[74:75]
	s_waitcnt vmcnt(7)
	v_lshlrev_b32_e32 v228, 16, v152
	v_lshlrev_b32_e32 v229, 16, v153
	v_lshlrev_b32_e32 v230, 16, v154
	v_lshlrev_b32_e32 v231, 16, v155
	v_and_b32_e32 v152, 0xffff0000, v152
	v_and_b32_e32 v153, 0xffff0000, v153
	v_and_b32_e32 v154, 0xffff0000, v154
	v_and_b32_e32 v155, 0xffff0000, v155
	v_fma_f32 v232, v84, v228, 0
	v_fma_f32 v233, v86, v229, 0
	v_fma_f32 v234, v80, v230, 0
	v_fma_f32 v235, v82, v231, 0
	v_fma_f32 v228, v85, v152, 0
	v_fma_f32 v229, v87, v153, 0
	v_fma_f32 v230, v81, v154, 0
	v_fma_f32 v231, v83, v155, 0
	v_cvt_pk_bf16_f32 v152, v232, v228
	v_cvt_pk_bf16_f32 v153, v233, v229
	v_cvt_pk_bf16_f32 v154, v234, v230
	v_cvt_pk_bf16_f32 v155, v235, v231
	v_add_u32_e32 v223, 0x1a000, v190
	global_load_dwordx4 v[84:87], v223, s[74:75]
	s_waitcnt vmcnt(7)
	v_lshlrev_b32_e32 v228, 16, v144
	v_lshlrev_b32_e32 v229, 16, v145
	v_lshlrev_b32_e32 v230, 16, v146
	v_lshlrev_b32_e32 v231, 16, v147
	v_and_b32_e32 v144, 0xffff0000, v144
	v_and_b32_e32 v145, 0xffff0000, v145
	v_and_b32_e32 v146, 0xffff0000, v146
	v_and_b32_e32 v147, 0xffff0000, v147
	v_fma_f32 v232, v76, v228, 0
	v_fma_f32 v233, v78, v229, 0
	v_fma_f32 v234, v72, v230, 0
	v_fma_f32 v235, v74, v231, 0
	v_fma_f32 v228, v77, v144, 0
	v_fma_f32 v229, v79, v145, 0
	v_fma_f32 v230, v73, v146, 0
	v_fma_f32 v231, v75, v147, 0
	v_cvt_pk_bf16_f32 v144, v232, v228
	v_cvt_pk_bf16_f32 v145, v233, v229
	v_cvt_pk_bf16_f32 v146, v234, v230
	v_cvt_pk_bf16_f32 v147, v235, v231
	v_add_u32_e32 v236, 0x1c000, v190
	global_load_dwordx4 v[76:79], v236, s[74:75]
	s_waitcnt vmcnt(7)
	v_lshlrev_b32_e32 v228, 16, v132
	v_lshlrev_b32_e32 v229, 16, v133
	v_lshlrev_b32_e32 v230, 16, v134
	v_lshlrev_b32_e32 v231, 16, v135
	v_and_b32_e32 v132, 0xffff0000, v132
	v_and_b32_e32 v133, 0xffff0000, v133
	v_and_b32_e32 v134, 0xffff0000, v134
	v_and_b32_e32 v135, 0xffff0000, v135
	v_fma_f32 v232, v68, v228, 0
	v_fma_f32 v233, v70, v229, 0
	v_fma_f32 v234, v64, v230, 0
	v_fma_f32 v235, v66, v231, 0
	v_fma_f32 v228, v69, v132, 0
	v_fma_f32 v229, v71, v133, 0
	v_fma_f32 v230, v65, v134, 0
	v_fma_f32 v231, v67, v135, 0
	v_cvt_pk_bf16_f32 v132, v232, v228
	v_cvt_pk_bf16_f32 v133, v233, v229
	v_cvt_pk_bf16_f32 v134, v234, v230
	v_cvt_pk_bf16_f32 v135, v235, v231
	v_add_u32_e32 v223, 0x1e000, v190
	global_load_dwordx4 v[68:71], v223, s[74:75]
	global_store_dwordx4 v190, v[128:131], s[78:79]
	v_add_u32_e32 v223, 0x2000, v190
	global_store_dwordx4 v223, v[140:143], s[78:79]
	v_add_u32_e32 v236, 0x4000, v190
	global_store_dwordx4 v236, v[156:159], s[78:79]
	v_add_u32_e32 v223, 0x6000, v190
	global_store_dwordx4 v223, v[168:171], s[78:79]
	v_add_u32_e32 v236, 0x8000, v190
	global_store_dwordx4 v236, v[164:167], s[78:79]
	v_add_u32_e32 v223, 0xa000, v190
	global_store_dwordx4 v223, v[152:155], s[78:79]
	v_add_u32_e32 v236, 0xc000, v190
	global_store_dwordx4 v236, v[144:147], s[78:79]
	v_add_u32_e32 v223, 0xe000, v190
	global_store_dwordx4 v223, v[132:135], s[78:79]
	v_mul_f32_e32 v60, 0xbfb8aa3b, v60
	v_mul_f32_e32 v61, 0xbfb8aa3b, v61
	v_mul_f32_e32 v62, 0xbfb8aa3b, v62
	v_mul_f32_e32 v63, 0xbfb8aa3b, v63
	v_mul_f32_e32 v56, 0xbfb8aa3b, v56
	v_mul_f32_e32 v57, 0xbfb8aa3b, v57
	v_mul_f32_e32 v58, 0xbfb8aa3b, v58
	v_mul_f32_e32 v59, 0xbfb8aa3b, v59
	v_exp_f32_e32 v60, v60
	v_exp_f32_e32 v61, v61
	v_exp_f32_e32 v62, v62
	v_exp_f32_e32 v63, v63
	v_exp_f32_e32 v56, v56
	v_exp_f32_e32 v57, v57
	v_exp_f32_e32 v58, v58
	v_exp_f32_e32 v59, v59
	v_add_f32_e32 v60, 1.0, v60
	v_add_f32_e32 v61, 1.0, v61
	v_add_f32_e32 v62, 1.0, v62
	v_add_f32_e32 v63, 1.0, v63
	v_add_f32_e32 v56, 1.0, v56
	v_add_f32_e32 v57, 1.0, v57
	v_add_f32_e32 v58, 1.0, v58
	v_add_f32_e32 v59, 1.0, v59
	v_rcp_f32_e32 v60, v60
	v_rcp_f32_e32 v61, v61
	v_rcp_f32_e32 v62, v62
	v_rcp_f32_e32 v63, v63
	v_rcp_f32_e32 v56, v56
	v_rcp_f32_e32 v57, v57
	v_rcp_f32_e32 v58, v58
	v_rcp_f32_e32 v59, v59
	v_mul_f32_e32 v52, 0xbfb8aa3b, v52
	v_mul_f32_e32 v53, 0xbfb8aa3b, v53
	v_mul_f32_e32 v54, 0xbfb8aa3b, v54
	v_mul_f32_e32 v55, 0xbfb8aa3b, v55
	v_mul_f32_e32 v48, 0xbfb8aa3b, v48
	v_mul_f32_e32 v49, 0xbfb8aa3b, v49
	v_mul_f32_e32 v50, 0xbfb8aa3b, v50
	v_mul_f32_e32 v51, 0xbfb8aa3b, v51
	v_exp_f32_e32 v52, v52
	v_exp_f32_e32 v53, v53
	v_exp_f32_e32 v54, v54
	v_exp_f32_e32 v55, v55
	v_exp_f32_e32 v48, v48
	v_exp_f32_e32 v49, v49
	v_exp_f32_e32 v50, v50
	v_exp_f32_e32 v51, v51
	v_add_f32_e32 v52, 1.0, v52
	v_add_f32_e32 v53, 1.0, v53
	v_add_f32_e32 v54, 1.0, v54
	v_add_f32_e32 v55, 1.0, v55
	v_add_f32_e32 v48, 1.0, v48
	v_add_f32_e32 v49, 1.0, v49
	v_add_f32_e32 v50, 1.0, v50
	v_add_f32_e32 v51, 1.0, v51
	v_rcp_f32_e32 v52, v52
	v_rcp_f32_e32 v53, v53
	v_rcp_f32_e32 v54, v54
	v_rcp_f32_e32 v55, v55
	v_rcp_f32_e32 v48, v48
	v_rcp_f32_e32 v49, v49
	v_rcp_f32_e32 v50, v50
	v_rcp_f32_e32 v51, v51
	v_mul_f32_e32 v44, 0xbfb8aa3b, v44
	v_mul_f32_e32 v45, 0xbfb8aa3b, v45
	v_mul_f32_e32 v46, 0xbfb8aa3b, v46
	v_mul_f32_e32 v47, 0xbfb8aa3b, v47
; __device__ __forceinline__ float sigmoidf_(float x) { return __builtin_amdgcn_rcpf(1.f + fexp(-x)); }
; __device__ __forceinline__ unsigned pack2(float a, float b) { unsigned r; asm volatile("v_cvt_pk_bf16_f32 %0, %1, %2" : "=v"(r) : "v"(a), "v"(b)); return r; }
; __device__ __forceinline__ void gemm_epi(const Params& p, int l, int kind, const GUnit& u, f32x4 (&acc)[2][2][4][2]) {
;     ...
; #pragma unroll
;         for (int bj = 0; bj < 2; ++bj)
; #pragma unroll
;           for (int m = 0; m < 4; ++m) {
;             const int q = (ai * 2 + bj) * 4 + m;
;             const uint4 yy = g[bj][m]; uint4 mo = mm[bj][m];
;             mo.x = (br > 0) ? mo.x : 0u; mo.y = (br > 0) ? mo.y : 0u; mo.z = (br > 0) ? mo.z : 0u; mo.w = (br > 0) ? mo.w : 0u;
;             f32x4 s0 = acc[ai][bj][m][0], s1 = acc[ai][bj][m][1];
; #pragma unroll
;             for (int j = 0; j < 4; ++j) { s0[j] = sigmoidf_(s0[j]); s1[j] = sigmoidf_(s1[j]); }
;             uint4 o;
;             o.x = pack2(__uint_as_float(yy.x << 16) * s0[0] + __uint_as_float(mo.x << 16), __uint_as_float(yy.x & 0xffff0000u) * s0[1] + __uint_as_float(mo.x & 0xffff0000u));
;             o.y = pack2(__uint_as_float(yy.y << 16) * s0[2] + __uint_as_float(mo.y << 16), __uint_as_float(yy.y & 0xffff0000u) * s0[3] + __uint_as_float(mo.y & 0xffff0000u));
;             o.z = pack2(__uint_as_float(yy.z << 16) * s1[0] + __uint_as_float(mo.z << 16), __uint_as_float(yy.z & 0xffff0000u) * s1[1] + __uint_as_float(mo.z & 0xffff0000u));
;             o.w = pack2(__uint_as_float(yy.w << 16) * s1[2] + __uint_as_float(mo.w << 16), __uint_as_float(yy.w & 0xffff0000u) * s1[3] + __uint_as_float(mo.w & 0xffff0000u));
;             if (br < 2) *reinterpret_cast<uint4*>((mbu + q * 8192) + lo16) = o;
;             mm[bj][m] = o;
;           }
	v_mul_f32_e32 v40, 0xbfb8aa3b, v40
	v_mul_f32_e32 v41, 0xbfb8aa3b, v41
	v_mul_f32_e32 v42, 0xbfb8aa3b, v42
	v_mul_f32_e32 v43, 0xbfb8aa3b, v43
	v_exp_f32_e32 v44, v44
	v_exp_f32_e32 v45, v45
	v_exp_f32_e32 v46, v46
	v_exp_f32_e32 v47, v47
	v_exp_f32_e32 v40, v40
	v_exp_f32_e32 v41, v41
	v_exp_f32_e32 v42, v42
	v_exp_f32_e32 v43, v43
	v_add_f32_e32 v44, 1.0, v44
	v_add_f32_e32 v45, 1.0, v45
	v_add_f32_e32 v46, 1.0, v46
	v_add_f32_e32 v47, 1.0, v47
	v_add_f32_e32 v40, 1.0, v40
	v_add_f32_e32 v41, 1.0, v41
	v_add_f32_e32 v42, 1.0, v42
	v_add_f32_e32 v43, 1.0, v43
	v_rcp_f32_e32 v44, v44
	v_rcp_f32_e32 v45, v45
	v_rcp_f32_e32 v46, v46
	v_rcp_f32_e32 v47, v47
	v_rcp_f32_e32 v40, v40
	v_rcp_f32_e32 v41, v41
	v_rcp_f32_e32 v42, v42
	v_rcp_f32_e32 v43, v43
	v_mul_f32_e32 v36, 0xbfb8aa3b, v36
	v_mul_f32_e32 v37, 0xbfb8aa3b, v37
	v_mul_f32_e32 v38, 0xbfb8aa3b, v38
	v_mul_f32_e32 v39, 0xbfb8aa3b, v39
	v_mul_f32_e32 v32, 0xbfb8aa3b, v32
	v_mul_f32_e32 v33, 0xbfb8aa3b, v33
	v_mul_f32_e32 v34, 0xbfb8aa3b, v34
	v_mul_f32_e32 v35, 0xbfb8aa3b, v35
	v_exp_f32_e32 v36, v36
	v_exp_f32_e32 v37, v37
	v_exp_f32_e32 v38, v38
	v_exp_f32_e32 v39, v39
	v_exp_f32_e32 v32, v32
	v_exp_f32_e32 v33, v33
	v_exp_f32_e32 v34, v34
	v_exp_f32_e32 v35, v35
	v_add_f32_e32 v36, 1.0, v36
	v_add_f32_e32 v37, 1.0, v37
	v_add_f32_e32 v38, 1.0, v38
	v_add_f32_e32 v39, 1.0, v39
	v_add_f32_e32 v32, 1.0, v32
	v_add_f32_e32 v33, 1.0, v33
	v_add_f32_e32 v34, 1.0, v34
	v_add_f32_e32 v35, 1.0, v35
	v_rcp_f32_e32 v36, v36
	v_rcp_f32_e32 v37, v37
	v_rcp_f32_e32 v38, v38
	v_rcp_f32_e32 v39, v39
	v_rcp_f32_e32 v32, v32
	v_rcp_f32_e32 v33, v33
	v_rcp_f32_e32 v34, v34
	v_rcp_f32_e32 v35, v35
	v_mul_f32_e32 v28, 0xbfb8aa3b, v28
	v_mul_f32_e32 v29, 0xbfb8aa3b, v29
	v_mul_f32_e32 v30, 0xbfb8aa3b, v30
	v_mul_f32_e32 v31, 0xbfb8aa3b, v31
	v_mul_f32_e32 v24, 0xbfb8aa3b, v24
	v_mul_f32_e32 v25, 0xbfb8aa3b, v25
	v_mul_f32_e32 v26, 0xbfb8aa3b, v26
	v_mul_f32_e32 v27, 0xbfb8aa3b, v27
	v_exp_f32_e32 v28, v28
	v_exp_f32_e32 v29, v29
	v_exp_f32_e32 v30, v30
	v_exp_f32_e32 v31, v31
	v_exp_f32_e32 v24, v24
	v_exp_f32_e32 v25, v25
	v_exp_f32_e32 v26, v26
	v_exp_f32_e32 v27, v27
	v_add_f32_e32 v28, 1.0, v28
	v_add_f32_e32 v29, 1.0, v29
	v_add_f32_e32 v30, 1.0, v30
	v_add_f32_e32 v31, 1.0, v31
	v_add_f32_e32 v24, 1.0, v24
	v_add_f32_e32 v25, 1.0, v25
	v_add_f32_e32 v26, 1.0, v26
	v_add_f32_e32 v27, 1.0, v27
	v_rcp_f32_e32 v28, v28
	v_rcp_f32_e32 v29, v29
	v_rcp_f32_e32 v30, v30
	v_rcp_f32_e32 v31, v31
	v_rcp_f32_e32 v24, v24
	v_rcp_f32_e32 v25, v25
	v_rcp_f32_e32 v26, v26
	v_rcp_f32_e32 v27, v27
	v_mul_f32_e32 v20, 0xbfb8aa3b, v20
	v_mul_f32_e32 v21, 0xbfb8aa3b, v21
	v_mul_f32_e32 v22, 0xbfb8aa3b, v22
	v_mul_f32_e32 v23, 0xbfb8aa3b, v23
	v_mul_f32_e32 v16, 0xbfb8aa3b, v16
	v_mul_f32_e32 v17, 0xbfb8aa3b, v17
	v_mul_f32_e32 v18, 0xbfb8aa3b, v18
	v_mul_f32_e32 v19, 0xbfb8aa3b, v19
	v_exp_f32_e32 v20, v20
	v_exp_f32_e32 v21, v21
	v_exp_f32_e32 v22, v22
	v_exp_f32_e32 v23, v23
	v_exp_f32_e32 v16, v16
	v_exp_f32_e32 v17, v17
	v_exp_f32_e32 v18, v18
	v_exp_f32_e32 v19, v19
	v_add_f32_e32 v20, 1.0, v20
	v_add_f32_e32 v21, 1.0, v21
	v_add_f32_e32 v22, 1.0, v22
	v_add_f32_e32 v23, 1.0, v23
	v_add_f32_e32 v16, 1.0, v16
	v_add_f32_e32 v17, 1.0, v17
	v_add_f32_e32 v18, 1.0, v18
	v_add_f32_e32 v19, 1.0, v19
	v_rcp_f32_e32 v20, v20
	v_rcp_f32_e32 v21, v21
	v_rcp_f32_e32 v22, v22
	v_rcp_f32_e32 v23, v23
	v_rcp_f32_e32 v16, v16
	v_rcp_f32_e32 v17, v17
	v_rcp_f32_e32 v18, v18
	v_rcp_f32_e32 v19, v19
	v_mul_f32_e32 v12, 0xbfb8aa3b, v12
	v_mul_f32_e32 v13, 0xbfb8aa3b, v13
	v_mul_f32_e32 v14, 0xbfb8aa3b, v14
	v_mul_f32_e32 v15, 0xbfb8aa3b, v15
	v_mul_f32_e32 v8, 0xbfb8aa3b, v8
	v_mul_f32_e32 v9, 0xbfb8aa3b, v9
	v_mul_f32_e32 v10, 0xbfb8aa3b, v10
	v_mul_f32_e32 v11, 0xbfb8aa3b, v11
	v_exp_f32_e32 v12, v12
	v_exp_f32_e32 v13, v13
	v_exp_f32_e32 v14, v14
	v_exp_f32_e32 v15, v15
	v_exp_f32_e32 v8, v8
	v_exp_f32_e32 v9, v9
	v_exp_f32_e32 v10, v10
	v_exp_f32_e32 v11, v11
	v_add_f32_e32 v12, 1.0, v12
	v_add_f32_e32 v13, 1.0, v13
	v_add_f32_e32 v14, 1.0, v14
	v_add_f32_e32 v15, 1.0, v15
	v_add_f32_e32 v8, 1.0, v8
	v_add_f32_e32 v9, 1.0, v9
	v_add_f32_e32 v10, 1.0, v10
	v_add_f32_e32 v11, 1.0, v11
	v_rcp_f32_e32 v12, v12
	v_rcp_f32_e32 v13, v13
	v_rcp_f32_e32 v14, v14
	v_rcp_f32_e32 v15, v15
	v_rcp_f32_e32 v8, v8
	v_rcp_f32_e32 v9, v9
	v_rcp_f32_e32 v10, v10
	v_rcp_f32_e32 v11, v11
	v_mul_f32_e32 v4, 0xbfb8aa3b, v4
	v_mul_f32_e32 v5, 0xbfb8aa3b, v5
	v_mul_f32_e32 v6, 0xbfb8aa3b, v6
	v_mul_f32_e32 v7, 0xbfb8aa3b, v7
	v_mul_f32_e32 v0, 0xbfb8aa3b, v0
	v_mul_f32_e32 v1, 0xbfb8aa3b, v1
	v_mul_f32_e32 v2, 0xbfb8aa3b, v2
	v_mul_f32_e32 v3, 0xbfb8aa3b, v3
	v_exp_f32_e32 v4, v4
	v_exp_f32_e32 v5, v5
	v_exp_f32_e32 v6, v6
	v_exp_f32_e32 v7, v7
	v_exp_f32_e32 v0, v0
	v_exp_f32_e32 v1, v1
	v_exp_f32_e32 v2, v2
	v_exp_f32_e32 v3, v3
	v_add_f32_e32 v4, 1.0, v4
	v_add_f32_e32 v5, 1.0, v5
	v_add_f32_e32 v6, 1.0, v6
	v_add_f32_e32 v7, 1.0, v7
	v_add_f32_e32 v0, 1.0, v0
	v_add_f32_e32 v1, 1.0, v1
	v_add_f32_e32 v2, 1.0, v2
	v_add_f32_e32 v3, 1.0, v3
	v_rcp_f32_e32 v4, v4
	v_rcp_f32_e32 v5, v5
	v_rcp_f32_e32 v6, v6
	v_rcp_f32_e32 v7, v7
	v_rcp_f32_e32 v0, v0
	v_rcp_f32_e32 v1, v1
	v_rcp_f32_e32 v2, v2
	v_rcp_f32_e32 v3, v3
	s_waitcnt vmcnt(15)
	v_lshlrev_b32_e32 v228, 16, v124
	v_lshlrev_b32_e32 v229, 16, v125
	v_lshlrev_b32_e32 v230, 16, v126
	v_lshlrev_b32_e32 v231, 16, v127
	v_and_b32_e32 v124, 0xffff0000, v124
	v_and_b32_e32 v125, 0xffff0000, v125
	v_and_b32_e32 v126, 0xffff0000, v126
	v_and_b32_e32 v127, 0xffff0000, v127
	v_fma_f32 v232, v60, v228, 0
	v_fma_f32 v233, v62, v229, 0
	v_fma_f32 v234, v56, v230, 0
	v_fma_f32 v235, v58, v231, 0
	v_fma_f32 v228, v61, v124, 0
	v_fma_f32 v229, v63, v125, 0
	v_fma_f32 v230, v57, v126, 0
	v_fma_f32 v231, v59, v127, 0
	v_cvt_pk_bf16_f32 v124, v232, v228
	v_cvt_pk_bf16_f32 v125, v233, v229
	v_cvt_pk_bf16_f32 v126, v234, v230
	v_cvt_pk_bf16_f32 v127, v235, v231
	v_add_u32_e32 v236, 0x10000, v190
	global_store_dwordx4 v236, v[124:127], s[78:79]
	s_waitcnt vmcnt(14)
; __device__ __forceinline__ float sigmoidf_(float x) { return __builtin_amdgcn_rcpf(1.f + fexp(-x)); }
; __device__ __forceinline__ unsigned pack2(float a, float b) { unsigned r; asm volatile("v_cvt_pk_bf16_f32 %0, %1, %2" : "=v"(r) : "v"(a), "v"(b)); return r; }
; __device__ __forceinline__ void gemm_epi(const Params& p, int l, int kind, const GUnit& u, f32x4 (&acc)[2][2][4][2]) {
;     ...
; #pragma unroll
;         for (int bj = 0; bj < 2; ++bj)
; #pragma unroll
;           for (int m = 0; m < 4; ++m) {
;             const int q = (ai * 2 + bj) * 4 + m;
;             const uint4 yy = g[bj][m]; uint4 mo = mm[bj][m];
;             mo.x = (br > 0) ? mo.x : 0u; mo.y = (br > 0) ? mo.y : 0u; mo.z = (br > 0) ? mo.z : 0u; mo.w = (br > 0) ? mo.w : 0u;
;             f32x4 s0 = acc[ai][bj][m][0], s1 = acc[ai][bj][m][1];
; #pragma unroll
;             for (int j = 0; j < 4; ++j) { s0[j] = sigmoidf_(s0[j]); s1[j] = sigmoidf_(s1[j]); }
;             uint4 o;
;             o.x = pack2(__uint_as_float(yy.x << 16) * s0[0] + __uint_as_float(mo.x << 16), __uint_as_float(yy.x & 0xffff0000u) * s0[1] + __uint_as_float(mo.x & 0xffff0000u));
;             o.y = pack2(__uint_as_float(yy.y << 16) * s0[2] + __uint_as_float(mo.y << 16), __uint_as_float(yy.y & 0xffff0000u) * s0[3] + __uint_as_float(mo.y & 0xffff0000u));
;             o.z = pack2(__uint_as_float(yy.z << 16) * s1[0] + __uint_as_float(mo.z << 16), __uint_as_float(yy.z & 0xffff0000u) * s1[1] + __uint_as_float(mo.z & 0xffff0000u));
;             o.w = pack2(__uint_as_float(yy.w << 16) * s1[2] + __uint_as_float(mo.w << 16), __uint_as_float(yy.w & 0xffff0000u) * s1[3] + __uint_as_float(mo.w & 0xffff0000u));
;             if (br < 2) *reinterpret_cast<uint4*>((mbu + q * 8192) + lo16) = o;
;             mm[bj][m] = o;
;           }
	v_lshlrev_b32_e32 v228, 16, v116
	v_lshlrev_b32_e32 v229, 16, v117
	v_lshlrev_b32_e32 v230, 16, v118
	v_lshlrev_b32_e32 v231, 16, v119
	v_and_b32_e32 v116, 0xffff0000, v116
	v_and_b32_e32 v117, 0xffff0000, v117
	v_and_b32_e32 v118, 0xffff0000, v118
	v_and_b32_e32 v119, 0xffff0000, v119
	v_fma_f32 v232, v52, v228, 0
	v_fma_f32 v233, v54, v229, 0
	v_fma_f32 v234, v48, v230, 0
	v_fma_f32 v235, v50, v231, 0
	v_fma_f32 v228, v53, v116, 0
	v_fma_f32 v229, v55, v117, 0
	v_fma_f32 v230, v49, v118, 0
	v_fma_f32 v231, v51, v119, 0
	v_cvt_pk_bf16_f32 v116, v232, v228
	v_cvt_pk_bf16_f32 v117, v233, v229
	v_cvt_pk_bf16_f32 v118, v234, v230
	v_cvt_pk_bf16_f32 v119, v235, v231
	v_add_u32_e32 v223, 0x12000, v190
	global_store_dwordx4 v223, v[116:119], s[78:79]
	s_waitcnt vmcnt(13)
	v_lshlrev_b32_e32 v228, 16, v108
	v_lshlrev_b32_e32 v229, 16, v109
	v_lshlrev_b32_e32 v230, 16, v110
	v_lshlrev_b32_e32 v231, 16, v111
	v_and_b32_e32 v108, 0xffff0000, v108
	v_and_b32_e32 v109, 0xffff0000, v109
	v_and_b32_e32 v110, 0xffff0000, v110
	v_and_b32_e32 v111, 0xffff0000, v111
	v_fma_f32 v232, v44, v228, 0
	v_fma_f32 v233, v46, v229, 0
	v_fma_f32 v234, v40, v230, 0
	v_fma_f32 v235, v42, v231, 0
	v_fma_f32 v228, v45, v108, 0
	v_fma_f32 v229, v47, v109, 0
	v_fma_f32 v230, v41, v110, 0
	v_fma_f32 v231, v43, v111, 0
	v_cvt_pk_bf16_f32 v108, v232, v228
	v_cvt_pk_bf16_f32 v109, v233, v229
	v_cvt_pk_bf16_f32 v110, v234, v230
	v_cvt_pk_bf16_f32 v111, v235, v231
	v_add_u32_e32 v236, 0x14000, v190
	global_store_dwordx4 v236, v[108:111], s[78:79]
	s_waitcnt vmcnt(12)
	v_lshlrev_b32_e32 v228, 16, v100
	v_lshlrev_b32_e32 v229, 16, v101
	v_lshlrev_b32_e32 v230, 16, v102
	v_lshlrev_b32_e32 v231, 16, v103
	v_and_b32_e32 v100, 0xffff0000, v100
	v_and_b32_e32 v101, 0xffff0000, v101
	v_and_b32_e32 v102, 0xffff0000, v102
	v_and_b32_e32 v103, 0xffff0000, v103
	v_fma_f32 v232, v36, v228, 0
	v_fma_f32 v233, v38, v229, 0
	v_fma_f32 v234, v32, v230, 0
	v_fma_f32 v235, v34, v231, 0
	v_fma_f32 v228, v37, v100, 0
	v_fma_f32 v229, v39, v101, 0
	v_fma_f32 v230, v33, v102, 0
	v_fma_f32 v231, v35, v103, 0
	v_cvt_pk_bf16_f32 v100, v232, v228
	v_cvt_pk_bf16_f32 v101, v233, v229
	v_cvt_pk_bf16_f32 v102, v234, v230
	v_cvt_pk_bf16_f32 v103, v235, v231
	v_add_u32_e32 v223, 0x16000, v190
	global_store_dwordx4 v223, v[100:103], s[78:79]
	s_waitcnt vmcnt(11)
	v_lshlrev_b32_e32 v228, 16, v92
	v_lshlrev_b32_e32 v229, 16, v93
	v_lshlrev_b32_e32 v230, 16, v94
	v_lshlrev_b32_e32 v231, 16, v95
	v_and_b32_e32 v92, 0xffff0000, v92
	v_and_b32_e32 v93, 0xffff0000, v93
	v_and_b32_e32 v94, 0xffff0000, v94
	v_and_b32_e32 v95, 0xffff0000, v95
	v_fma_f32 v232, v28, v228, 0
	v_fma_f32 v233, v30, v229, 0
	v_fma_f32 v234, v24, v230, 0
	v_fma_f32 v235, v26, v231, 0
	v_fma_f32 v228, v29, v92, 0
	v_fma_f32 v229, v31, v93, 0
	v_fma_f32 v230, v25, v94, 0
	v_fma_f32 v231, v27, v95, 0
	v_cvt_pk_bf16_f32 v92, v232, v228
	v_cvt_pk_bf16_f32 v93, v233, v229
	v_cvt_pk_bf16_f32 v94, v234, v230
	v_cvt_pk_bf16_f32 v95, v235, v231
	v_add_u32_e32 v236, 0x18000, v190
	global_store_dwordx4 v236, v[92:95], s[78:79]
	s_waitcnt vmcnt(10)
	v_lshlrev_b32_e32 v228, 16, v84
	v_lshlrev_b32_e32 v229, 16, v85
	v_lshlrev_b32_e32 v230, 16, v86
	v_lshlrev_b32_e32 v231, 16, v87
	v_and_b32_e32 v84, 0xffff0000, v84
	v_and_b32_e32 v85, 0xffff0000, v85
	v_and_b32_e32 v86, 0xffff0000, v86
	v_and_b32_e32 v87, 0xffff0000, v87
	v_fma_f32 v232, v20, v228, 0
	v_fma_f32 v233, v22, v229, 0
	v_fma_f32 v234, v16, v230, 0
	v_fma_f32 v235, v18, v231, 0
	v_fma_f32 v228, v21, v84, 0
	v_fma_f32 v229, v23, v85, 0
	v_fma_f32 v230, v17, v86, 0
	v_fma_f32 v231, v19, v87, 0
	v_cvt_pk_bf16_f32 v84, v232, v228
	v_cvt_pk_bf16_f32 v85, v233, v229
	v_cvt_pk_bf16_f32 v86, v234, v230
	v_cvt_pk_bf16_f32 v87, v235, v231
	v_add_u32_e32 v223, 0x1a000, v190
	global_store_dwordx4 v223, v[84:87], s[78:79]
	s_waitcnt vmcnt(9)
	v_lshlrev_b32_e32 v228, 16, v76
	v_lshlrev_b32_e32 v229, 16, v77
	v_lshlrev_b32_e32 v230, 16, v78
	v_lshlrev_b32_e32 v231, 16, v79
	v_and_b32_e32 v76, 0xffff0000, v76
	v_and_b32_e32 v77, 0xffff0000, v77
	v_and_b32_e32 v78, 0xffff0000, v78
	v_and_b32_e32 v79, 0xffff0000, v79
	v_fma_f32 v232, v12, v228, 0
	v_fma_f32 v233, v14, v229, 0
	v_fma_f32 v234, v8, v230, 0
	v_fma_f32 v235, v10, v231, 0
	v_fma_f32 v228, v13, v76, 0
	v_fma_f32 v229, v15, v77, 0
	v_fma_f32 v230, v9, v78, 0
	v_fma_f32 v231, v11, v79, 0
	v_cvt_pk_bf16_f32 v76, v232, v228
	v_cvt_pk_bf16_f32 v77, v233, v229
	v_cvt_pk_bf16_f32 v78, v234, v230
	v_cvt_pk_bf16_f32 v79, v235, v231
	v_add_u32_e32 v236, 0x1c000, v190
	global_store_dwordx4 v236, v[76:79], s[78:79]
	s_waitcnt vmcnt(8)
	v_lshlrev_b32_e32 v228, 16, v68
	v_lshlrev_b32_e32 v229, 16, v69
	v_lshlrev_b32_e32 v230, 16, v70
	v_lshlrev_b32_e32 v231, 16, v71
	v_and_b32_e32 v68, 0xffff0000, v68
	v_and_b32_e32 v69, 0xffff0000, v69
	v_and_b32_e32 v70, 0xffff0000, v70
	v_and_b32_e32 v71, 0xffff0000, v71
	v_fma_f32 v232, v4, v228, 0
	v_fma_f32 v233, v6, v229, 0
	v_fma_f32 v234, v0, v230, 0
	v_fma_f32 v235, v2, v231, 0
	v_fma_f32 v228, v5, v68, 0
	v_fma_f32 v229, v7, v69, 0
	v_fma_f32 v230, v1, v70, 0
	v_fma_f32 v231, v3, v71, 0
	v_cvt_pk_bf16_f32 v68, v232, v228
	v_cvt_pk_bf16_f32 v69, v233, v229
	v_cvt_pk_bf16_f32 v70, v234, v230
	v_cvt_pk_bf16_f32 v71, v235, v231
	v_add_u32_e32 v223, 0x1e000, v190
	global_store_dwordx4 v223, v[68:71], s[78:79]
	s_branch .Lg3_end
; __device__ __forceinline__ float sigmoidf_(float x) { return __builtin_amdgcn_rcpf(1.f + fexp(-x)); }
; __device__ __forceinline__ void gemm_epi(const Params& p, int l, int kind, const GUnit& u, f32x4 (&acc)[2][2][4][2]) {
;     ...
;     } else {
; #pragma unroll
;       for (int ai = 0; ai < 2; ++ai) {
;         uint4 g[2][4], mm[2][4];
; #pragma unroll
;         for (int bj = 0; bj < 2; ++bj)
; #pragma unroll
;           for (int m = 0; m < 4; ++m) {
;             const int q = (ai * 2 + bj) * 4 + m;
;             g[bj][m] = *reinterpret_cast<const uint4*>((gbu + q * 8192) + lo16);
;             mm[bj][m] = *reinterpret_cast<const uint4*>((mbu + q * 8192) + lo16);
;           }
; #pragma unroll
;         for (int bj = 0; bj < 2; ++bj)
; #pragma unroll
;           for (int m = 0; m < 4; ++m) {
;             const int q = (ai * 2 + bj) * 4 + m;
;             const uint4 yy = g[bj][m]; uint4 mo = mm[bj][m];
;             mo.x = (br > 0) ? mo.x : 0u; mo.y = (br > 0) ? mo.y : 0u; mo.z = (br > 0) ? mo.z : 0u; mo.w = (br > 0) ? mo.w : 0u;
;             f32x4 s0 = acc[ai][bj][m][0], s1 = acc[ai][bj][m][1];
; #pragma unroll
;             for (int j = 0; j < 4; ++j) { s0[j] = sigmoidf_(s0[j]); s1[j] = sigmoidf_(s1[j]); }
.Lg3_general:
	global_load_dwordx4 v[128:131], v190, s[74:75]
	global_load_dwordx4 v[224:227], v190, s[78:79]
	v_add_u32_e32 v223, 0x2000, v190
	global_load_dwordx4 v[140:143], v223, s[74:75]
	global_load_dwordx4 v[184:187], v223, s[78:79]
	v_add_u32_e32 v236, 0x4000, v190
	global_load_dwordx4 v[156:159], v236, s[74:75]
	global_load_dwordx4 v[180:183], v236, s[78:79]
	v_add_u32_e32 v223, 0x6000, v190
	global_load_dwordx4 v[168:171], v223, s[74:75]
	global_load_dwordx4 v[176:179], v223, s[78:79]
	v_add_u32_e32 v236, 0x8000, v190
	global_load_dwordx4 v[164:167], v236, s[74:75]
	global_load_dwordx4 v[172:175], v236, s[78:79]
	v_add_u32_e32 v223, 0xa000, v190
	global_load_dwordx4 v[152:155], v223, s[74:75]
	global_load_dwordx4 v[160:163], v223, s[78:79]
	v_add_u32_e32 v236, 0xc000, v190
	global_load_dwordx4 v[144:147], v236, s[74:75]
	global_load_dwordx4 v[148:151], v236, s[78:79]
	v_add_u32_e32 v223, 0xe000, v190
	global_load_dwordx4 v[132:135], v223, s[74:75]
	global_load_dwordx4 v[136:139], v223, s[78:79]
	v_mul_f32_e32 v124, 0xbfb8aa3b, v124
	v_mul_f32_e32 v125, 0xbfb8aa3b, v125
	v_mul_f32_e32 v126, 0xbfb8aa3b, v126
	v_mul_f32_e32 v127, 0xbfb8aa3b, v127
	v_mul_f32_e32 v120, 0xbfb8aa3b, v120
	v_mul_f32_e32 v121, 0xbfb8aa3b, v121
	v_mul_f32_e32 v122, 0xbfb8aa3b, v122
	v_mul_f32_e32 v123, 0xbfb8aa3b, v123
	v_exp_f32_e32 v124, v124
	v_exp_f32_e32 v125, v125
	v_exp_f32_e32 v126, v126
	v_exp_f32_e32 v127, v127
	v_exp_f32_e32 v120, v120
	v_exp_f32_e32 v121, v121
	v_exp_f32_e32 v122, v122
	v_exp_f32_e32 v123, v123
	v_add_f32_e32 v124, 1.0, v124
	v_add_f32_e32 v125, 1.0, v125
	v_add_f32_e32 v126, 1.0, v126
	v_add_f32_e32 v127, 1.0, v127
	v_add_f32_e32 v120, 1.0, v120
	v_add_f32_e32 v121, 1.0, v121
	v_add_f32_e32 v122, 1.0, v122
	v_add_f32_e32 v123, 1.0, v123
	v_rcp_f32_e32 v124, v124
	v_rcp_f32_e32 v125, v125
	v_rcp_f32_e32 v126, v126
	v_rcp_f32_e32 v127, v127
	v_rcp_f32_e32 v120, v120
	v_rcp_f32_e32 v121, v121
	v_rcp_f32_e32 v122, v122
	v_rcp_f32_e32 v123, v123
	v_mul_f32_e32 v116, 0xbfb8aa3b, v116
	v_mul_f32_e32 v117, 0xbfb8aa3b, v117
	v_mul_f32_e32 v118, 0xbfb8aa3b, v118
	v_mul_f32_e32 v119, 0xbfb8aa3b, v119
	v_mul_f32_e32 v112, 0xbfb8aa3b, v112
	v_mul_f32_e32 v113, 0xbfb8aa3b, v113
	v_mul_f32_e32 v114, 0xbfb8aa3b, v114
	v_mul_f32_e32 v115, 0xbfb8aa3b, v115
	v_exp_f32_e32 v116, v116
	v_exp_f32_e32 v117, v117
	v_exp_f32_e32 v118, v118
	v_exp_f32_e32 v119, v119
	v_exp_f32_e32 v112, v112
	v_exp_f32_e32 v113, v113
	v_exp_f32_e32 v114, v114
	v_exp_f32_e32 v115, v115
	v_add_f32_e32 v116, 1.0, v116
	v_add_f32_e32 v117, 1.0, v117
	v_add_f32_e32 v118, 1.0, v118
	v_add_f32_e32 v119, 1.0, v119
	v_add_f32_e32 v112, 1.0, v112
	v_add_f32_e32 v113, 1.0, v113
	v_add_f32_e32 v114, 1.0, v114
	v_add_f32_e32 v115, 1.0, v115
	v_rcp_f32_e32 v116, v116
	v_rcp_f32_e32 v117, v117
	v_rcp_f32_e32 v118, v118
	v_rcp_f32_e32 v119, v119
	v_rcp_f32_e32 v112, v112
	v_rcp_f32_e32 v113, v113
	v_rcp_f32_e32 v114, v114
	v_rcp_f32_e32 v115, v115
	v_mul_f32_e32 v108, 0xbfb8aa3b, v108
	v_mul_f32_e32 v109, 0xbfb8aa3b, v109
	v_mul_f32_e32 v110, 0xbfb8aa3b, v110
	v_mul_f32_e32 v111, 0xbfb8aa3b, v111
	v_mul_f32_e32 v104, 0xbfb8aa3b, v104
	v_mul_f32_e32 v105, 0xbfb8aa3b, v105
	v_mul_f32_e32 v106, 0xbfb8aa3b, v106
	v_mul_f32_e32 v107, 0xbfb8aa3b, v107
	v_exp_f32_e32 v108, v108
	v_exp_f32_e32 v109, v109
	v_exp_f32_e32 v110, v110
	v_exp_f32_e32 v111, v111
	v_exp_f32_e32 v104, v104
	v_exp_f32_e32 v105, v105
	v_exp_f32_e32 v106, v106
	v_exp_f32_e32 v107, v107
	v_add_f32_e32 v108, 1.0, v108
	v_add_f32_e32 v109, 1.0, v109
	v_add_f32_e32 v110, 1.0, v110
	v_add_f32_e32 v111, 1.0, v111
	v_add_f32_e32 v104, 1.0, v104
	v_add_f32_e32 v105, 1.0, v105
	v_add_f32_e32 v106, 1.0, v106
	v_add_f32_e32 v107, 1.0, v107
	v_rcp_f32_e32 v108, v108
	v_rcp_f32_e32 v109, v109
	v_rcp_f32_e32 v110, v110
	v_rcp_f32_e32 v111, v111
	v_rcp_f32_e32 v104, v104
	v_rcp_f32_e32 v105, v105
	v_rcp_f32_e32 v106, v106
	v_rcp_f32_e32 v107, v107
	v_mul_f32_e32 v100, 0xbfb8aa3b, v100
	v_mul_f32_e32 v101, 0xbfb8aa3b, v101
	v_mul_f32_e32 v102, 0xbfb8aa3b, v102
	v_mul_f32_e32 v103, 0xbfb8aa3b, v103
	v_mul_f32_e32 v96, 0xbfb8aa3b, v96
	v_mul_f32_e32 v97, 0xbfb8aa3b, v97
	v_mul_f32_e32 v98, 0xbfb8aa3b, v98
	v_mul_f32_e32 v99, 0xbfb8aa3b, v99
	v_exp_f32_e32 v100, v100
	v_exp_f32_e32 v101, v101
	v_exp_f32_e32 v102, v102
	v_exp_f32_e32 v103, v103
	v_exp_f32_e32 v96, v96
	v_exp_f32_e32 v97, v97
	v_exp_f32_e32 v98, v98
	v_exp_f32_e32 v99, v99
	v_add_f32_e32 v100, 1.0, v100
	v_add_f32_e32 v101, 1.0, v101
	v_add_f32_e32 v102, 1.0, v102
	v_add_f32_e32 v103, 1.0, v103
	v_add_f32_e32 v96, 1.0, v96
	v_add_f32_e32 v97, 1.0, v97
	v_add_f32_e32 v98, 1.0, v98
	v_add_f32_e32 v99, 1.0, v99
	v_rcp_f32_e32 v100, v100
	v_rcp_f32_e32 v101, v101
	v_rcp_f32_e32 v102, v102
	v_rcp_f32_e32 v103, v103
	v_rcp_f32_e32 v96, v96
	v_rcp_f32_e32 v97, v97
	v_rcp_f32_e32 v98, v98
	v_rcp_f32_e32 v99, v99
	v_mul_f32_e32 v92, 0xbfb8aa3b, v92
	v_mul_f32_e32 v93, 0xbfb8aa3b, v93
	v_mul_f32_e32 v94, 0xbfb8aa3b, v94
	v_mul_f32_e32 v95, 0xbfb8aa3b, v95
	v_mul_f32_e32 v88, 0xbfb8aa3b, v88
	v_mul_f32_e32 v89, 0xbfb8aa3b, v89
	v_mul_f32_e32 v90, 0xbfb8aa3b, v90
	v_mul_f32_e32 v91, 0xbfb8aa3b, v91
	v_exp_f32_e32 v92, v92
	v_exp_f32_e32 v93, v93
	v_exp_f32_e32 v94, v94
	v_exp_f32_e32 v95, v95
	v_exp_f32_e32 v88, v88
	v_exp_f32_e32 v89, v89
	v_exp_f32_e32 v90, v90
	v_exp_f32_e32 v91, v91
	v_add_f32_e32 v92, 1.0, v92
	v_add_f32_e32 v93, 1.0, v93
	v_add_f32_e32 v94, 1.0, v94
	v_add_f32_e32 v95, 1.0, v95
	v_add_f32_e32 v88, 1.0, v88
	v_add_f32_e32 v89, 1.0, v89
	v_add_f32_e32 v90, 1.0, v90
	v_add_f32_e32 v91, 1.0, v91
	v_rcp_f32_e32 v92, v92
	v_rcp_f32_e32 v93, v93
	v_rcp_f32_e32 v94, v94
; __device__ __forceinline__ float sigmoidf_(float x) { return __builtin_amdgcn_rcpf(1.f + fexp(-x)); }
; __device__ __forceinline__ unsigned pack2(float a, float b) { unsigned r; asm volatile("v_cvt_pk_bf16_f32 %0, %1, %2" : "=v"(r) : "v"(a), "v"(b)); return r; }
; __device__ __forceinline__ void gemm_epi(const Params& p, int l, int kind, const GUnit& u, f32x4 (&acc)[2][2][4][2]) {
;     ...
;         uint4 g[2][4], mm[2][4];
; #pragma unroll
;         for (int bj = 0; bj < 2; ++bj)
; #pragma unroll
;           for (int m = 0; m < 4; ++m) {
;             const int q = (ai * 2 + bj) * 4 + m;
;             g[bj][m] = *reinterpret_cast<const uint4*>((gbu + q * 8192) + lo16);
;             mm[bj][m] = *reinterpret_cast<const uint4*>((mbu + q * 8192) + lo16);
;           }
; #pragma unroll
;         for (int bj = 0; bj < 2; ++bj)
; #pragma unroll
;           for (int m = 0; m < 4; ++m) {
;             const int q = (ai * 2 + bj) * 4 + m;
;             const uint4 yy = g[bj][m]; uint4 mo = mm[bj][m];
;             mo.x = (br > 0) ? mo.x : 0u; mo.y = (br > 0) ? mo.y : 0u; mo.z = (br > 0) ? mo.z : 0u; mo.w = (br > 0) ? mo.w : 0u;
;             f32x4 s0 = acc[ai][bj][m][0], s1 = acc[ai][bj][m][1];
; #pragma unroll
;             for (int j = 0; j < 4; ++j) { s0[j] = sigmoidf_(s0[j]); s1[j] = sigmoidf_(s1[j]); }
;             uint4 o;
;             o.x = pack2(__uint_as_float(yy.x << 16) * s0[0] + __uint_as_float(mo.x << 16), __uint_as_float(yy.x & 0xffff0000u) * s0[1] + __uint_as_float(mo.x & 0xffff0000u));
;             o.y = pack2(__uint_as_float(yy.y << 16) * s0[2] + __uint_as_float(mo.y << 16), __uint_as_float(yy.y & 0xffff0000u) * s0[3] + __uint_as_float(mo.y & 0xffff0000u));
;             o.z = pack2(__uint_as_float(yy.z << 16) * s1[0] + __uint_as_float(mo.z << 16), __uint_as_float(yy.z & 0xffff0000u) * s1[1] + __uint_as_float(mo.z & 0xffff0000u));
;             o.w = pack2(__uint_as_float(yy.w << 16) * s1[2] + __uint_as_float(mo.w << 16), __uint_as_float(yy.w & 0xffff0000u) * s1[3] + __uint_as_float(mo.w & 0xffff0000u));
;             if (br < 2) *reinterpret_cast<uint4*>((mbu + q * 8192) + lo16) = o;
;             mm[bj][m] = o;
;           }
	v_rcp_f32_e32 v95, v95
	v_rcp_f32_e32 v88, v88
	v_rcp_f32_e32 v89, v89
	v_rcp_f32_e32 v90, v90
	v_rcp_f32_e32 v91, v91
	v_mul_f32_e32 v84, 0xbfb8aa3b, v84
	v_mul_f32_e32 v85, 0xbfb8aa3b, v85
	v_mul_f32_e32 v86, 0xbfb8aa3b, v86
	v_mul_f32_e32 v87, 0xbfb8aa3b, v87
	v_mul_f32_e32 v80, 0xbfb8aa3b, v80
	v_mul_f32_e32 v81, 0xbfb8aa3b, v81
	v_mul_f32_e32 v82, 0xbfb8aa3b, v82
	v_mul_f32_e32 v83, 0xbfb8aa3b, v83
	v_exp_f32_e32 v84, v84
	v_exp_f32_e32 v85, v85
	v_exp_f32_e32 v86, v86
	v_exp_f32_e32 v87, v87
	v_exp_f32_e32 v80, v80
	v_exp_f32_e32 v81, v81
	v_exp_f32_e32 v82, v82
	v_exp_f32_e32 v83, v83
	v_add_f32_e32 v84, 1.0, v84
	v_add_f32_e32 v85, 1.0, v85
	v_add_f32_e32 v86, 1.0, v86
	v_add_f32_e32 v87, 1.0, v87
	v_add_f32_e32 v80, 1.0, v80
	v_add_f32_e32 v81, 1.0, v81
	v_add_f32_e32 v82, 1.0, v82
	v_add_f32_e32 v83, 1.0, v83
	v_rcp_f32_e32 v84, v84
	v_rcp_f32_e32 v85, v85
	v_rcp_f32_e32 v86, v86
	v_rcp_f32_e32 v87, v87
	v_rcp_f32_e32 v80, v80
	v_rcp_f32_e32 v81, v81
	v_rcp_f32_e32 v82, v82
	v_rcp_f32_e32 v83, v83
	v_mul_f32_e32 v76, 0xbfb8aa3b, v76
	v_mul_f32_e32 v77, 0xbfb8aa3b, v77
	v_mul_f32_e32 v78, 0xbfb8aa3b, v78
	v_mul_f32_e32 v79, 0xbfb8aa3b, v79
	v_mul_f32_e32 v72, 0xbfb8aa3b, v72
	v_mul_f32_e32 v73, 0xbfb8aa3b, v73
	v_mul_f32_e32 v74, 0xbfb8aa3b, v74
	v_mul_f32_e32 v75, 0xbfb8aa3b, v75
	v_exp_f32_e32 v76, v76
	v_exp_f32_e32 v77, v77
	v_exp_f32_e32 v78, v78
	v_exp_f32_e32 v79, v79
	v_exp_f32_e32 v72, v72
	v_exp_f32_e32 v73, v73
	v_exp_f32_e32 v74, v74
	v_exp_f32_e32 v75, v75
	v_add_f32_e32 v76, 1.0, v76
	v_add_f32_e32 v77, 1.0, v77
	v_add_f32_e32 v78, 1.0, v78
	v_add_f32_e32 v79, 1.0, v79
	v_add_f32_e32 v72, 1.0, v72
	v_add_f32_e32 v73, 1.0, v73
	v_add_f32_e32 v74, 1.0, v74
	v_add_f32_e32 v75, 1.0, v75
	v_rcp_f32_e32 v76, v76
	v_rcp_f32_e32 v77, v77
	v_rcp_f32_e32 v78, v78
	v_rcp_f32_e32 v79, v79
	v_rcp_f32_e32 v72, v72
	v_rcp_f32_e32 v73, v73
	v_rcp_f32_e32 v74, v74
	v_rcp_f32_e32 v75, v75
	v_mul_f32_e32 v68, 0xbfb8aa3b, v68
	v_mul_f32_e32 v69, 0xbfb8aa3b, v69
	v_mul_f32_e32 v70, 0xbfb8aa3b, v70
	v_mul_f32_e32 v71, 0xbfb8aa3b, v71
	v_mul_f32_e32 v64, 0xbfb8aa3b, v64
	v_mul_f32_e32 v65, 0xbfb8aa3b, v65
	v_mul_f32_e32 v66, 0xbfb8aa3b, v66
	v_mul_f32_e32 v67, 0xbfb8aa3b, v67
	v_exp_f32_e32 v68, v68
	v_exp_f32_e32 v69, v69
	v_exp_f32_e32 v70, v70
	v_exp_f32_e32 v71, v71
	v_exp_f32_e32 v64, v64
	v_exp_f32_e32 v65, v65
	v_exp_f32_e32 v66, v66
	v_exp_f32_e32 v67, v67
	v_add_f32_e32 v68, 1.0, v68
	v_add_f32_e32 v69, 1.0, v69
	v_add_f32_e32 v70, 1.0, v70
	v_add_f32_e32 v71, 1.0, v71
	v_add_f32_e32 v64, 1.0, v64
	v_add_f32_e32 v65, 1.0, v65
	v_add_f32_e32 v66, 1.0, v66
	v_add_f32_e32 v67, 1.0, v67
	v_rcp_f32_e32 v68, v68
	v_rcp_f32_e32 v69, v69
	v_rcp_f32_e32 v70, v70
	v_rcp_f32_e32 v71, v71
	v_rcp_f32_e32 v64, v64
	v_rcp_f32_e32 v65, v65
	v_rcp_f32_e32 v66, v66
	v_rcp_f32_e32 v67, v67
	s_waitcnt vmcnt(14)
	v_cndmask_b32_e64 v224, 0, v224, s[10:11]
	v_cndmask_b32_e64 v225, 0, v225, s[10:11]
	v_cndmask_b32_e64 v226, 0, v226, s[10:11]
	v_cndmask_b32_e64 v227, 0, v227, s[10:11]
	v_lshlrev_b32_e32 v228, 16, v128
	v_lshlrev_b32_e32 v229, 16, v129
	v_lshlrev_b32_e32 v230, 16, v130
	v_lshlrev_b32_e32 v231, 16, v131
	v_lshlrev_b32_e32 v232, 16, v224
	v_lshlrev_b32_e32 v233, 16, v225
	v_lshlrev_b32_e32 v234, 16, v226
	v_lshlrev_b32_e32 v235, 16, v227
	v_and_b32_e32 v128, 0xffff0000, v128
	v_and_b32_e32 v129, 0xffff0000, v129
	v_and_b32_e32 v130, 0xffff0000, v130
	v_and_b32_e32 v131, 0xffff0000, v131
	v_and_b32_e32 v224, 0xffff0000, v224
	v_and_b32_e32 v225, 0xffff0000, v225
	v_and_b32_e32 v226, 0xffff0000, v226
	v_and_b32_e32 v227, 0xffff0000, v227
	v_fmac_f32_e32 v232, v124, v228
	v_fmac_f32_e32 v233, v126, v229
	v_fmac_f32_e32 v234, v120, v230
	v_fmac_f32_e32 v235, v122, v231
	v_fmac_f32_e32 v224, v125, v128
	v_fmac_f32_e32 v225, v127, v129
	v_fmac_f32_e32 v226, v121, v130
	v_fmac_f32_e32 v227, v123, v131
	v_cvt_pk_bf16_f32 v128, v232, v224
	v_cvt_pk_bf16_f32 v129, v233, v225
	v_cvt_pk_bf16_f32 v130, v234, v226
	v_cvt_pk_bf16_f32 v131, v235, v227
	v_add_u32_e32 v236, 0x10000, v190
	global_load_dwordx4 v[124:127], v236, s[74:75]
	global_load_dwordx4 v[120:123], v236, s[78:79]
	s_waitcnt vmcnt(14)
	v_cndmask_b32_e64 v184, 0, v184, s[10:11]
	v_cndmask_b32_e64 v185, 0, v185, s[10:11]
	v_cndmask_b32_e64 v186, 0, v186, s[10:11]
	v_cndmask_b32_e64 v187, 0, v187, s[10:11]
	v_lshlrev_b32_e32 v228, 16, v140
	v_lshlrev_b32_e32 v229, 16, v141
	v_lshlrev_b32_e32 v230, 16, v142
	v_lshlrev_b32_e32 v231, 16, v143
	v_lshlrev_b32_e32 v232, 16, v184
	v_lshlrev_b32_e32 v233, 16, v185
	v_lshlrev_b32_e32 v234, 16, v186
	v_lshlrev_b32_e32 v235, 16, v187
	v_and_b32_e32 v140, 0xffff0000, v140
	v_and_b32_e32 v141, 0xffff0000, v141
	v_and_b32_e32 v142, 0xffff0000, v142
	v_and_b32_e32 v143, 0xffff0000, v143
	v_and_b32_e32 v184, 0xffff0000, v184
	v_and_b32_e32 v185, 0xffff0000, v185
	v_and_b32_e32 v186, 0xffff0000, v186
	v_and_b32_e32 v187, 0xffff0000, v187
	v_fmac_f32_e32 v232, v116, v228
	v_fmac_f32_e32 v233, v118, v229
	v_fmac_f32_e32 v234, v112, v230
	v_fmac_f32_e32 v235, v114, v231
	v_fmac_f32_e32 v184, v117, v140
	v_fmac_f32_e32 v185, v119, v141
	v_fmac_f32_e32 v186, v113, v142
	v_fmac_f32_e32 v187, v115, v143
	v_cvt_pk_bf16_f32 v140, v232, v184
	v_cvt_pk_bf16_f32 v141, v233, v185
	v_cvt_pk_bf16_f32 v142, v234, v186
	v_cvt_pk_bf16_f32 v143, v235, v187
	v_add_u32_e32 v223, 0x12000, v190
	global_load_dwordx4 v[116:119], v223, s[74:75]
	global_load_dwordx4 v[112:115], v223, s[78:79]
	s_waitcnt vmcnt(14)
; __device__ __forceinline__ float sigmoidf_(float x) { return __builtin_amdgcn_rcpf(1.f + fexp(-x)); }
; __device__ __forceinline__ unsigned pack2(float a, float b) { unsigned r; asm volatile("v_cvt_pk_bf16_f32 %0, %1, %2" : "=v"(r) : "v"(a), "v"(b)); return r; }
; __device__ __forceinline__ void gemm_epi(const Params& p, int l, int kind, const GUnit& u, f32x4 (&acc)[2][2][4][2]) {
;     ...
; #pragma unroll
;         for (int bj = 0; bj < 2; ++bj)
; #pragma unroll
;           for (int m = 0; m < 4; ++m) {
;             const int q = (ai * 2 + bj) * 4 + m;
;             const uint4 yy = g[bj][m]; uint4 mo = mm[bj][m];
;             mo.x = (br > 0) ? mo.x : 0u; mo.y = (br > 0) ? mo.y : 0u; mo.z = (br > 0) ? mo.z : 0u; mo.w = (br > 0) ? mo.w : 0u;
;             f32x4 s0 = acc[ai][bj][m][0], s1 = acc[ai][bj][m][1];
; #pragma unroll
;             for (int j = 0; j < 4; ++j) { s0[j] = sigmoidf_(s0[j]); s1[j] = sigmoidf_(s1[j]); }
;             uint4 o;
;             o.x = pack2(__uint_as_float(yy.x << 16) * s0[0] + __uint_as_float(mo.x << 16), __uint_as_float(yy.x & 0xffff0000u) * s0[1] + __uint_as_float(mo.x & 0xffff0000u));
;             o.y = pack2(__uint_as_float(yy.y << 16) * s0[2] + __uint_as_float(mo.y << 16), __uint_as_float(yy.y & 0xffff0000u) * s0[3] + __uint_as_float(mo.y & 0xffff0000u));
;             o.z = pack2(__uint_as_float(yy.z << 16) * s1[0] + __uint_as_float(mo.z << 16), __uint_as_float(yy.z & 0xffff0000u) * s1[1] + __uint_as_float(mo.z & 0xffff0000u));
;             o.w = pack2(__uint_as_float(yy.w << 16) * s1[2] + __uint_as_float(mo.w << 16), __uint_as_float(yy.w & 0xffff0000u) * s1[3] + __uint_as_float(mo.w & 0xffff0000u));
;             if (br < 2) *reinterpret_cast<uint4*>((mbu + q * 8192) + lo16) = o;
;             mm[bj][m] = o;
;           }
	v_cndmask_b32_e64 v180, 0, v180, s[10:11]
	v_cndmask_b32_e64 v181, 0, v181, s[10:11]
	v_cndmask_b32_e64 v182, 0, v182, s[10:11]
	v_cndmask_b32_e64 v183, 0, v183, s[10:11]
	v_lshlrev_b32_e32 v228, 16, v156
	v_lshlrev_b32_e32 v229, 16, v157
	v_lshlrev_b32_e32 v230, 16, v158
	v_lshlrev_b32_e32 v231, 16, v159
	v_lshlrev_b32_e32 v232, 16, v180
	v_lshlrev_b32_e32 v233, 16, v181
	v_lshlrev_b32_e32 v234, 16, v182
	v_lshlrev_b32_e32 v235, 16, v183
	v_and_b32_e32 v156, 0xffff0000, v156
	v_and_b32_e32 v157, 0xffff0000, v157
	v_and_b32_e32 v158, 0xffff0000, v158
	v_and_b32_e32 v159, 0xffff0000, v159
	v_and_b32_e32 v180, 0xffff0000, v180
	v_and_b32_e32 v181, 0xffff0000, v181
	v_and_b32_e32 v182, 0xffff0000, v182
	v_and_b32_e32 v183, 0xffff0000, v183
	v_fmac_f32_e32 v232, v108, v228
	v_fmac_f32_e32 v233, v110, v229
	v_fmac_f32_e32 v234, v104, v230
	v_fmac_f32_e32 v235, v106, v231
	v_fmac_f32_e32 v180, v109, v156
	v_fmac_f32_e32 v181, v111, v157
	v_fmac_f32_e32 v182, v105, v158
	v_fmac_f32_e32 v183, v107, v159
	v_cvt_pk_bf16_f32 v156, v232, v180
	v_cvt_pk_bf16_f32 v157, v233, v181
	v_cvt_pk_bf16_f32 v158, v234, v182
	v_cvt_pk_bf16_f32 v159, v235, v183
	v_add_u32_e32 v236, 0x14000, v190
	global_load_dwordx4 v[108:111], v236, s[74:75]
	global_load_dwordx4 v[104:107], v236, s[78:79]
	s_waitcnt vmcnt(14)
	v_cndmask_b32_e64 v176, 0, v176, s[10:11]
	v_cndmask_b32_e64 v177, 0, v177, s[10:11]
	v_cndmask_b32_e64 v178, 0, v178, s[10:11]
	v_cndmask_b32_e64 v179, 0, v179, s[10:11]
	v_lshlrev_b32_e32 v228, 16, v168
	v_lshlrev_b32_e32 v229, 16, v169
	v_lshlrev_b32_e32 v230, 16, v170
	v_lshlrev_b32_e32 v231, 16, v171
	v_lshlrev_b32_e32 v232, 16, v176
	v_lshlrev_b32_e32 v233, 16, v177
	v_lshlrev_b32_e32 v234, 16, v178
	v_lshlrev_b32_e32 v235, 16, v179
	v_and_b32_e32 v168, 0xffff0000, v168
	v_and_b32_e32 v169, 0xffff0000, v169
	v_and_b32_e32 v170, 0xffff0000, v170
	v_and_b32_e32 v171, 0xffff0000, v171
	v_and_b32_e32 v176, 0xffff0000, v176
	v_and_b32_e32 v177, 0xffff0000, v177
	v_and_b32_e32 v178, 0xffff0000, v178
	v_and_b32_e32 v179, 0xffff0000, v179
	v_fmac_f32_e32 v232, v100, v228
	v_fmac_f32_e32 v233, v102, v229
	v_fmac_f32_e32 v234, v96, v230
	v_fmac_f32_e32 v235, v98, v231
	v_fmac_f32_e32 v176, v101, v168
	v_fmac_f32_e32 v177, v103, v169
	v_fmac_f32_e32 v178, v97, v170
	v_fmac_f32_e32 v179, v99, v171
	v_cvt_pk_bf16_f32 v168, v232, v176
	v_cvt_pk_bf16_f32 v169, v233, v177
	v_cvt_pk_bf16_f32 v170, v234, v178
	v_cvt_pk_bf16_f32 v171, v235, v179
	v_add_u32_e32 v223, 0x16000, v190
	global_load_dwordx4 v[100:103], v223, s[74:75]
	global_load_dwordx4 v[96:99], v223, s[78:79]
	s_waitcnt vmcnt(14)
	v_cndmask_b32_e64 v172, 0, v172, s[10:11]
	v_cndmask_b32_e64 v173, 0, v173, s[10:11]
	v_cndmask_b32_e64 v174, 0, v174, s[10:11]
	v_cndmask_b32_e64 v175, 0, v175, s[10:11]
	v_lshlrev_b32_e32 v228, 16, v164
	v_lshlrev_b32_e32 v229, 16, v165
	v_lshlrev_b32_e32 v230, 16, v166
	v_lshlrev_b32_e32 v231, 16, v167
	v_lshlrev_b32_e32 v232, 16, v172
	v_lshlrev_b32_e32 v233, 16, v173
	v_lshlrev_b32_e32 v234, 16, v174
	v_lshlrev_b32_e32 v235, 16, v175
	v_and_b32_e32 v164, 0xffff0000, v164
	v_and_b32_e32 v165, 0xffff0000, v165
	v_and_b32_e32 v166, 0xffff0000, v166
	v_and_b32_e32 v167, 0xffff0000, v167
	v_and_b32_e32 v172, 0xffff0000, v172
	v_and_b32_e32 v173, 0xffff0000, v173
	v_and_b32_e32 v174, 0xffff0000, v174
	v_and_b32_e32 v175, 0xffff0000, v175
	v_fmac_f32_e32 v232, v92, v228
	v_fmac_f32_e32 v233, v94, v229
	v_fmac_f32_e32 v234, v88, v230
	v_fmac_f32_e32 v235, v90, v231
	v_fmac_f32_e32 v172, v93, v164
	v_fmac_f32_e32 v173, v95, v165
	v_fmac_f32_e32 v174, v89, v166
	v_fmac_f32_e32 v175, v91, v167
	v_cvt_pk_bf16_f32 v164, v232, v172
	v_cvt_pk_bf16_f32 v165, v233, v173
	v_cvt_pk_bf16_f32 v166, v234, v174
	v_cvt_pk_bf16_f32 v167, v235, v175
	v_add_u32_e32 v236, 0x18000, v190
	global_load_dwordx4 v[92:95], v236, s[74:75]
	global_load_dwordx4 v[88:91], v236, s[78:79]
	s_waitcnt vmcnt(14)
; __device__ __forceinline__ float sigmoidf_(float x) { return __builtin_amdgcn_rcpf(1.f + fexp(-x)); }
; __device__ __forceinline__ unsigned pack2(float a, float b) { unsigned r; asm volatile("v_cvt_pk_bf16_f32 %0, %1, %2" : "=v"(r) : "v"(a), "v"(b)); return r; }
; __device__ __forceinline__ void gemm_epi(const Params& p, int l, int kind, const GUnit& u, f32x4 (&acc)[2][2][4][2]) {
;     ...
; #pragma unroll
;         for (int bj = 0; bj < 2; ++bj)
; #pragma unroll
;           for (int m = 0; m < 4; ++m) {
;             const int q = (ai * 2 + bj) * 4 + m;
;             const uint4 yy = g[bj][m]; uint4 mo = mm[bj][m];
;             mo.x = (br > 0) ? mo.x : 0u; mo.y = (br > 0) ? mo.y : 0u; mo.z = (br > 0) ? mo.z : 0u; mo.w = (br > 0) ? mo.w : 0u;
;             f32x4 s0 = acc[ai][bj][m][0], s1 = acc[ai][bj][m][1];
; #pragma unroll
;             for (int j = 0; j < 4; ++j) { s0[j] = sigmoidf_(s0[j]); s1[j] = sigmoidf_(s1[j]); }
;             uint4 o;
;             o.x = pack2(__uint_as_float(yy.x << 16) * s0[0] + __uint_as_float(mo.x << 16), __uint_as_float(yy.x & 0xffff0000u) * s0[1] + __uint_as_float(mo.x & 0xffff0000u));
;             o.y = pack2(__uint_as_float(yy.y << 16) * s0[2] + __uint_as_float(mo.y << 16), __uint_as_float(yy.y & 0xffff0000u) * s0[3] + __uint_as_float(mo.y & 0xffff0000u));
;             o.z = pack2(__uint_as_float(yy.z << 16) * s1[0] + __uint_as_float(mo.z << 16), __uint_as_float(yy.z & 0xffff0000u) * s1[1] + __uint_as_float(mo.z & 0xffff0000u));
;             o.w = pack2(__uint_as_float(yy.w << 16) * s1[2] + __uint_as_float(mo.w << 16), __uint_as_float(yy.w & 0xffff0000u) * s1[3] + __uint_as_float(mo.w & 0xffff0000u));
;             if (br < 2) *reinterpret_cast<uint4*>((mbu + q * 8192) + lo16) = o;
;             mm[bj][m] = o;
;           }
	v_cndmask_b32_e64 v160, 0, v160, s[10:11]
	v_cndmask_b32_e64 v161, 0, v161, s[10:11]
	v_cndmask_b32_e64 v162, 0, v162, s[10:11]
	v_cndmask_b32_e64 v163, 0, v163, s[10:11]
	v_lshlrev_b32_e32 v228, 16, v152
	v_lshlrev_b32_e32 v229, 16, v153
	v_lshlrev_b32_e32 v230, 16, v154
	v_lshlrev_b32_e32 v231, 16, v155
	v_lshlrev_b32_e32 v232, 16, v160
	v_lshlrev_b32_e32 v233, 16, v161
	v_lshlrev_b32_e32 v234, 16, v162
	v_lshlrev_b32_e32 v235, 16, v163
	v_and_b32_e32 v152, 0xffff0000, v152
	v_and_b32_e32 v153, 0xffff0000, v153
	v_and_b32_e32 v154, 0xffff0000, v154
	v_and_b32_e32 v155, 0xffff0000, v155
	v_and_b32_e32 v160, 0xffff0000, v160
	v_and_b32_e32 v161, 0xffff0000, v161
	v_and_b32_e32 v162, 0xffff0000, v162
	v_and_b32_e32 v163, 0xffff0000, v163
	v_fmac_f32_e32 v232, v84, v228
	v_fmac_f32_e32 v233, v86, v229
	v_fmac_f32_e32 v234, v80, v230
	v_fmac_f32_e32 v235, v82, v231
	v_fmac_f32_e32 v160, v85, v152
	v_fmac_f32_e32 v161, v87, v153
	v_fmac_f32_e32 v162, v81, v154
	v_fmac_f32_e32 v163, v83, v155
	v_cvt_pk_bf16_f32 v152, v232, v160
	v_cvt_pk_bf16_f32 v153, v233, v161
	v_cvt_pk_bf16_f32 v154, v234, v162
	v_cvt_pk_bf16_f32 v155, v235, v163
	v_add_u32_e32 v223, 0x1a000, v190
	global_load_dwordx4 v[84:87], v223, s[74:75]
	global_load_dwordx4 v[80:83], v223, s[78:79]
	s_waitcnt vmcnt(14)
	v_cndmask_b32_e64 v148, 0, v148, s[10:11]
	v_cndmask_b32_e64 v149, 0, v149, s[10:11]
	v_cndmask_b32_e64 v150, 0, v150, s[10:11]
	v_cndmask_b32_e64 v151, 0, v151, s[10:11]
	v_lshlrev_b32_e32 v228, 16, v144
	v_lshlrev_b32_e32 v229, 16, v145
	v_lshlrev_b32_e32 v230, 16, v146
	v_lshlrev_b32_e32 v231, 16, v147
	v_lshlrev_b32_e32 v232, 16, v148
	v_lshlrev_b32_e32 v233, 16, v149
	v_lshlrev_b32_e32 v234, 16, v150
	v_lshlrev_b32_e32 v235, 16, v151
	v_and_b32_e32 v144, 0xffff0000, v144
	v_and_b32_e32 v145, 0xffff0000, v145
	v_and_b32_e32 v146, 0xffff0000, v146
	v_and_b32_e32 v147, 0xffff0000, v147
	v_and_b32_e32 v148, 0xffff0000, v148
	v_and_b32_e32 v149, 0xffff0000, v149
	v_and_b32_e32 v150, 0xffff0000, v150
	v_and_b32_e32 v151, 0xffff0000, v151
	v_fmac_f32_e32 v232, v76, v228
	v_fmac_f32_e32 v233, v78, v229
	v_fmac_f32_e32 v234, v72, v230
	v_fmac_f32_e32 v235, v74, v231
	v_fmac_f32_e32 v148, v77, v144
	v_fmac_f32_e32 v149, v79, v145
	v_fmac_f32_e32 v150, v73, v146
	v_fmac_f32_e32 v151, v75, v147
	v_cvt_pk_bf16_f32 v144, v232, v148
	v_cvt_pk_bf16_f32 v145, v233, v149
	v_cvt_pk_bf16_f32 v146, v234, v150
	v_cvt_pk_bf16_f32 v147, v235, v151
	v_add_u32_e32 v236, 0x1c000, v190
	global_load_dwordx4 v[76:79], v236, s[74:75]
	global_load_dwordx4 v[72:75], v236, s[78:79]
	s_waitcnt vmcnt(14)
	v_cndmask_b32_e64 v136, 0, v136, s[10:11]
	v_cndmask_b32_e64 v137, 0, v137, s[10:11]
	v_cndmask_b32_e64 v138, 0, v138, s[10:11]
	v_cndmask_b32_e64 v139, 0, v139, s[10:11]
	v_lshlrev_b32_e32 v228, 16, v132
	v_lshlrev_b32_e32 v229, 16, v133
	v_lshlrev_b32_e32 v230, 16, v134
	v_lshlrev_b32_e32 v231, 16, v135
	v_lshlrev_b32_e32 v232, 16, v136
	v_lshlrev_b32_e32 v233, 16, v137
	v_lshlrev_b32_e32 v234, 16, v138
	v_lshlrev_b32_e32 v235, 16, v139
	v_and_b32_e32 v132, 0xffff0000, v132
	v_and_b32_e32 v133, 0xffff0000, v133
	v_and_b32_e32 v134, 0xffff0000, v134
	v_and_b32_e32 v135, 0xffff0000, v135
	v_and_b32_e32 v136, 0xffff0000, v136
	v_and_b32_e32 v137, 0xffff0000, v137
	v_and_b32_e32 v138, 0xffff0000, v138
	v_and_b32_e32 v139, 0xffff0000, v139
	v_fmac_f32_e32 v232, v68, v228
	v_fmac_f32_e32 v233, v70, v229
	v_fmac_f32_e32 v234, v64, v230
	v_fmac_f32_e32 v235, v66, v231
	v_fmac_f32_e32 v136, v69, v132
	v_fmac_f32_e32 v137, v71, v133
	v_fmac_f32_e32 v138, v65, v134
	v_fmac_f32_e32 v139, v67, v135
	v_cvt_pk_bf16_f32 v132, v232, v136
	v_cvt_pk_bf16_f32 v133, v233, v137
	v_cvt_pk_bf16_f32 v134, v234, v138
	v_cvt_pk_bf16_f32 v135, v235, v139
	v_add_u32_e32 v223, 0x1e000, v190
	global_load_dwordx4 v[68:71], v223, s[74:75]
	global_load_dwordx4 v[64:67], v223, s[78:79]
	s_cmp_lt_i32 s2, 2
	s_cbranch_scc0 .Lg3_m0
	global_store_dwordx4 v190, v[128:131], s[78:79]
	v_add_u32_e32 v223, 0x2000, v190
	global_store_dwordx4 v223, v[140:143], s[78:79]
	v_add_u32_e32 v236, 0x4000, v190
	global_store_dwordx4 v236, v[156:159], s[78:79]
	v_add_u32_e32 v223, 0x6000, v190
	global_store_dwordx4 v223, v[168:171], s[78:79]
	v_add_u32_e32 v236, 0x8000, v190
	global_store_dwordx4 v236, v[164:167], s[78:79]
	v_add_u32_e32 v223, 0xa000, v190
	global_store_dwordx4 v223, v[152:155], s[78:79]
	v_add_u32_e32 v236, 0xc000, v190
	global_store_dwordx4 v236, v[144:147], s[78:79]
	v_add_u32_e32 v223, 0xe000, v190
	global_store_dwordx4 v223, v[132:135], s[78:79]
	s_branch .Lg3_s0done

; #define G_STAGE(bufoff, gbase, v0, v1) do { \
;     __builtin_amdgcn_global_load_lds((const unsigned*)((const char*)(gbase) + (v0)), (LAS unsigned*)(lds + (bufoff) + ldsw), 16, 0, 0); \
;     __builtin_amdgcn_global_load_lds((const unsigned*)((const char*)(gbase) + (v1)), (LAS unsigned*)(lds + (bufoff) + ldsw + 8192), 16, 0, 0); } while (0)
; #define G_LDA(dst, b, h) do { _Pragma("unroll") for (int m = 0; m < 4; ++m) _Pragma("unroll") for (int k = 0; k < 2; ++k) dst[m][k] = *(const LAS bf16x8*)(lds + G_SA(b, h) + aoff + m * 2048 + k * 1024); } while (0)
; #define G_LDB(dst, b, h) do { _Pragma("unroll") for (int n = 0; n < 2; ++n) _Pragma("unroll") for (int k = 0; k < 2; ++k) dst[n][k] = *(const LAS bf16x8*)(lds + G_SB(b, h) + boff + n * 2048 + k * 1024); } while (0)
; #define G_MMA(ai, bj, At, Bt) do { __builtin_amdgcn_s_setprio(1); _Pragma("unroll") for (int m = 0; m < 4; ++m) _Pragma("unroll") for (int n = 0; n < 2; ++n) _Pragma("unroll") for (int k = 0; k < 2; ++k) \
;     acc[ai][bj][m][n] = __builtin_amdgcn_mfma_f32_16x16x32_bf16(Bt[n][k], At[m][k], acc[ai][bj][m][n], 0, 0, 0); __builtin_amdgcn_s_setprio(0); } while (0)
; #define G_WAIT_L(n) asm volatile("s_waitcnt lgkmcnt(" #n ")" ::: "memory")
; #define G_BAR __builtin_amdgcn_s_barrier()
; #define G_SCHED __builtin_amdgcn_sched_barrier(0)
; __device__ __forceinline__ void gemm_run(const Params& p, int l, int kind, int single) {
;     ...
;     for (int t = 0; t < nt; t += 2) {
;       const bool last = (t == nt - 2);
;       const char* a1 = cA + (size_t)(t + 1) * kstep;
;       const char* a2 = last ? nA : cA + (size_t)(t + 2) * kstep; const char* b2 = last ? nB : cB + (size_t)(t + 2) * kstep;
;       const char* a3 = a2 + kstep; const char* b3 = b2 + kstep;
;       const unsigned w0 = last ? vn0 : vc0, w1 = last ? vn1 : vc1; const size_t h2 = last ? hn : hc;
;       G_LDB(B0, 0, 0); G_SCHED; G_LDA(At, 0, 0); G_STAGE(G_SA(1, 1), a1 + hc, vc0, vc1);
;       G_WAIT_L(8); G_BAR; G_WAIT_L(0); G_MMA(0, 0, At, B0); G_BAR; G_SCHED;
;       G_LDB(B1, 0, 1); G_STAGE(G_SB(0, 0), b2, w0, w1);
;       G_BAR; G_WAIT_L(0); G_MMA(0, 1, At, B1); G_BAR;
;       G_LDA(At, 0, 1); G_STAGE(G_SA(0, 0), a2, w0, w1);
;       G_BAR; G_WAIT_L(0); G_MMA(1, 0, At, B0); G_BAR; G_SCHED;
.LBB0_1012:
	s_add_u32 s14, s12, 0xfffc0080
	s_addc_u32 s15, s13, -1
	s_cmp_eq_u32 s27, 12
	s_cselect_b32 s17, s9, s15
	s_cselect_b32 s16, s8, s14
	s_cselect_b32 s15, s11, s5
	s_cselect_b32 s14, s10, s1
	s_add_i32 s28, s89, 0x100
	v_add_u32_e32 v138, s28, v140
	ds_read_b128 v[134:137], v138
	ds_read_b128 v[142:145], v138 offset:1024
	ds_read_b128 v[146:149], v138 offset:2048
	ds_read_b128 v[150:153], v138 offset:3072
	v_lshl_add_u64 v[138:139], s[12:13], 0, v[130:131]
	s_add_i32 m0, s18, 0xc000
	ds_read_b128 v[154:157], v141
	ds_read_b128 v[158:161], v141 offset:1024
	ds_read_b128 v[162:165], v141 offset:2048
	ds_read_b128 v[166:169], v141 offset:3072
	ds_read_b128 v[170:173], v141 offset:4096
	ds_read_b128 v[174:177], v141 offset:5120
	ds_read_b128 v[178:181], v141 offset:6144
	ds_read_b128 v[182:185], v141 offset:7168
	global_load_lds_dwordx4 v[138:139], off
	v_lshl_add_u64 v[138:139], s[12:13], 0, v[132:133]
	s_add_i32 m0, s18, 0xe000
	s_nop 0
	global_load_lds_dwordx4 v[138:139], off
	s_waitcnt lgkmcnt(8)
	s_barrier
	s_waitcnt lgkmcnt(0)
	s_setprio 1
	v_mfma_f32_16x16x32_bf16 v[124:127], v[134:137], v[154:157], v[124:127]
	v_mfma_f32_16x16x32_bf16 v[120:123], v[146:149], v[154:157], v[120:123]
	v_mfma_f32_16x16x32_bf16 v[116:119], v[134:137], v[162:165], v[116:119]
	v_mfma_f32_16x16x32_bf16 v[112:115], v[146:149], v[162:165], v[112:115]
	v_mfma_f32_16x16x32_bf16 v[108:111], v[134:137], v[170:173], v[108:111]
	v_mfma_f32_16x16x32_bf16 v[100:103], v[146:149], v[170:173], v[100:103]
	v_mfma_f32_16x16x32_bf16 v[84:87], v[134:137], v[178:181], v[84:87]
	v_mfma_f32_16x16x32_bf16 v[72:75], v[146:149], v[178:181], v[72:75]
	v_mfma_f32_16x16x32_bf16 v[124:127], v[142:145], v[158:161], v[124:127]
	v_mfma_f32_16x16x32_bf16 v[120:123], v[150:153], v[158:161], v[120:123]
	v_mfma_f32_16x16x32_bf16 v[116:119], v[142:145], v[166:169], v[116:119]
	v_mfma_f32_16x16x32_bf16 v[112:115], v[150:153], v[166:169], v[112:115]
	v_mfma_f32_16x16x32_bf16 v[108:111], v[142:145], v[174:177], v[108:111]
	v_mfma_f32_16x16x32_bf16 v[100:103], v[150:153], v[174:177], v[100:103]
	v_mfma_f32_16x16x32_bf16 v[84:87], v[142:145], v[182:185], v[84:87]
	v_mfma_f32_16x16x32_bf16 v[72:75], v[150:153], v[182:185], v[72:75]
	s_setprio 0
	s_barrier
	s_add_i32 s30, s90, 0x100
	v_add_u32_e32 v138, s30, v140
	s_add_i32 s28, s28, s3
	ds_read_b128 v[200:203], v138
	ds_read_b128 v[204:207], v138 offset:1024
	ds_read_b128 v[218:221], v138 offset:2048
	ds_read_b128 v[222:225], v138 offset:3072
	v_lshl_add_u64 v[138:139], s[14:15], 0, v[190:191]
	s_mov_b32 m0, s28
	v_lshl_add_u64 v[186:187], s[14:15], 0, v[128:129]
	global_load_lds_dwordx4 v[138:139], off
	s_add_i32 m0, s28, 0x2000
	s_nop 0
	global_load_lds_dwordx4 v[186:187], off
	s_barrier
	s_waitcnt lgkmcnt(0)
	s_setprio 1
	v_mfma_f32_16x16x32_bf16 v[104:107], v[200:203], v[154:157], v[104:107]
	v_mfma_f32_16x16x32_bf16 v[96:99], v[218:221], v[154:157], v[96:99]
	v_mfma_f32_16x16x32_bf16 v[92:95], v[200:203], v[162:165], v[92:95]
	v_mfma_f32_16x16x32_bf16 v[88:91], v[218:221], v[162:165], v[88:91]
	v_mfma_f32_16x16x32_bf16 v[80:83], v[200:203], v[170:173], v[80:83]
	v_mfma_f32_16x16x32_bf16 v[76:79], v[218:221], v[170:173], v[76:79]
	v_mfma_f32_16x16x32_bf16 v[68:71], v[200:203], v[178:181], v[68:71]
	v_mfma_f32_16x16x32_bf16 v[64:67], v[218:221], v[178:181], v[64:67]
	v_mfma_f32_16x16x32_bf16 v[104:107], v[204:207], v[158:161], v[104:107]
	v_mfma_f32_16x16x32_bf16 v[96:99], v[222:225], v[158:161], v[96:99]
	v_mfma_f32_16x16x32_bf16 v[92:95], v[204:207], v[166:169], v[92:95]
	v_mfma_f32_16x16x32_bf16 v[88:91], v[222:225], v[166:169], v[88:91]
	v_mfma_f32_16x16x32_bf16 v[80:83], v[204:207], v[174:177], v[80:83]
	v_mfma_f32_16x16x32_bf16 v[76:79], v[222:225], v[174:177], v[76:79]
	v_mfma_f32_16x16x32_bf16 v[68:71], v[204:207], v[182:185], v[68:71]
	v_mfma_f32_16x16x32_bf16 v[64:67], v[222:225], v[182:185], v[64:67]
	s_setprio 0
	s_mov_b32 m0, s18
	v_lshl_add_u64 v[226:227], s[16:17], 0, v[190:191]
	s_barrier
	ds_read_b128 v[154:157], v141 offset:16384
	ds_read_b128 v[158:161], v141 offset:17408
	ds_read_b128 v[162:165], v141 offset:18432
	ds_read_b128 v[166:169], v141 offset:19456
	ds_read_b128 v[170:173], v141 offset:20480
	ds_read_b128 v[174:177], v141 offset:21504
	ds_read_b128 v[178:181], v141 offset:22528
	ds_read_b128 v[182:185], v141 offset:23552
	global_load_lds_dwordx4 v[226:227], off
	v_lshl_add_u64 v[228:229], s[16:17], 0, v[128:129]
	s_mov_b32 m0, s19
	s_nop 0
	global_load_lds_dwordx4 v[228:229], off
	s_barrier
	s_waitcnt lgkmcnt(0)
	s_setprio 1
	v_mfma_f32_16x16x32_bf16 v[60:63], v[134:137], v[154:157], v[60:63]
	v_mfma_f32_16x16x32_bf16 v[56:59], v[146:149], v[154:157], v[56:59]
	v_mfma_f32_16x16x32_bf16 v[52:55], v[134:137], v[162:165], v[52:55]
	v_mfma_f32_16x16x32_bf16 v[48:51], v[146:149], v[162:165], v[48:51]
	v_mfma_f32_16x16x32_bf16 v[44:47], v[134:137], v[170:173], v[44:47]
	v_mfma_f32_16x16x32_bf16 v[36:39], v[146:149], v[170:173], v[36:39]
	v_mfma_f32_16x16x32_bf16 v[28:31], v[134:137], v[178:181], v[28:31]
	v_mfma_f32_16x16x32_bf16 v[16:19], v[146:149], v[178:181], v[16:19]
	v_mfma_f32_16x16x32_bf16 v[60:63], v[142:145], v[158:161], v[60:63]
	v_mfma_f32_16x16x32_bf16 v[56:59], v[150:153], v[158:161], v[56:59]
	v_mfma_f32_16x16x32_bf16 v[52:55], v[142:145], v[166:169], v[52:55]
	v_mfma_f32_16x16x32_bf16 v[48:51], v[150:153], v[166:169], v[48:51]
	v_mfma_f32_16x16x32_bf16 v[44:47], v[142:145], v[174:177], v[44:47]
	v_mfma_f32_16x16x32_bf16 v[36:39], v[150:153], v[174:177], v[36:39]
	v_mfma_f32_16x16x32_bf16 v[28:31], v[142:145], v[182:185], v[28:31]
	v_mfma_f32_16x16x32_bf16 v[16:19], v[150:153], v[182:185], v[16:19]
	s_setprio 0
	s_barrier
; #define G_STAGE(bufoff, gbase, v0, v1) do { \
;     __builtin_amdgcn_global_load_lds((const unsigned*)((const char*)(gbase) + (v0)), (LAS unsigned*)(lds + (bufoff) + ldsw), 16, 0, 0); \
;     __builtin_amdgcn_global_load_lds((const unsigned*)((const char*)(gbase) + (v1)), (LAS unsigned*)(lds + (bufoff) + ldsw + 8192), 16, 0, 0); } while (0)
; #define G_LDA(dst, b, h) do { _Pragma("unroll") for (int m = 0; m < 4; ++m) _Pragma("unroll") for (int k = 0; k < 2; ++k) dst[m][k] = *(const LAS bf16x8*)(lds + G_SA(b, h) + aoff + m * 2048 + k * 1024); } while (0)
; #define G_LDB(dst, b, h) do { _Pragma("unroll") for (int n = 0; n < 2; ++n) _Pragma("unroll") for (int k = 0; k < 2; ++k) dst[n][k] = *(const LAS bf16x8*)(lds + G_SB(b, h) + boff + n * 2048 + k * 1024); } while (0)
; #define G_MMA(ai, bj, At, Bt) do { __builtin_amdgcn_s_setprio(1); _Pragma("unroll") for (int m = 0; m < 4; ++m) _Pragma("unroll") for (int n = 0; n < 2; ++n) _Pragma("unroll") for (int k = 0; k < 2; ++k) \
;     acc[ai][bj][m][n] = __builtin_amdgcn_mfma_f32_16x16x32_bf16(Bt[n][k], At[m][k], acc[ai][bj][m][n], 0, 0, 0); __builtin_amdgcn_s_setprio(0); } while (0)
; #define G_WAIT_V(n) asm volatile("s_waitcnt vmcnt(" #n ")" ::: "memory")
; #define G_WAIT_L(n) asm volatile("s_waitcnt lgkmcnt(" #n ")" ::: "memory")
; #define G_BAR __builtin_amdgcn_s_barrier()
; #define G_SCHED __builtin_amdgcn_sched_barrier(0)
; __device__ __forceinline__ void gemm_run(const Params& p, int l, int kind, int single) {
;     ...
;       G_STAGE(G_SB(0, 1), b2 + h2, w0, w1);
;       G_WAIT_V(6); G_BAR; G_MMA(1, 1, At, B1); G_BAR;
;       G_LDB(B0, 1, 0); G_SCHED; G_LDA(At, 1, 0); G_STAGE(G_SA(0, 1), a2 + h2, w0, w1);
;       G_WAIT_L(8); G_BAR; G_WAIT_L(0); G_MMA(0, 0, At, B0); G_BAR; G_SCHED;
;       G_LDB(B1, 1, 1); G_STAGE(G_SB(1, 0), b3, w0, w1);
	s_add_u32 s28, s14, 0x40000
	s_addc_u32 s29, s15, 0
	s_add_i32 s30, s30, s3
	v_lshl_add_u64 v[134:135], s[28:29], 0, v[190:191]
	s_mov_b32 m0, s30
	s_nop 0
	global_load_lds_dwordx4 v[134:135], off
	v_lshl_add_u64 v[134:135], s[28:29], 0, v[128:129]
	s_add_i32 m0, s30, 0x2000
	s_nop 0
	global_load_lds_dwordx4 v[134:135], off
	s_waitcnt vmcnt(6)
	s_barrier
	s_setprio 1
	v_mfma_f32_16x16x32_bf16 v[40:43], v[200:203], v[154:157], v[40:43]
	v_mfma_f32_16x16x32_bf16 v[32:35], v[218:221], v[154:157], v[32:35]
	v_mfma_f32_16x16x32_bf16 v[24:27], v[200:203], v[162:165], v[24:27]
	v_mfma_f32_16x16x32_bf16 v[20:23], v[218:221], v[162:165], v[20:23]
	v_mfma_f32_16x16x32_bf16 v[12:15], v[200:203], v[170:173], v[12:15]
	v_mfma_f32_16x16x32_bf16 v[8:11], v[218:221], v[170:173], v[8:11]
	v_mfma_f32_16x16x32_bf16 v[4:7], v[200:203], v[178:181], v[4:7]
	v_mfma_f32_16x16x32_bf16 v[0:3], v[218:221], v[178:181], v[0:3]
	v_mfma_f32_16x16x32_bf16 v[40:43], v[204:207], v[158:161], v[40:43]
	v_mfma_f32_16x16x32_bf16 v[32:35], v[222:225], v[158:161], v[32:35]
	v_mfma_f32_16x16x32_bf16 v[24:27], v[204:207], v[166:169], v[24:27]
	v_mfma_f32_16x16x32_bf16 v[20:23], v[222:225], v[166:169], v[20:23]
	v_mfma_f32_16x16x32_bf16 v[12:15], v[204:207], v[174:177], v[12:15]
	v_mfma_f32_16x16x32_bf16 v[8:11], v[222:225], v[174:177], v[8:11]
	v_mfma_f32_16x16x32_bf16 v[4:7], v[204:207], v[182:185], v[4:7]
	v_mfma_f32_16x16x32_bf16 v[0:3], v[222:225], v[182:185], v[0:3]
	s_setprio 0
	s_add_i32 s28, s91, 0x100
	v_add_u32_e32 v150, s28, v140
	s_barrier
	ds_read_b128 v[134:137], v150
	ds_read_b128 v[142:145], v150 offset:1024
	ds_read_b128 v[146:149], v150 offset:2048
	ds_read_b128 v[150:153], v150 offset:3072
	s_add_u32 s16, s16, 0x40000
	s_addc_u32 s17, s17, 0
	s_mov_b32 m0, s20
	v_lshl_add_u64 v[200:201], s[16:17], 0, v[190:191]
	ds_read_b128 v[154:157], v141 offset:32768
	ds_read_b128 v[158:161], v141 offset:33792
	ds_read_b128 v[162:165], v141 offset:34816
	ds_read_b128 v[166:169], v141 offset:35840
	ds_read_b128 v[170:173], v141 offset:36864
	ds_read_b128 v[174:177], v141 offset:37888
	ds_read_b128 v[178:181], v141 offset:38912
	ds_read_b128 v[182:185], v141 offset:39936
	global_load_lds_dwordx4 v[200:201], off
	v_lshl_add_u64 v[200:201], s[16:17], 0, v[128:129]
	s_mov_b32 m0, s21
	s_nop 0
	global_load_lds_dwordx4 v[200:201], off
	s_waitcnt lgkmcnt(8)
	s_barrier
	s_waitcnt lgkmcnt(0)
	s_setprio 1
	v_mfma_f32_16x16x32_bf16 v[124:127], v[134:137], v[154:157], v[124:127]
	v_mfma_f32_16x16x32_bf16 v[120:123], v[146:149], v[154:157], v[120:123]
	v_mfma_f32_16x16x32_bf16 v[116:119], v[134:137], v[162:165], v[116:119]
	v_mfma_f32_16x16x32_bf16 v[112:115], v[146:149], v[162:165], v[112:115]
	v_mfma_f32_16x16x32_bf16 v[108:111], v[134:137], v[170:173], v[108:111]
	v_mfma_f32_16x16x32_bf16 v[100:103], v[146:149], v[170:173], v[100:103]
	v_mfma_f32_16x16x32_bf16 v[84:87], v[134:137], v[178:181], v[84:87]
	v_mfma_f32_16x16x32_bf16 v[72:75], v[146:149], v[178:181], v[72:75]
	v_mfma_f32_16x16x32_bf16 v[124:127], v[142:145], v[158:161], v[124:127]
	v_mfma_f32_16x16x32_bf16 v[120:123], v[150:153], v[158:161], v[120:123]
	v_mfma_f32_16x16x32_bf16 v[116:119], v[142:145], v[166:169], v[116:119]
	v_mfma_f32_16x16x32_bf16 v[112:115], v[150:153], v[166:169], v[112:115]
	v_mfma_f32_16x16x32_bf16 v[108:111], v[142:145], v[174:177], v[108:111]
	v_mfma_f32_16x16x32_bf16 v[100:103], v[150:153], v[174:177], v[100:103]
	v_mfma_f32_16x16x32_bf16 v[84:87], v[142:145], v[182:185], v[84:87]
	v_mfma_f32_16x16x32_bf16 v[72:75], v[150:153], v[182:185], v[72:75]
	s_setprio 0
	s_barrier
	s_add_i32 s16, s94, 0x100
	s_add_i32 s17, s28, s3
	v_add_u32_e32 v199, s16, v140
	v_lshl_add_u64 v[138:139], v[138:139], 0, s[96:97]
	s_mov_b32 m0, s17
	ds_read_b128 v[200:203], v199
	ds_read_b128 v[204:207], v199 offset:1024
	ds_read_b128 v[218:221], v199 offset:2048
	ds_read_b128 v[222:225], v199 offset:3072
	global_load_lds_dwordx4 v[138:139], off
	v_lshl_add_u64 v[138:139], v[186:187], 0, s[96:97]
	s_add_i32 m0, s17, 0x2000
	s_nop 0
	global_load_lds_dwordx4 v[138:139], off
	s_barrier
; #define G_STAGE(bufoff, gbase, v0, v1) do { \
;     __builtin_amdgcn_global_load_lds((const unsigned*)((const char*)(gbase) + (v0)), (LAS unsigned*)(lds + (bufoff) + ldsw), 16, 0, 0); \
;     __builtin_amdgcn_global_load_lds((const unsigned*)((const char*)(gbase) + (v1)), (LAS unsigned*)(lds + (bufoff) + ldsw + 8192), 16, 0, 0); } while (0)
; #define G_LDA(dst, b, h) do { _Pragma("unroll") for (int m = 0; m < 4; ++m) _Pragma("unroll") for (int k = 0; k < 2; ++k) dst[m][k] = *(const LAS bf16x8*)(lds + G_SA(b, h) + aoff + m * 2048 + k * 1024); } while (0)
; #define G_LDB(dst, b, h) do { _Pragma("unroll") for (int n = 0; n < 2; ++n) _Pragma("unroll") for (int k = 0; k < 2; ++k) dst[n][k] = *(const LAS bf16x8*)(lds + G_SB(b, h) + boff + n * 2048 + k * 1024); } while (0)
; #define G_MMA(ai, bj, At, Bt) do { __builtin_amdgcn_s_setprio(1); _Pragma("unroll") for (int m = 0; m < 4; ++m) _Pragma("unroll") for (int n = 0; n < 2; ++n) _Pragma("unroll") for (int k = 0; k < 2; ++k) \
;     acc[ai][bj][m][n] = __builtin_amdgcn_mfma_f32_16x16x32_bf16(Bt[n][k], At[m][k], acc[ai][bj][m][n], 0, 0, 0); __builtin_amdgcn_s_setprio(0); } while (0)
; #define G_WAIT_V(n) asm volatile("s_waitcnt vmcnt(" #n ")" ::: "memory")
; #define G_WAIT_L(n) asm volatile("s_waitcnt lgkmcnt(" #n ")" ::: "memory")
; #define G_BAR __builtin_amdgcn_s_barrier()
; #define G_SCHED __builtin_amdgcn_sched_barrier(0)
; __device__ __forceinline__ void gemm_epi(const Params& p, int l, int kind, const GUnit& u, f32x4 (&acc)[2][2][4][2]) {
;     ...
;     const float* xbase = (l == 0) ? (u.pm < 256 ? p.xp : p.xs - (long)NP * 1024) : p.out;
; __device__ __forceinline__ void gemm_run(const Params& p, int l, int kind, int single) {
;     ...
;       G_LDB(B1, 1, 1); G_STAGE(G_SB(1, 0), b3, w0, w1);
;       G_BAR; G_WAIT_L(0); G_MMA(0, 1, At, B1); G_BAR;
;       G_LDA(At, 1, 1); G_STAGE(G_SA(1, 0), a3, w0, w1);
;       G_BAR; G_WAIT_L(0); G_MMA(1, 0, At, B0); G_BAR; G_SCHED;
;       G_STAGE(G_SB(1, 1), b3 + h2, w0, w1);
;       G_WAIT_V(6); G_BAR; G_MMA(1, 1, At, B1); G_BAR;
	s_waitcnt lgkmcnt(0)
	s_setprio 1
	v_mfma_f32_16x16x32_bf16 v[104:107], v[200:203], v[154:157], v[104:107]
	v_mfma_f32_16x16x32_bf16 v[96:99], v[218:221], v[154:157], v[96:99]
	v_mfma_f32_16x16x32_bf16 v[92:95], v[200:203], v[162:165], v[92:95]
	v_mfma_f32_16x16x32_bf16 v[88:91], v[218:221], v[162:165], v[88:91]
	v_mfma_f32_16x16x32_bf16 v[80:83], v[200:203], v[170:173], v[80:83]
	v_mfma_f32_16x16x32_bf16 v[76:79], v[218:221], v[170:173], v[76:79]
	v_mfma_f32_16x16x32_bf16 v[68:71], v[200:203], v[178:181], v[68:71]
	v_mfma_f32_16x16x32_bf16 v[64:67], v[218:221], v[178:181], v[64:67]
	v_mfma_f32_16x16x32_bf16 v[104:107], v[204:207], v[158:161], v[104:107]
	v_mfma_f32_16x16x32_bf16 v[96:99], v[222:225], v[158:161], v[96:99]
	v_mfma_f32_16x16x32_bf16 v[92:95], v[204:207], v[166:169], v[92:95]
	v_mfma_f32_16x16x32_bf16 v[88:91], v[222:225], v[166:169], v[88:91]
	v_mfma_f32_16x16x32_bf16 v[80:83], v[204:207], v[174:177], v[80:83]
	v_mfma_f32_16x16x32_bf16 v[76:79], v[222:225], v[174:177], v[76:79]
	v_mfma_f32_16x16x32_bf16 v[68:71], v[204:207], v[182:185], v[68:71]
	v_mfma_f32_16x16x32_bf16 v[64:67], v[222:225], v[182:185], v[64:67]
	s_setprio 0
	s_mov_b32 m0, s22
	v_lshl_add_u64 v[138:139], v[226:227], 0, s[96:97]
	s_barrier
	ds_read_b128 v[154:157], v141 offset:49152
	ds_read_b128 v[158:161], v141 offset:50176
	ds_read_b128 v[162:165], v141 offset:51200
	ds_read_b128 v[166:169], v141 offset:52224
	ds_read_b128 v[170:173], v141 offset:53248
	ds_read_b128 v[174:177], v141 offset:54272
	ds_read_b128 v[178:181], v141 offset:55296
	ds_read_b128 v[182:185], v141 offset:56320
	global_load_lds_dwordx4 v[138:139], off
	v_lshl_add_u64 v[138:139], v[228:229], 0, s[96:97]
	s_mov_b32 m0, s23
	s_nop 0
	global_load_lds_dwordx4 v[138:139], off
	s_barrier
	s_waitcnt lgkmcnt(0)
	s_setprio 1
	v_mfma_f32_16x16x32_bf16 v[60:63], v[134:137], v[154:157], v[60:63]
	v_mfma_f32_16x16x32_bf16 v[56:59], v[146:149], v[154:157], v[56:59]
	v_mfma_f32_16x16x32_bf16 v[52:55], v[134:137], v[162:165], v[52:55]
	v_mfma_f32_16x16x32_bf16 v[48:51], v[146:149], v[162:165], v[48:51]
	v_mfma_f32_16x16x32_bf16 v[44:47], v[134:137], v[170:173], v[44:47]
	v_mfma_f32_16x16x32_bf16 v[36:39], v[146:149], v[170:173], v[36:39]
	v_mfma_f32_16x16x32_bf16 v[28:31], v[134:137], v[178:181], v[28:31]
	v_mfma_f32_16x16x32_bf16 v[16:19], v[146:149], v[178:181], v[16:19]
	v_mfma_f32_16x16x32_bf16 v[60:63], v[142:145], v[158:161], v[60:63]
	v_mfma_f32_16x16x32_bf16 v[56:59], v[150:153], v[158:161], v[56:59]
	v_mfma_f32_16x16x32_bf16 v[52:55], v[142:145], v[166:169], v[52:55]
	v_mfma_f32_16x16x32_bf16 v[48:51], v[150:153], v[166:169], v[48:51]
	v_mfma_f32_16x16x32_bf16 v[44:47], v[142:145], v[174:177], v[44:47]
	v_mfma_f32_16x16x32_bf16 v[36:39], v[150:153], v[174:177], v[36:39]
	v_mfma_f32_16x16x32_bf16 v[28:31], v[142:145], v[182:185], v[28:31]
	v_mfma_f32_16x16x32_bf16 v[16:19], v[150:153], v[182:185], v[16:19]
	s_setprio 0
	s_barrier
	s_add_u32 s14, s14, 0x40080
	s_addc_u32 s15, s15, 0
	s_add_i32 s16, s16, s3
	v_lshl_add_u64 v[134:135], s[14:15], 0, v[190:191]
	s_mov_b32 m0, s16
	s_nop 0
	global_load_lds_dwordx4 v[134:135], off
	v_lshl_add_u64 v[134:135], s[14:15], 0, v[128:129]
	s_add_i32 m0, s16, 0x2000
	s_nop 0
	global_load_lds_dwordx4 v[134:135], off
	s_waitcnt vmcnt(6)
	s_barrier
	s_setprio 1
	v_mfma_f32_16x16x32_bf16 v[40:43], v[200:203], v[154:157], v[40:43]
	v_mfma_f32_16x16x32_bf16 v[32:35], v[218:221], v[154:157], v[32:35]
	v_mfma_f32_16x16x32_bf16 v[24:27], v[200:203], v[162:165], v[24:27]
	v_mfma_f32_16x16x32_bf16 v[20:23], v[218:221], v[162:165], v[20:23]
	v_mfma_f32_16x16x32_bf16 v[12:15], v[200:203], v[170:173], v[12:15]
	v_mfma_f32_16x16x32_bf16 v[8:11], v[218:221], v[170:173], v[8:11]
	v_mfma_f32_16x16x32_bf16 v[4:7], v[200:203], v[178:181], v[4:7]
	v_mfma_f32_16x16x32_bf16 v[0:3], v[218:221], v[178:181], v[0:3]
	v_mfma_f32_16x16x32_bf16 v[40:43], v[204:207], v[158:161], v[40:43]
	v_mfma_f32_16x16x32_bf16 v[32:35], v[222:225], v[158:161], v[32:35]
	v_mfma_f32_16x16x32_bf16 v[24:27], v[204:207], v[166:169], v[24:27]
	v_mfma_f32_16x16x32_bf16 v[20:23], v[222:225], v[166:169], v[20:23]
	v_mfma_f32_16x16x32_bf16 v[12:15], v[204:207], v[174:177], v[12:15]
	v_mfma_f32_16x16x32_bf16 v[8:11], v[222:225], v[174:177], v[8:11]
	v_mfma_f32_16x16x32_bf16 v[4:7], v[204:207], v[182:185], v[4:7]
	v_mfma_f32_16x16x32_bf16 v[0:3], v[222:225], v[182:185], v[0:3]
	s_setprio 0
	s_add_i32 s27, s27, 2
	s_add_u32 s12, s12, 0x100
	s_addc_u32 s13, s13, 0
	s_add_u32 s1, s1, 0x100
	s_addc_u32 s5, s5, 0
	s_cmp_gt_u32 s27, 13
	s_barrier
	s_cbranch_scc0 .LBB0_1012
	s_cmpk_gt_u32 s2, 0xff
	s_cbranch_scc1 .Lal4_a
	s_barrier
